# k16 with the packed f32 ops (v_pk_mul/add/fma_f32) of the rewritten SwiGLU, residual, EpiOut and EpiOutT epilogues split into scalar f32 ops (bit-identical math)
# baseline (speedup 1.0000x reference)
; __device__ __forceinline__ unsigned cvtpk(float lo, float hi) { f32x2_t v = {lo, hi}; bf16x2_t b = __builtin_convertvector(v, bf16x2_t); return __builtin_bit_cast(unsigned, b); }
;     __device__ __forceinline__ void operator()(const f32x4 (&acc)[2][2][4][2], const Unit& u, int wr, int wc, int fr, int fq) const {
;         const int row0 = u.pm * BM + wr * 64 + fr, col0 = u.pn * 128 + wc * 32 + 8 * fq;
; #pragma unroll
;         for (int ai = 0; ai < 2; ++ai)
; #pragma unroll
;             for (int m = 0; m < 4; ++m) {
;                 const int row = row0 + ai * HALF + m * 16;
;                 const float rs = 1.0f / sqrtf(ssq_sum(ssq + (size_t)row * 16) * (1.0f / DM) + EPS);
;                 float hv[8];
; #pragma unroll
;                 for (int n = 0; n < 2; ++n)
; #pragma unroll
;                     for (int e = 0; e < 4; ++e) {
;                         const float gg = acc[ai][0][m][n][e] * rs, uu = acc[ai][1][m][n][e] * rs;
;                         const float den = 1.0f + __builtin_amdgcn_exp2f(-gg * LOG2E);
;                         hv[n * 4 + e] = gg * uu * __builtin_amdgcn_rcpf(den);
;                     }
;                 u32x4 w; w.x = cvtpk(hv[0], hv[1]); w.y = cvtpk(hv[2], hv[3]); w.z = cvtpk(hv[4], hv[5]); w.w = cvtpk(hv[6], hv[7]);
;                 *(u32x4*)(H + (size_t)row * DFF + col0) = w;
;             }
.LBB0_244:
	v_readlane_b32 s9, v254, 7
	v_mbcnt_lo_u32_b32 v144, -1, 0
	v_mbcnt_hi_u32_b32 v144, -1, v144
	v_lshrrev_b32_e32 v145, 1, v144
	v_lshl_add_u32 v145, s9, 5, v145
	v_and_b32_e32 v146, 1, v144
	v_lshl_add_u32 v147, s8, 8, v145
	v_lshlrev_b32_e32 v147, 6, v147
	v_lshl_add_u32 v147, v146, 5, v147
	global_load_dwordx4 v[160:163], v147, s[14:15]
	global_load_dwordx4 v[164:167], v147, s[14:15] offset:16
	v_lshl_add_u32 v148, s8, 8, v152
	v_mov_b64_e32 v[146:147], s[16:17]
	v_mad_i64_i32 v[176:177], s[8:9], v148, s56, v[146:147]
	v_lshl_or_b32 v150, s2, 7, v154
	v_mov_b32_e32 v151, 0
	v_lshlrev_b64 v[150:151], 1, v[150:151]
	v_lshl_add_u64 v[176:177], v[176:177], 0, v[150:151]
	v_lshlrev_b32_e32 v145, 3, v145
	v_add_u32_e32 v145, 0x20100, v145
	v_lshlrev_b32_e32 v146, 3, v152
	v_add_u32_e32 v146, 0x20100, v146
	s_mov_b32 s9, 0
	s_waitcnt vmcnt(0)
	v_add_f32_e32 v160, v160, v162
	v_add_f32_e32 v161, v161, v163
	v_add_f32_e32 v164, v164, v166
	v_add_f32_e32 v165, v165, v167
	v_add_f32_e32 v160, v160, v164
	v_add_f32_e32 v161, v161, v165
	v_add_f32_e32 v160, v160, v161
	s_nop 1
	v_add_f32_dpp v160, v160, v160 quad_perm:[1,0,3,2] row_mask:0xf bank_mask:0xf
	v_fmamk_f32 v160, v160, 0x3a800000, v158
	v_rsq_f32_e32 v161, v160
	s_nop 0
	v_mul_f32_e32 v161, 0xbfb8aa3b, v161
	ds_write_b64 v145, v[160:161]
	s_waitcnt lgkmcnt(0)
	s_barrier
	ds_read_b64 v[160:161], v146 offset:0
	ds_read_b64 v[162:163], v146 offset:128
	ds_read_b64 v[164:165], v146 offset:256
	ds_read_b64 v[166:167], v146 offset:384
	ds_read_b64 v[168:169], v146 offset:1024
	ds_read_b64 v[170:171], v146 offset:1152
	ds_read_b64 v[172:173], v146 offset:1280
	ds_read_b64 v[174:175], v146 offset:1408
	v_mul_f32_e32 v116, v124, v116
	v_mul_f32_e32 v117, v125, v117
	v_mul_f32_e32 v118, v126, v118
	v_mul_f32_e32 v119, v127, v119
	v_mul_f32_e32 v112, v120, v112
	v_mul_f32_e32 v113, v121, v113
	v_mul_f32_e32 v114, v122, v114
	v_mul_f32_e32 v115, v123, v115
	s_waitcnt lgkmcnt(7)
	v_mul_f32_e32 v124, v161, v124
	v_mul_f32_e32 v125, v161, v125
	v_mul_f32_e32 v126, v161, v126
	v_mul_f32_e32 v127, v161, v127
	v_mul_f32_e32 v120, v161, v120
	v_mul_f32_e32 v121, v161, v121
	v_mul_f32_e32 v122, v161, v122
	v_mul_f32_e32 v123, v161, v123
	v_exp_f32_e32 v124, v124
	v_exp_f32_e32 v125, v125
	v_exp_f32_e32 v126, v126
	v_exp_f32_e32 v127, v127
	v_exp_f32_e32 v120, v120
	v_exp_f32_e32 v121, v121
	v_exp_f32_e32 v122, v122
	v_exp_f32_e32 v123, v123
	v_fma_f32 v124, v124, v160, v160
	v_fma_f32 v125, v125, v160, v160
	v_fma_f32 v126, v126, v160, v160
	v_fma_f32 v127, v127, v160, v160
	v_fma_f32 v120, v120, v160, v160
	v_fma_f32 v121, v121, v160, v160
	v_fma_f32 v122, v122, v160, v160
	v_fma_f32 v123, v123, v160, v160
	v_rcp_f32_e32 v124, v124
	v_rcp_f32_e32 v125, v125
	v_rcp_f32_e32 v126, v126
	v_rcp_f32_e32 v127, v127
	v_rcp_f32_e32 v120, v120
	v_rcp_f32_e32 v121, v121
	v_rcp_f32_e32 v122, v122
	v_rcp_f32_e32 v123, v123
	v_mul_f32_e32 v116, v116, v124
	v_mul_f32_e32 v117, v117, v125
	v_mul_f32_e32 v118, v118, v126
	v_mul_f32_e32 v119, v119, v127
	v_mul_f32_e32 v112, v112, v120
	v_mul_f32_e32 v113, v113, v121
	v_mul_f32_e32 v114, v114, v122
	v_mul_f32_e32 v115, v115, v123
	v_cvt_pk_bf16_f32 v124, v116, v117
	v_cvt_pk_bf16_f32 v125, v118, v119
	v_cvt_pk_bf16_f32 v126, v112, v113
	v_cvt_pk_bf16_f32 v127, v114, v115
	global_store_dwordx4 v[176:177], v[124:127], off
	v_mul_f32_e32 v100, v108, v100
	v_mul_f32_e32 v101, v109, v101
	v_mul_f32_e32 v102, v110, v102
	v_mul_f32_e32 v103, v111, v103
	v_mul_f32_e32 v96, v104, v96
	v_mul_f32_e32 v97, v105, v97
	v_mul_f32_e32 v98, v106, v98
	v_mul_f32_e32 v99, v107, v99
	s_waitcnt lgkmcnt(6)
	v_mul_f32_e32 v108, v163, v108
	v_mul_f32_e32 v109, v163, v109
	v_mul_f32_e32 v110, v163, v110
	v_mul_f32_e32 v111, v163, v111
	v_mul_f32_e32 v104, v163, v104
	v_mul_f32_e32 v105, v163, v105
	v_mul_f32_e32 v106, v163, v106
	v_mul_f32_e32 v107, v163, v107
	v_exp_f32_e32 v108, v108
	v_exp_f32_e32 v109, v109
	v_exp_f32_e32 v110, v110
	v_exp_f32_e32 v111, v111
	v_exp_f32_e32 v104, v104
	v_exp_f32_e32 v105, v105
	v_exp_f32_e32 v106, v106
	v_exp_f32_e32 v107, v107
	v_fma_f32 v108, v108, v162, v162
	v_fma_f32 v109, v109, v162, v162
	v_fma_f32 v110, v110, v162, v162
	v_fma_f32 v111, v111, v162, v162
	v_fma_f32 v104, v104, v162, v162
	v_fma_f32 v105, v105, v162, v162
	v_fma_f32 v106, v106, v162, v162
	v_fma_f32 v107, v107, v162, v162
	v_rcp_f32_e32 v108, v108
	v_rcp_f32_e32 v109, v109
	v_rcp_f32_e32 v110, v110
	v_rcp_f32_e32 v111, v111
	v_rcp_f32_e32 v104, v104
	v_rcp_f32_e32 v105, v105
	v_rcp_f32_e32 v106, v106
	v_rcp_f32_e32 v107, v107
	s_mov_b32 s8, 0x16000
	v_mul_f32_e32 v100, v100, v108
	v_mul_f32_e32 v101, v101, v109
	v_mul_f32_e32 v102, v102, v110
	v_mul_f32_e32 v103, v103, v111
	v_mul_f32_e32 v96, v96, v104
	v_mul_f32_e32 v97, v97, v105
	v_mul_f32_e32 v98, v98, v106
	v_mul_f32_e32 v99, v99, v107
	v_cvt_pk_bf16_f32 v108, v100, v101
	v_cvt_pk_bf16_f32 v109, v102, v103
	v_cvt_pk_bf16_f32 v110, v96, v97
	v_cvt_pk_bf16_f32 v111, v98, v99
	v_lshl_add_u64 v[178:179], v[176:177], 0, s[8:9]
	global_store_dwordx4 v[178:179], v[108:111], off
	v_mul_f32_e32 v84, v92, v84
	v_mul_f32_e32 v85, v93, v85
	v_mul_f32_e32 v86, v94, v86
	v_mul_f32_e32 v87, v95, v87
	v_mul_f32_e32 v80, v88, v80
	v_mul_f32_e32 v81, v89, v81
	v_mul_f32_e32 v82, v90, v82
	v_mul_f32_e32 v83, v91, v83
	s_waitcnt lgkmcnt(5)
; __device__ __forceinline__ unsigned cvtpk(float lo, float hi) { f32x2_t v = {lo, hi}; bf16x2_t b = __builtin_convertvector(v, bf16x2_t); return __builtin_bit_cast(unsigned, b); }
;     __device__ __forceinline__ void operator()(const f32x4 (&acc)[2][2][4][2], const Unit& u, int wr, int wc, int fr, int fq) const {
;     ...
;             for (int m = 0; m < 4; ++m) {
;                 const int row = row0 + ai * HALF + m * 16;
;                 const float rs = 1.0f / sqrtf(ssq_sum(ssq + (size_t)row * 16) * (1.0f / DM) + EPS);
;                 float hv[8];
; #pragma unroll
;                 for (int n = 0; n < 2; ++n)
; #pragma unroll
;                     for (int e = 0; e < 4; ++e) {
;                         const float gg = acc[ai][0][m][n][e] * rs, uu = acc[ai][1][m][n][e] * rs;
;                         const float den = 1.0f + __builtin_amdgcn_exp2f(-gg * LOG2E);
;                         hv[n * 4 + e] = gg * uu * __builtin_amdgcn_rcpf(den);
;                     }
;                 u32x4 w; w.x = cvtpk(hv[0], hv[1]); w.y = cvtpk(hv[2], hv[3]); w.z = cvtpk(hv[4], hv[5]); w.w = cvtpk(hv[6], hv[7]);
;                 *(u32x4*)(H + (size_t)row * DFF + col0) = w;
	v_mul_f32_e32 v92, v165, v92
	v_mul_f32_e32 v93, v165, v93
	v_mul_f32_e32 v94, v165, v94
	v_mul_f32_e32 v95, v165, v95
	v_mul_f32_e32 v88, v165, v88
	v_mul_f32_e32 v89, v165, v89
	v_mul_f32_e32 v90, v165, v90
	v_mul_f32_e32 v91, v165, v91
	v_exp_f32_e32 v92, v92
	v_exp_f32_e32 v93, v93
	v_exp_f32_e32 v94, v94
	v_exp_f32_e32 v95, v95
	v_exp_f32_e32 v88, v88
	v_exp_f32_e32 v89, v89
	v_exp_f32_e32 v90, v90
	v_exp_f32_e32 v91, v91
	v_fma_f32 v92, v92, v164, v164
	v_fma_f32 v93, v93, v164, v164
	v_fma_f32 v94, v94, v164, v164
	v_fma_f32 v95, v95, v164, v164
	v_fma_f32 v88, v88, v164, v164
	v_fma_f32 v89, v89, v164, v164
	v_fma_f32 v90, v90, v164, v164
	v_fma_f32 v91, v91, v164, v164
	v_rcp_f32_e32 v92, v92
	v_rcp_f32_e32 v93, v93
	v_rcp_f32_e32 v94, v94
	v_rcp_f32_e32 v95, v95
	v_rcp_f32_e32 v88, v88
	v_rcp_f32_e32 v89, v89
	v_rcp_f32_e32 v90, v90
	v_rcp_f32_e32 v91, v91
	s_mov_b32 s8, 0x2c000
	v_mul_f32_e32 v84, v84, v92
	v_mul_f32_e32 v85, v85, v93
	v_mul_f32_e32 v86, v86, v94
	v_mul_f32_e32 v87, v87, v95
	v_mul_f32_e32 v80, v80, v88
	v_mul_f32_e32 v81, v81, v89
	v_mul_f32_e32 v82, v82, v90
	v_mul_f32_e32 v83, v83, v91
	v_cvt_pk_bf16_f32 v92, v84, v85
	v_cvt_pk_bf16_f32 v93, v86, v87
	v_cvt_pk_bf16_f32 v94, v80, v81
	v_cvt_pk_bf16_f32 v95, v82, v83
	v_lshl_add_u64 v[178:179], v[176:177], 0, s[8:9]
	global_store_dwordx4 v[178:179], v[92:95], off
	v_mul_f32_e32 v68, v76, v68
	v_mul_f32_e32 v69, v77, v69
	v_mul_f32_e32 v70, v78, v70
	v_mul_f32_e32 v71, v79, v71
	v_mul_f32_e32 v64, v72, v64
	v_mul_f32_e32 v65, v73, v65
	v_mul_f32_e32 v66, v74, v66
	v_mul_f32_e32 v67, v75, v67
	s_waitcnt lgkmcnt(4)
	v_mul_f32_e32 v76, v167, v76
	v_mul_f32_e32 v77, v167, v77
	v_mul_f32_e32 v78, v167, v78
	v_mul_f32_e32 v79, v167, v79
	v_mul_f32_e32 v72, v167, v72
	v_mul_f32_e32 v73, v167, v73
	v_mul_f32_e32 v74, v167, v74
	v_mul_f32_e32 v75, v167, v75
	v_exp_f32_e32 v76, v76
	v_exp_f32_e32 v77, v77
	v_exp_f32_e32 v78, v78
	v_exp_f32_e32 v79, v79
	v_exp_f32_e32 v72, v72
	v_exp_f32_e32 v73, v73
	v_exp_f32_e32 v74, v74
	v_exp_f32_e32 v75, v75
	v_fma_f32 v76, v76, v166, v166
	v_fma_f32 v77, v77, v166, v166
	v_fma_f32 v78, v78, v166, v166
	v_fma_f32 v79, v79, v166, v166
	v_fma_f32 v72, v72, v166, v166
	v_fma_f32 v73, v73, v166, v166
	v_fma_f32 v74, v74, v166, v166
	v_fma_f32 v75, v75, v166, v166
	v_rcp_f32_e32 v76, v76
	v_rcp_f32_e32 v77, v77
	v_rcp_f32_e32 v78, v78
	v_rcp_f32_e32 v79, v79
	v_rcp_f32_e32 v72, v72
	v_rcp_f32_e32 v73, v73
	v_rcp_f32_e32 v74, v74
	v_rcp_f32_e32 v75, v75
	s_mov_b32 s8, 0x42000
	v_mul_f32_e32 v68, v68, v76
	v_mul_f32_e32 v69, v69, v77
	v_mul_f32_e32 v70, v70, v78
	v_mul_f32_e32 v71, v71, v79
	v_mul_f32_e32 v64, v64, v72
	v_mul_f32_e32 v65, v65, v73
	v_mul_f32_e32 v66, v66, v74
	v_mul_f32_e32 v67, v67, v75
	v_cvt_pk_bf16_f32 v76, v68, v69
	v_cvt_pk_bf16_f32 v77, v70, v71
	v_cvt_pk_bf16_f32 v78, v64, v65
	v_cvt_pk_bf16_f32 v79, v66, v67
	v_lshl_add_u64 v[178:179], v[176:177], 0, s[8:9]
	global_store_dwordx4 v[178:179], v[76:79], off
	v_mul_f32_e32 v52, v60, v52
	v_mul_f32_e32 v53, v61, v53
	v_mul_f32_e32 v54, v62, v54
	v_mul_f32_e32 v55, v63, v55
	v_mul_f32_e32 v48, v56, v48
	v_mul_f32_e32 v49, v57, v49
	v_mul_f32_e32 v50, v58, v50
	v_mul_f32_e32 v51, v59, v51
	s_waitcnt lgkmcnt(3)
	v_mul_f32_e32 v60, v169, v60
	v_mul_f32_e32 v61, v169, v61
	v_mul_f32_e32 v62, v169, v62
	v_mul_f32_e32 v63, v169, v63
	v_mul_f32_e32 v56, v169, v56
	v_mul_f32_e32 v57, v169, v57
	v_mul_f32_e32 v58, v169, v58
	v_mul_f32_e32 v59, v169, v59
	v_exp_f32_e32 v60, v60
	v_exp_f32_e32 v61, v61
	v_exp_f32_e32 v62, v62
	v_exp_f32_e32 v63, v63
	v_exp_f32_e32 v56, v56
	v_exp_f32_e32 v57, v57
	v_exp_f32_e32 v58, v58
	v_exp_f32_e32 v59, v59
	v_fma_f32 v60, v60, v168, v168
	v_fma_f32 v61, v61, v168, v168
	v_fma_f32 v62, v62, v168, v168
	v_fma_f32 v63, v63, v168, v168
	v_fma_f32 v56, v56, v168, v168
	v_fma_f32 v57, v57, v168, v168
	v_fma_f32 v58, v58, v168, v168
	v_fma_f32 v59, v59, v168, v168
	v_rcp_f32_e32 v60, v60
	v_rcp_f32_e32 v61, v61
	v_rcp_f32_e32 v62, v62
	v_rcp_f32_e32 v63, v63
	v_rcp_f32_e32 v56, v56
	v_rcp_f32_e32 v57, v57
	v_rcp_f32_e32 v58, v58
	v_rcp_f32_e32 v59, v59
	s_mov_b32 s8, 0xb0000
	v_mul_f32_e32 v52, v52, v60
	v_mul_f32_e32 v53, v53, v61
	v_mul_f32_e32 v54, v54, v62
	v_mul_f32_e32 v55, v55, v63
	v_mul_f32_e32 v48, v48, v56
	v_mul_f32_e32 v49, v49, v57
	v_mul_f32_e32 v50, v50, v58
	v_mul_f32_e32 v51, v51, v59
	v_cvt_pk_bf16_f32 v60, v52, v53
	v_cvt_pk_bf16_f32 v61, v54, v55
	v_cvt_pk_bf16_f32 v62, v48, v49
	v_cvt_pk_bf16_f32 v63, v50, v51
	v_lshl_add_u64 v[178:179], v[176:177], 0, s[8:9]
	global_store_dwordx4 v[178:179], v[60:63], off
	v_mul_f32_e32 v36, v44, v36
	v_mul_f32_e32 v37, v45, v37
	v_mul_f32_e32 v38, v46, v38
	v_mul_f32_e32 v39, v47, v39
	v_mul_f32_e32 v32, v40, v32
	v_mul_f32_e32 v33, v41, v33
	v_mul_f32_e32 v34, v42, v34
	v_mul_f32_e32 v35, v43, v35
	s_waitcnt lgkmcnt(2)
; __device__ __forceinline__ unsigned cvtpk(float lo, float hi) { f32x2_t v = {lo, hi}; bf16x2_t b = __builtin_convertvector(v, bf16x2_t); return __builtin_bit_cast(unsigned, b); }
;     __device__ __forceinline__ void operator()(const f32x4 (&acc)[2][2][4][2], const Unit& u, int wr, int wc, int fr, int fq) const {
;     ...
;             for (int m = 0; m < 4; ++m) {
;                 const int row = row0 + ai * HALF + m * 16;
;                 const float rs = 1.0f / sqrtf(ssq_sum(ssq + (size_t)row * 16) * (1.0f / DM) + EPS);
;                 float hv[8];
; #pragma unroll
;                 for (int n = 0; n < 2; ++n)
; #pragma unroll
;                     for (int e = 0; e < 4; ++e) {
;                         const float gg = acc[ai][0][m][n][e] * rs, uu = acc[ai][1][m][n][e] * rs;
;                         const float den = 1.0f + __builtin_amdgcn_exp2f(-gg * LOG2E);
;                         hv[n * 4 + e] = gg * uu * __builtin_amdgcn_rcpf(den);
;                     }
;                 u32x4 w; w.x = cvtpk(hv[0], hv[1]); w.y = cvtpk(hv[2], hv[3]); w.z = cvtpk(hv[4], hv[5]); w.w = cvtpk(hv[6], hv[7]);
;                 *(u32x4*)(H + (size_t)row * DFF + col0) = w;
;             }
	v_mul_f32_e32 v44, v171, v44
	v_mul_f32_e32 v45, v171, v45
	v_mul_f32_e32 v46, v171, v46
	v_mul_f32_e32 v47, v171, v47
	v_mul_f32_e32 v40, v171, v40
	v_mul_f32_e32 v41, v171, v41
	v_mul_f32_e32 v42, v171, v42
	v_mul_f32_e32 v43, v171, v43
	v_exp_f32_e32 v44, v44
	v_exp_f32_e32 v45, v45
	v_exp_f32_e32 v46, v46
	v_exp_f32_e32 v47, v47
	v_exp_f32_e32 v40, v40
	v_exp_f32_e32 v41, v41
	v_exp_f32_e32 v42, v42
	v_exp_f32_e32 v43, v43
	v_fma_f32 v44, v44, v170, v170
	v_fma_f32 v45, v45, v170, v170
	v_fma_f32 v46, v46, v170, v170
	v_fma_f32 v47, v47, v170, v170
	v_fma_f32 v40, v40, v170, v170
	v_fma_f32 v41, v41, v170, v170
	v_fma_f32 v42, v42, v170, v170
	v_fma_f32 v43, v43, v170, v170
	v_rcp_f32_e32 v44, v44
	v_rcp_f32_e32 v45, v45
	v_rcp_f32_e32 v46, v46
	v_rcp_f32_e32 v47, v47
	v_rcp_f32_e32 v40, v40
	v_rcp_f32_e32 v41, v41
	v_rcp_f32_e32 v42, v42
	v_rcp_f32_e32 v43, v43
	s_mov_b32 s8, 0xc6000
	v_mul_f32_e32 v36, v36, v44
	v_mul_f32_e32 v37, v37, v45
	v_mul_f32_e32 v38, v38, v46
	v_mul_f32_e32 v39, v39, v47
	v_mul_f32_e32 v32, v32, v40
	v_mul_f32_e32 v33, v33, v41
	v_mul_f32_e32 v34, v34, v42
	v_mul_f32_e32 v35, v35, v43
	v_cvt_pk_bf16_f32 v44, v36, v37
	v_cvt_pk_bf16_f32 v45, v38, v39
	v_cvt_pk_bf16_f32 v46, v32, v33
	v_cvt_pk_bf16_f32 v47, v34, v35
	v_lshl_add_u64 v[178:179], v[176:177], 0, s[8:9]
	global_store_dwordx4 v[178:179], v[44:47], off
	v_mul_f32_e32 v20, v28, v20
	v_mul_f32_e32 v21, v29, v21
	v_mul_f32_e32 v22, v30, v22
	v_mul_f32_e32 v23, v31, v23
	v_mul_f32_e32 v16, v24, v16
	v_mul_f32_e32 v17, v25, v17
	v_mul_f32_e32 v18, v26, v18
	v_mul_f32_e32 v19, v27, v19
	s_waitcnt lgkmcnt(1)
	v_mul_f32_e32 v28, v173, v28
	v_mul_f32_e32 v29, v173, v29
	v_mul_f32_e32 v30, v173, v30
	v_mul_f32_e32 v31, v173, v31
	v_mul_f32_e32 v24, v173, v24
	v_mul_f32_e32 v25, v173, v25
	v_mul_f32_e32 v26, v173, v26
	v_mul_f32_e32 v27, v173, v27
	v_exp_f32_e32 v28, v28
	v_exp_f32_e32 v29, v29
	v_exp_f32_e32 v30, v30
	v_exp_f32_e32 v31, v31
	v_exp_f32_e32 v24, v24
	v_exp_f32_e32 v25, v25
	v_exp_f32_e32 v26, v26
	v_exp_f32_e32 v27, v27
	v_fma_f32 v28, v28, v172, v172
	v_fma_f32 v29, v29, v172, v172
	v_fma_f32 v30, v30, v172, v172
	v_fma_f32 v31, v31, v172, v172
	v_fma_f32 v24, v24, v172, v172
	v_fma_f32 v25, v25, v172, v172
	v_fma_f32 v26, v26, v172, v172
	v_fma_f32 v27, v27, v172, v172
	v_rcp_f32_e32 v28, v28
	v_rcp_f32_e32 v29, v29
	v_rcp_f32_e32 v30, v30
	v_rcp_f32_e32 v31, v31
	v_rcp_f32_e32 v24, v24
	v_rcp_f32_e32 v25, v25
	v_rcp_f32_e32 v26, v26
	v_rcp_f32_e32 v27, v27
	s_mov_b32 s8, 0xdc000
	v_mul_f32_e32 v20, v20, v28
	v_mul_f32_e32 v21, v21, v29
	v_mul_f32_e32 v22, v22, v30
	v_mul_f32_e32 v23, v23, v31
	v_mul_f32_e32 v16, v16, v24
	v_mul_f32_e32 v17, v17, v25
	v_mul_f32_e32 v18, v18, v26
	v_mul_f32_e32 v19, v19, v27
	v_cvt_pk_bf16_f32 v28, v20, v21
	v_cvt_pk_bf16_f32 v29, v22, v23
	v_cvt_pk_bf16_f32 v30, v16, v17
	v_cvt_pk_bf16_f32 v31, v18, v19
	v_lshl_add_u64 v[178:179], v[176:177], 0, s[8:9]
	global_store_dwordx4 v[178:179], v[28:31], off
	v_mul_f32_e32 v4, v12, v4
	v_mul_f32_e32 v5, v13, v5
	v_mul_f32_e32 v6, v14, v6
	v_mul_f32_e32 v7, v15, v7
	v_mul_f32_e32 v0, v8, v0
	v_mul_f32_e32 v1, v9, v1
	v_mul_f32_e32 v2, v10, v2
	v_mul_f32_e32 v3, v11, v3
	s_waitcnt lgkmcnt(0)
	v_mul_f32_e32 v12, v175, v12
	v_mul_f32_e32 v13, v175, v13
	v_mul_f32_e32 v14, v175, v14
	v_mul_f32_e32 v15, v175, v15
	v_mul_f32_e32 v8, v175, v8
	v_mul_f32_e32 v9, v175, v9
	v_mul_f32_e32 v10, v175, v10
	v_mul_f32_e32 v11, v175, v11
	v_exp_f32_e32 v12, v12
	v_exp_f32_e32 v13, v13
	v_exp_f32_e32 v14, v14
	v_exp_f32_e32 v15, v15
	v_exp_f32_e32 v8, v8
	v_exp_f32_e32 v9, v9
	v_exp_f32_e32 v10, v10
	v_exp_f32_e32 v11, v11
	v_fma_f32 v12, v12, v174, v174
	v_fma_f32 v13, v13, v174, v174
	v_fma_f32 v14, v14, v174, v174
	v_fma_f32 v15, v15, v174, v174
	v_fma_f32 v8, v8, v174, v174
	v_fma_f32 v9, v9, v174, v174
	v_fma_f32 v10, v10, v174, v174
	v_fma_f32 v11, v11, v174, v174
	v_rcp_f32_e32 v12, v12
	v_rcp_f32_e32 v13, v13
	v_rcp_f32_e32 v14, v14
	v_rcp_f32_e32 v15, v15
	v_rcp_f32_e32 v8, v8
	v_rcp_f32_e32 v9, v9
	v_rcp_f32_e32 v10, v10
	v_rcp_f32_e32 v11, v11
	s_mov_b32 s8, 0xf2000
	v_mul_f32_e32 v4, v4, v12
	v_mul_f32_e32 v5, v5, v13
	v_mul_f32_e32 v6, v6, v14
	v_mul_f32_e32 v7, v7, v15
	v_mul_f32_e32 v0, v0, v8
	v_mul_f32_e32 v1, v1, v9
	v_mul_f32_e32 v2, v2, v10
	v_mul_f32_e32 v3, v3, v11
	v_cvt_pk_bf16_f32 v12, v4, v5
	v_cvt_pk_bf16_f32 v13, v6, v7
	v_cvt_pk_bf16_f32 v14, v0, v1
	v_cvt_pk_bf16_f32 v15, v2, v3
	v_lshl_add_u64 v[178:179], v[176:177], 0, s[8:9]
	global_store_dwordx4 v[178:179], v[12:15], off
	s_andn2_b64 vcc, exec, s[6:7]
	s_mov_b64 s[6:7], -1
	s_cbranch_vccnz .LBB0_237
	s_andn2_b64 vcc, exec, s[12:13]
	s_cbranch_vccnz .LBB0_236
	s_barrier
	s_branch .LBB0_236

; __device__ __forceinline__ unsigned cvtpk(float lo, float hi) { f32x2_t v = {lo, hi}; bf16x2_t b = __builtin_convertvector(v, bf16x2_t); return __builtin_bit_cast(unsigned, b); }
;     __device__ __forceinline__ void operator()(const f32x4 (&acc)[2][2][4][2], const Unit& u, int wr, int wc, int fr, int fq) const {
;         const int row0 = u.pm * BM + wr * 64 + fr, col0 = u.pn * BM + wc * 32 + 8 * fq;
;         f32x4 cs[2][2];
; #pragma unroll
;         for (int bj = 0; bj < 2; ++bj)
; #pragma unroll
;             for (int n = 0; n < 2; ++n) {
; #pragma unroll
;                 for (int e = 0; e < 4; ++e) cs[bj][n][e] = 1.0f / sqrtf(ssq_sum(ssq_in + (size_t)(col0 + bj * HALF + 4 * n + e) * 16) * inv_dim + EPS); }
; #pragma unroll
;         for (int ai = 0; ai < 2; ++ai)
; #pragma unroll
;             for (int m = 0; m < 4; ++m) {
;                 const int row = row0 + ai * HALF + m * 16;
; #pragma unroll
;                 for (int bj = 0; bj < 2; ++bj) {
;                     const f32x4 v0 = acc[ai][bj][m][0] * cs[bj][0], v1 = acc[ai][bj][m][1] * cs[bj][1];
;                     u32x4 w; w.x = cvtpk(v0[0], v0[1]); w.y = cvtpk(v0[2], v0[3]); w.z = cvtpk(v1[0], v1[1]); w.w = cvtpk(v1[2], v1[3]);
;                     *(u32x4*)(O + (size_t)row * ldc + col0 + bj * HALF) = w;
;                 }
.LBB0_503:
	v_readlane_b32 vcc_lo, v254, 7
	v_mbcnt_lo_u32_b32 v170, -1, 0
	v_mbcnt_hi_u32_b32 v170, -1, v170
	v_lshrrev_b32_e32 v171, 1, v170
	v_lshl_add_u32 v171, vcc_lo, 5, v171
	v_and_b32_e32 v172, 1, v170
	v_lshl_add_u32 v173, s2, 8, v171
	v_lshlrev_b32_e32 v173, 6, v173
	v_lshl_add_u32 v173, v172, 5, v173
	global_load_dwordx4 v[174:177], v173, s[18:19]
	global_load_dwordx4 v[178:181], v173, s[18:19] offset:16
	v_lshl_or_b32 v182, s2, 8, v164
	v_lshl_add_u32 v183, s42, 8, v162
	v_lshlrev_b32_e32 v183, 16, v183
	v_lshl_add_u32 v183, v182, 1, v183
	v_lshlrev_b32_e32 v171, 2, v171
	v_add_u32_e32 v171, 0x20100, v171
	v_lshlrev_b32_e32 v172, 2, v164
	v_add_u32_e32 v172, 0x20100, v172
	s_waitcnt vmcnt(0)
	v_add_f32_e32 v174, v174, v176
	v_add_f32_e32 v175, v175, v177
	v_add_f32_e32 v178, v178, v180
	v_add_f32_e32 v179, v179, v181
	v_add_f32_e32 v174, v174, v178
	v_add_f32_e32 v175, v175, v179
	v_add_f32_e32 v174, v174, v175
	s_nop 1
	v_add_f32_dpp v174, v174, v174 quad_perm:[1,0,3,2] row_mask:0xf bank_mask:0xf
	v_fmamk_f32 v174, v174, 0x3a800000, v168
	v_rsq_f32_e32 v174, v174
	s_nop 0
	ds_write_b32 v171, v174
	s_waitcnt lgkmcnt(0)
	s_barrier
	ds_read_b128 v[146:149], v172
	ds_read_b128 v[150:153], v172 offset:16
	ds_read_b128 v[154:157], v172 offset:512
	ds_read_b128 v[158:161], v172 offset:528
	s_waitcnt lgkmcnt(0)
	v_mul_f32_e32 v124, v124, v146
	v_mul_f32_e32 v125, v125, v147
	v_mul_f32_e32 v126, v126, v148
	v_mul_f32_e32 v127, v127, v149
	v_mul_f32_e32 v120, v120, v150
	v_mul_f32_e32 v121, v121, v151
	v_mul_f32_e32 v122, v122, v152
	v_mul_f32_e32 v123, v123, v153
	v_mul_f32_e32 v116, v116, v154
	v_mul_f32_e32 v117, v117, v155
	v_mul_f32_e32 v118, v118, v156
	v_mul_f32_e32 v119, v119, v157
	v_mul_f32_e32 v104, v104, v158
	v_mul_f32_e32 v105, v105, v159
	v_mul_f32_e32 v106, v106, v160
	v_mul_f32_e32 v107, v107, v161
	v_cvt_pk_bf16_f32 v124, v124, v125
	v_cvt_pk_bf16_f32 v125, v126, v127
	v_cvt_pk_bf16_f32 v126, v120, v121
	v_cvt_pk_bf16_f32 v127, v122, v123
	v_cvt_pk_bf16_f32 v116, v116, v117
	v_cvt_pk_bf16_f32 v117, v118, v119
	v_cvt_pk_bf16_f32 v118, v104, v105
	v_cvt_pk_bf16_f32 v119, v106, v107
	global_store_dwordx4 v183, v[124:127], s[14:15]
	global_store_dwordx4 v183, v[116:119], s[14:15] offset:256
	v_mul_f32_e32 v112, v112, v146
	v_mul_f32_e32 v113, v113, v147
	v_mul_f32_e32 v114, v114, v148
	v_mul_f32_e32 v115, v115, v149
	v_mul_f32_e32 v108, v108, v150
	v_mul_f32_e32 v109, v109, v151
	v_mul_f32_e32 v110, v110, v152
	v_mul_f32_e32 v111, v111, v153
	v_mul_f32_e32 v96, v96, v154
	v_mul_f32_e32 v97, v97, v155
	v_mul_f32_e32 v98, v98, v156
	v_mul_f32_e32 v99, v99, v157
	v_mul_f32_e32 v88, v88, v158
	v_mul_f32_e32 v89, v89, v159
	v_mul_f32_e32 v90, v90, v160
	v_mul_f32_e32 v91, v91, v161
	v_cvt_pk_bf16_f32 v112, v112, v113
	v_cvt_pk_bf16_f32 v113, v114, v115
	v_cvt_pk_bf16_f32 v114, v108, v109
	v_cvt_pk_bf16_f32 v115, v110, v111
	v_cvt_pk_bf16_f32 v96, v96, v97
	v_cvt_pk_bf16_f32 v97, v98, v99
	v_cvt_pk_bf16_f32 v98, v88, v89
	v_cvt_pk_bf16_f32 v99, v90, v91
	v_add_u32_e32 v184, 0x100000, v183
	global_store_dwordx4 v184, v[112:115], s[14:15]
	global_store_dwordx4 v184, v[96:99], s[14:15] offset:256
	v_mul_f32_e32 v100, v100, v146
	v_mul_f32_e32 v101, v101, v147
	v_mul_f32_e32 v102, v102, v148
	v_mul_f32_e32 v103, v103, v149
	v_mul_f32_e32 v92, v92, v150
	v_mul_f32_e32 v93, v93, v151
	v_mul_f32_e32 v94, v94, v152
	v_mul_f32_e32 v95, v95, v153
	v_mul_f32_e32 v80, v80, v154
	v_mul_f32_e32 v81, v81, v155
	v_mul_f32_e32 v82, v82, v156
	v_mul_f32_e32 v83, v83, v157
	v_mul_f32_e32 v72, v72, v158
	v_mul_f32_e32 v73, v73, v159
	v_mul_f32_e32 v74, v74, v160
	v_mul_f32_e32 v75, v75, v161
	v_cvt_pk_bf16_f32 v100, v100, v101
	v_cvt_pk_bf16_f32 v101, v102, v103
	v_cvt_pk_bf16_f32 v102, v92, v93
	v_cvt_pk_bf16_f32 v103, v94, v95
	v_cvt_pk_bf16_f32 v80, v80, v81
	v_cvt_pk_bf16_f32 v81, v82, v83
	v_cvt_pk_bf16_f32 v82, v72, v73
	v_cvt_pk_bf16_f32 v83, v74, v75
	v_add_u32_e32 v184, 0x200000, v183
	global_store_dwordx4 v184, v[100:103], s[14:15]
	global_store_dwordx4 v184, v[80:83], s[14:15] offset:256
	v_mul_f32_e32 v84, v84, v146
	v_mul_f32_e32 v85, v85, v147
	v_mul_f32_e32 v86, v86, v148
	v_mul_f32_e32 v87, v87, v149
	v_mul_f32_e32 v76, v76, v150
	v_mul_f32_e32 v77, v77, v151
	v_mul_f32_e32 v78, v78, v152
	v_mul_f32_e32 v79, v79, v153
; __device__ __forceinline__ unsigned cvtpk(float lo, float hi) { f32x2_t v = {lo, hi}; bf16x2_t b = __builtin_convertvector(v, bf16x2_t); return __builtin_bit_cast(unsigned, b); }
;     __device__ __forceinline__ void operator()(const f32x4 (&acc)[2][2][4][2], const Unit& u, int wr, int wc, int fr, int fq) const {
;     ...
;         for (int ai = 0; ai < 2; ++ai)
; #pragma unroll
;             for (int m = 0; m < 4; ++m) {
;                 const int row = row0 + ai * HALF + m * 16;
; #pragma unroll
;                 for (int bj = 0; bj < 2; ++bj) {
;                     const f32x4 v0 = acc[ai][bj][m][0] * cs[bj][0], v1 = acc[ai][bj][m][1] * cs[bj][1];
;                     u32x4 w; w.x = cvtpk(v0[0], v0[1]); w.y = cvtpk(v0[2], v0[3]); w.z = cvtpk(v1[0], v1[1]); w.w = cvtpk(v1[2], v1[3]);
;                     *(u32x4*)(O + (size_t)row * ldc + col0 + bj * HALF) = w;
;                 }
;             }
	v_mul_f32_e32 v68, v68, v154
	v_mul_f32_e32 v69, v69, v155
	v_mul_f32_e32 v70, v70, v156
	v_mul_f32_e32 v71, v71, v157
	v_mul_f32_e32 v64, v64, v158
	v_mul_f32_e32 v65, v65, v159
	v_mul_f32_e32 v66, v66, v160
	v_mul_f32_e32 v67, v67, v161
	v_cvt_pk_bf16_f32 v84, v84, v85
	v_cvt_pk_bf16_f32 v85, v86, v87
	v_cvt_pk_bf16_f32 v86, v76, v77
	v_cvt_pk_bf16_f32 v87, v78, v79
	v_cvt_pk_bf16_f32 v68, v68, v69
	v_cvt_pk_bf16_f32 v69, v70, v71
	v_cvt_pk_bf16_f32 v70, v64, v65
	v_cvt_pk_bf16_f32 v71, v66, v67
	v_add_u32_e32 v184, 0x300000, v183
	global_store_dwordx4 v184, v[84:87], s[14:15]
	global_store_dwordx4 v184, v[68:71], s[14:15] offset:256
	v_mul_f32_e32 v60, v60, v146
	v_mul_f32_e32 v61, v61, v147
	v_mul_f32_e32 v62, v62, v148
	v_mul_f32_e32 v63, v63, v149
	v_mul_f32_e32 v56, v56, v150
	v_mul_f32_e32 v57, v57, v151
	v_mul_f32_e32 v58, v58, v152
	v_mul_f32_e32 v59, v59, v153
	v_mul_f32_e32 v48, v48, v154
	v_mul_f32_e32 v49, v49, v155
	v_mul_f32_e32 v50, v50, v156
	v_mul_f32_e32 v51, v51, v157
	v_mul_f32_e32 v40, v40, v158
	v_mul_f32_e32 v41, v41, v159
	v_mul_f32_e32 v42, v42, v160
	v_mul_f32_e32 v43, v43, v161
	v_cvt_pk_bf16_f32 v60, v60, v61
	v_cvt_pk_bf16_f32 v61, v62, v63
	v_cvt_pk_bf16_f32 v62, v56, v57
	v_cvt_pk_bf16_f32 v63, v58, v59
	v_cvt_pk_bf16_f32 v48, v48, v49
	v_cvt_pk_bf16_f32 v49, v50, v51
	v_cvt_pk_bf16_f32 v50, v40, v41
	v_cvt_pk_bf16_f32 v51, v42, v43
	v_add_u32_e32 v184, 0x800000, v183
	global_store_dwordx4 v184, v[60:63], s[14:15]
	global_store_dwordx4 v184, v[48:51], s[14:15] offset:256
	v_mul_f32_e32 v52, v52, v146
	v_mul_f32_e32 v53, v53, v147
	v_mul_f32_e32 v54, v54, v148
	v_mul_f32_e32 v55, v55, v149
	v_mul_f32_e32 v44, v44, v150
	v_mul_f32_e32 v45, v45, v151
	v_mul_f32_e32 v46, v46, v152
	v_mul_f32_e32 v47, v47, v153
	v_mul_f32_e32 v32, v32, v154
	v_mul_f32_e32 v33, v33, v155
	v_mul_f32_e32 v34, v34, v156
	v_mul_f32_e32 v35, v35, v157
	v_mul_f32_e32 v24, v24, v158
	v_mul_f32_e32 v25, v25, v159
	v_mul_f32_e32 v26, v26, v160
	v_mul_f32_e32 v27, v27, v161
	v_cvt_pk_bf16_f32 v52, v52, v53
	v_cvt_pk_bf16_f32 v53, v54, v55
	v_cvt_pk_bf16_f32 v54, v44, v45
	v_cvt_pk_bf16_f32 v55, v46, v47
	v_cvt_pk_bf16_f32 v32, v32, v33
	v_cvt_pk_bf16_f32 v33, v34, v35
	v_cvt_pk_bf16_f32 v34, v24, v25
	v_cvt_pk_bf16_f32 v35, v26, v27
	v_add_u32_e32 v184, 0x900000, v183
	global_store_dwordx4 v184, v[52:55], s[14:15]
	global_store_dwordx4 v184, v[32:35], s[14:15] offset:256
	v_mul_f32_e32 v36, v36, v146
	v_mul_f32_e32 v37, v37, v147
	v_mul_f32_e32 v38, v38, v148
	v_mul_f32_e32 v39, v39, v149
	v_mul_f32_e32 v28, v28, v150
	v_mul_f32_e32 v29, v29, v151
	v_mul_f32_e32 v30, v30, v152
	v_mul_f32_e32 v31, v31, v153
	v_mul_f32_e32 v16, v16, v154
	v_mul_f32_e32 v17, v17, v155
	v_mul_f32_e32 v18, v18, v156
	v_mul_f32_e32 v19, v19, v157
	v_mul_f32_e32 v8, v8, v158
	v_mul_f32_e32 v9, v9, v159
	v_mul_f32_e32 v10, v10, v160
	v_mul_f32_e32 v11, v11, v161
	v_cvt_pk_bf16_f32 v36, v36, v37
	v_cvt_pk_bf16_f32 v37, v38, v39
	v_cvt_pk_bf16_f32 v38, v28, v29
	v_cvt_pk_bf16_f32 v39, v30, v31
	v_cvt_pk_bf16_f32 v16, v16, v17
	v_cvt_pk_bf16_f32 v17, v18, v19
	v_cvt_pk_bf16_f32 v18, v8, v9
	v_cvt_pk_bf16_f32 v19, v10, v11
	v_add_u32_e32 v184, 0xa00000, v183
	global_store_dwordx4 v184, v[36:39], s[14:15]
	global_store_dwordx4 v184, v[16:19], s[14:15] offset:256
	v_mul_f32_e32 v20, v20, v146
	v_mul_f32_e32 v21, v21, v147
	v_mul_f32_e32 v22, v22, v148
	v_mul_f32_e32 v23, v23, v149
	v_mul_f32_e32 v12, v12, v150
	v_mul_f32_e32 v13, v13, v151
	v_mul_f32_e32 v14, v14, v152
	v_mul_f32_e32 v15, v15, v153
	v_mul_f32_e32 v4, v4, v154
	v_mul_f32_e32 v5, v5, v155
	v_mul_f32_e32 v6, v6, v156
	v_mul_f32_e32 v7, v7, v157
	v_mul_f32_e32 v0, v0, v158
	v_mul_f32_e32 v1, v1, v159
	v_mul_f32_e32 v2, v2, v160
	v_mul_f32_e32 v3, v3, v161
	v_cvt_pk_bf16_f32 v20, v20, v21
	v_cvt_pk_bf16_f32 v21, v22, v23
	v_cvt_pk_bf16_f32 v22, v12, v13
	v_cvt_pk_bf16_f32 v23, v14, v15
	v_cvt_pk_bf16_f32 v4, v4, v5
	v_cvt_pk_bf16_f32 v5, v6, v7
	v_cvt_pk_bf16_f32 v6, v0, v1
	v_cvt_pk_bf16_f32 v7, v2, v3
	v_add_u32_e32 v184, 0xb00000, v183
	global_store_dwordx4 v184, v[20:23], s[14:15]
	global_store_dwordx4 v184, v[4:7], s[14:15] offset:256
	s_andn2_b64 vcc, exec, s[6:7]
	s_mov_b64 s[6:7], -1
	s_cbranch_vccnz .LBB0_492
	s_andn2_b64 vcc, exec, s[12:13]
	s_cbranch_vccnz .LBB0_491
	s_barrier
	s_branch .LBB0_491

; __device__ __forceinline__ unsigned cvtpk(float lo, float hi) { f32x2_t v = {lo, hi}; bf16x2_t b = __builtin_convertvector(v, bf16x2_t); return __builtin_bit_cast(unsigned, b); }
;     __device__ __forceinline__ void operator()(const f32x4 (&acc)[2][2][4][2], const Unit& u, int wr, int wc, int fr, int fq) const {
;         const int row0 = u.pm * BM + wr * 64 + fr, col0 = u.pn * BM + wc * 32 + 8 * fq;
;         u32x4 xv[RM == 0 ? 1 : 2][RM == 0 ? 1 : 4][RM == 0 ? 1 : 2];
;         if (RM != 0) {
; #pragma unroll
;             for (int ai = 0; ai < 2; ++ai)
; #pragma unroll
;                 for (int m = 0; m < 4; ++m)
; #pragma unroll
;                     for (int bj = 0; bj < 2; ++bj) xv[RM == 0 ? 0 : ai][RM == 0 ? 0 : m][RM == 0 ? 0 : bj] = *(const u32x4*)(xb + (size_t)(row0 + ai * HALF + m * 16) * DM + col0 + bj * HALF);
;         }
; #pragma unroll
;         for (int ai = 0; ai < 2; ++ai)
; #pragma unroll
;             for (int m = 0; m < 4; ++m) {
;                 const int row = row0 + ai * HALF + m * 16; float s = 0.f;
; #pragma unroll
;                 for (int bj = 0; bj < 2; ++bj) {
;                     const size_t off = (size_t)row * DM + col0 + bj * HALF;
;                     f32x4 v0, v1;
;                     if (RM == 0) { v0 = *(const f32x4*)(xf + off); v1 = *(const f32x4*)(xf + off + 4); }
;                     else { const u32x4 w = xv[RM == 0 ? 0 : ai][RM == 0 ? 0 : m][RM == 0 ? 0 : bj]; v0 = (f32x4){bflo(w.x), bfhi(w.x), bflo(w.y), bfhi(w.y)}; v1 = (f32x4){bflo(w.z), bfhi(w.z), bflo(w.w), bfhi(w.w)}; }
;                     v0 = v0 + acc[ai][bj][m][0] * alpha; v1 = v1 + acc[ai][bj][m][1] * alpha;
;                     if (RM == 2) { *(f32x4*)(outf + off) = v0; *(f32x4*)(outf + off + 4) = v1; }
;                     else {
;                         u32x4 w; w.x = cvtpk(v0[0], v0[1]); w.y = cvtpk(v0[2], v0[3]); w.z = cvtpk(v1[0], v1[1]); w.w = cvtpk(v1[2], v1[3]);
;                         *(u32x4*)(xb + off) = w;
;                         s += (v0[0] * v0[0] + v0[1] * v0[1]) + (v0[2] * v0[2] + v0[3] * v0[3]) + (v1[0] * v1[0] + v1[1] * v1[1]) + (v1[2] * v1[2] + v1[3] * v1[3]);
;                     }
;                 }
;                 if (RM != 2) { s += __shfl_xor(s, 16); s += __shfl_xor(s, 32); if (fq == 0) ssq_out[(size_t)row * 16 + u.pn * 4 + wc] = s; }
.LBB0_717:
	v_lshl_or_b32 v232, s12, 8, v242
	v_lshl_add_u32 v233, s34, 8, v240
	v_lshlrev_b32_e32 v204, 11, v233
	v_lshl_add_u32 v204, v232, 1, v204
	v_add_u32_e32 v205, 0x8000, v204
	v_add_u32_e32 v206, 0x10000, v204
	v_add_u32_e32 v207, 0x18000, v204
	v_add_u32_e32 v208, 0x40000, v204
	v_add_u32_e32 v209, 0x48000, v204
	v_add_u32_e32 v210, 0x50000, v204
	v_add_u32_e32 v211, 0x58000, v204
	global_load_dwordx4 v[152:155], v204, s[16:17]
	global_load_dwordx4 v[156:159], v204, s[16:17] offset:256
	global_load_dwordx4 v[160:163], v205, s[16:17]
	global_load_dwordx4 v[164:167], v205, s[16:17] offset:256
	global_load_dwordx4 v[168:171], v206, s[16:17]
	global_load_dwordx4 v[172:175], v206, s[16:17] offset:256
	global_load_dwordx4 v[176:179], v207, s[16:17]
	global_load_dwordx4 v[180:183], v207, s[16:17] offset:256
	global_load_dwordx4 v[184:187], v208, s[16:17]
	global_load_dwordx4 v[188:191], v208, s[16:17] offset:256
	global_load_dwordx4 v[120:123], v209, s[16:17]
	global_load_dwordx4 v[124:127], v209, s[16:17] offset:256
	global_load_dwordx4 v[128:131], v210, s[16:17]
	global_load_dwordx4 v[132:135], v210, s[16:17] offset:256
	global_load_dwordx4 v[136:139], v211, s[16:17]
	global_load_dwordx4 v[140:143], v211, s[16:17] offset:256
	v_mbcnt_lo_u32_b32 v234, -1, 0
	v_mbcnt_hi_u32_b32 v234, -1, v234
	v_lshrrev_b32_e32 v235, 4, v234
	v_and_b32_e32 v236, 1, v235
	v_lshlrev_b32_e32 v236, 5, v236
	v_lshrrev_b32_e32 v235, 1, v235
	v_lshl_add_u32 v236, v235, 4, v236
	v_add_u32_e32 v236, v233, v236
	v_lshlrev_b32_e32 v236, 6, v236
	s_lshl_b32 s36, s12, 4
	s_lshl_b32 s37, s44, 2
	s_add_u32 s36, s36, s37
	v_add_u32_e32 v236, s36, v236
	v_add_u32_e32 v237, 0x2000, v236
	s_waitcnt vmcnt(14)
	v_lshlrev_b32_e32 v222, 16, v152
	v_and_b32_e32 v223, 0xffff0000, v152
	v_lshlrev_b32_e32 v224, 16, v153
	v_and_b32_e32 v225, 0xffff0000, v153
	v_lshlrev_b32_e32 v226, 16, v154
	v_and_b32_e32 v227, 0xffff0000, v154
	v_lshlrev_b32_e32 v228, 16, v155
	v_and_b32_e32 v229, 0xffff0000, v155
	v_add_f32_e32 v148, v148, v222
	v_add_f32_e32 v149, v149, v223
	v_add_f32_e32 v150, v150, v224
	v_add_f32_e32 v151, v151, v225
	v_add_f32_e32 v144, v144, v226
	v_add_f32_e32 v145, v145, v227
	v_add_f32_e32 v146, v146, v228
	v_add_f32_e32 v147, v147, v229
	v_cvt_pk_bf16_f32 v152, v148, v149
	v_cvt_pk_bf16_f32 v153, v150, v151
	v_cvt_pk_bf16_f32 v154, v144, v145
	v_cvt_pk_bf16_f32 v155, v146, v147
	global_store_dwordx4 v204, v[152:155], s[16:17]
	v_mul_f32_e32 v220, v148, v148
	v_mul_f32_e32 v221, v149, v149
	v_fmac_f32_e32 v220, v150, v150
	v_fmac_f32_e32 v221, v151, v151
	v_fmac_f32_e32 v220, v144, v144
	v_fmac_f32_e32 v221, v145, v145
	v_fmac_f32_e32 v220, v146, v146
	v_fmac_f32_e32 v221, v147, v147
	v_lshlrev_b32_e32 v222, 16, v156
	v_and_b32_e32 v223, 0xffff0000, v156
	v_lshlrev_b32_e32 v224, 16, v157
	v_and_b32_e32 v225, 0xffff0000, v157
	v_lshlrev_b32_e32 v226, 16, v158
	v_and_b32_e32 v227, 0xffff0000, v158
	v_lshlrev_b32_e32 v228, 16, v159
	v_and_b32_e32 v229, 0xffff0000, v159
	v_add_f32_e32 v116, v116, v222
	v_add_f32_e32 v117, v117, v223
	v_add_f32_e32 v118, v118, v224
	v_add_f32_e32 v119, v119, v225
	v_add_f32_e32 v112, v112, v226
	v_add_f32_e32 v113, v113, v227
	v_add_f32_e32 v114, v114, v228
	v_add_f32_e32 v115, v115, v229
	v_cvt_pk_bf16_f32 v156, v116, v117
	v_cvt_pk_bf16_f32 v157, v118, v119
	v_cvt_pk_bf16_f32 v158, v112, v113
	v_cvt_pk_bf16_f32 v159, v114, v115
	global_store_dwordx4 v204, v[156:159], s[16:17] offset:256
	v_mul_f32_e32 v230, v116, v116
	v_mul_f32_e32 v231, v117, v117
	v_fmac_f32_e32 v230, v118, v118
	v_fmac_f32_e32 v231, v119, v119
	v_fmac_f32_e32 v230, v112, v112
	v_fmac_f32_e32 v231, v113, v113
	v_fmac_f32_e32 v230, v114, v114
	v_fmac_f32_e32 v231, v115, v115
	v_add_f32_e32 v220, v220, v230
	v_add_f32_e32 v221, v221, v231
	v_add_f32_e32 v212, v220, v221
	s_waitcnt vmcnt(14)
	v_lshlrev_b32_e32 v222, 16, v160
	v_and_b32_e32 v223, 0xffff0000, v160
	v_lshlrev_b32_e32 v224, 16, v161
	v_and_b32_e32 v225, 0xffff0000, v161
	v_lshlrev_b32_e32 v226, 16, v162
	v_and_b32_e32 v227, 0xffff0000, v162
	v_lshlrev_b32_e32 v228, 16, v163
	v_and_b32_e32 v229, 0xffff0000, v163
	v_add_f32_e32 v108, v108, v222
	v_add_f32_e32 v109, v109, v223
	v_add_f32_e32 v110, v110, v224
	v_add_f32_e32 v111, v111, v225
	v_add_f32_e32 v104, v104, v226
	v_add_f32_e32 v105, v105, v227
	v_add_f32_e32 v106, v106, v228
	v_add_f32_e32 v107, v107, v229
	v_cvt_pk_bf16_f32 v160, v108, v109
	v_cvt_pk_bf16_f32 v161, v110, v111
	v_cvt_pk_bf16_f32 v162, v104, v105
	v_cvt_pk_bf16_f32 v163, v106, v107
	global_store_dwordx4 v205, v[160:163], s[16:17]
	v_mul_f32_e32 v220, v108, v108
	v_mul_f32_e32 v221, v109, v109
	v_fmac_f32_e32 v220, v110, v110
	v_fmac_f32_e32 v221, v111, v111
	v_fmac_f32_e32 v220, v104, v104
	v_fmac_f32_e32 v221, v105, v105
	v_fmac_f32_e32 v220, v106, v106
	v_fmac_f32_e32 v221, v107, v107
	v_lshlrev_b32_e32 v222, 16, v164
	v_and_b32_e32 v223, 0xffff0000, v164
	v_lshlrev_b32_e32 v224, 16, v165
	v_and_b32_e32 v225, 0xffff0000, v165
	v_lshlrev_b32_e32 v226, 16, v166
	v_and_b32_e32 v227, 0xffff0000, v166
	v_lshlrev_b32_e32 v228, 16, v167
	v_and_b32_e32 v229, 0xffff0000, v167
	v_add_f32_e32 v100, v100, v222
	v_add_f32_e32 v101, v101, v223
	v_add_f32_e32 v102, v102, v224
	v_add_f32_e32 v103, v103, v225
	v_add_f32_e32 v96, v96, v226
	v_add_f32_e32 v97, v97, v227
	v_add_f32_e32 v98, v98, v228
	v_add_f32_e32 v99, v99, v229
	v_cvt_pk_bf16_f32 v164, v100, v101
	v_cvt_pk_bf16_f32 v165, v102, v103
	v_cvt_pk_bf16_f32 v166, v96, v97
	v_cvt_pk_bf16_f32 v167, v98, v99
	global_store_dwordx4 v205, v[164:167], s[16:17] offset:256
	v_mul_f32_e32 v230, v100, v100
	v_mul_f32_e32 v231, v101, v101
	v_fmac_f32_e32 v230, v102, v102
	v_fmac_f32_e32 v231, v103, v103
	v_fmac_f32_e32 v230, v96, v96
	v_fmac_f32_e32 v231, v97, v97
	v_fmac_f32_e32 v230, v98, v98
	v_fmac_f32_e32 v231, v99, v99
	v_add_f32_e32 v220, v220, v230
	v_add_f32_e32 v221, v221, v231
	v_add_f32_e32 v213, v220, v221
	s_waitcnt vmcnt(14)
; __device__ __forceinline__ unsigned cvtpk(float lo, float hi) { f32x2_t v = {lo, hi}; bf16x2_t b = __builtin_convertvector(v, bf16x2_t); return __builtin_bit_cast(unsigned, b); }
; __device__ __forceinline__ float bflo(unsigned w) { return __uint_as_float(w << 16); }
; __device__ __forceinline__ float bfhi(unsigned w) { return __uint_as_float(w & 0xffff0000u); }
;     __device__ __forceinline__ void operator()(const f32x4 (&acc)[2][2][4][2], const Unit& u, int wr, int wc, int fr, int fq) const {
;     ...
;         for (int ai = 0; ai < 2; ++ai)
; #pragma unroll
;             for (int m = 0; m < 4; ++m) {
;                 const int row = row0 + ai * HALF + m * 16; float s = 0.f;
; #pragma unroll
;                 for (int bj = 0; bj < 2; ++bj) {
;                     const size_t off = (size_t)row * DM + col0 + bj * HALF;
;                     f32x4 v0, v1;
;                     if (RM == 0) { v0 = *(const f32x4*)(xf + off); v1 = *(const f32x4*)(xf + off + 4); }
;                     else { const u32x4 w = xv[RM == 0 ? 0 : ai][RM == 0 ? 0 : m][RM == 0 ? 0 : bj]; v0 = (f32x4){bflo(w.x), bfhi(w.x), bflo(w.y), bfhi(w.y)}; v1 = (f32x4){bflo(w.z), bfhi(w.z), bflo(w.w), bfhi(w.w)}; }
;                     v0 = v0 + acc[ai][bj][m][0] * alpha; v1 = v1 + acc[ai][bj][m][1] * alpha;
;                     if (RM == 2) { *(f32x4*)(outf + off) = v0; *(f32x4*)(outf + off + 4) = v1; }
;                     else {
;                         u32x4 w; w.x = cvtpk(v0[0], v0[1]); w.y = cvtpk(v0[2], v0[3]); w.z = cvtpk(v1[0], v1[1]); w.w = cvtpk(v1[2], v1[3]);
;                         *(u32x4*)(xb + off) = w;
;                         s += (v0[0] * v0[0] + v0[1] * v0[1]) + (v0[2] * v0[2] + v0[3] * v0[3]) + (v1[0] * v1[0] + v1[1] * v1[1]) + (v1[2] * v1[2] + v1[3] * v1[3]);
;                     }
;                 }
	v_lshlrev_b32_e32 v222, 16, v168
	v_and_b32_e32 v223, 0xffff0000, v168
	v_lshlrev_b32_e32 v224, 16, v169
	v_and_b32_e32 v225, 0xffff0000, v169
	v_lshlrev_b32_e32 v226, 16, v170
	v_and_b32_e32 v227, 0xffff0000, v170
	v_lshlrev_b32_e32 v228, 16, v171
	v_and_b32_e32 v229, 0xffff0000, v171
	v_add_f32_e32 v92, v92, v222
	v_add_f32_e32 v93, v93, v223
	v_add_f32_e32 v94, v94, v224
	v_add_f32_e32 v95, v95, v225
	v_add_f32_e32 v88, v88, v226
	v_add_f32_e32 v89, v89, v227
	v_add_f32_e32 v90, v90, v228
	v_add_f32_e32 v91, v91, v229
	v_cvt_pk_bf16_f32 v168, v92, v93
	v_cvt_pk_bf16_f32 v169, v94, v95
	v_cvt_pk_bf16_f32 v170, v88, v89
	v_cvt_pk_bf16_f32 v171, v90, v91
	global_store_dwordx4 v206, v[168:171], s[16:17]
	v_mul_f32_e32 v220, v92, v92
	v_mul_f32_e32 v221, v93, v93
	v_fmac_f32_e32 v220, v94, v94
	v_fmac_f32_e32 v221, v95, v95
	v_fmac_f32_e32 v220, v88, v88
	v_fmac_f32_e32 v221, v89, v89
	v_fmac_f32_e32 v220, v90, v90
	v_fmac_f32_e32 v221, v91, v91
	v_lshlrev_b32_e32 v222, 16, v172
	v_and_b32_e32 v223, 0xffff0000, v172
	v_lshlrev_b32_e32 v224, 16, v173
	v_and_b32_e32 v225, 0xffff0000, v173
	v_lshlrev_b32_e32 v226, 16, v174
	v_and_b32_e32 v227, 0xffff0000, v174
	v_lshlrev_b32_e32 v228, 16, v175
	v_and_b32_e32 v229, 0xffff0000, v175
	v_add_f32_e32 v84, v84, v222
	v_add_f32_e32 v85, v85, v223
	v_add_f32_e32 v86, v86, v224
	v_add_f32_e32 v87, v87, v225
	v_add_f32_e32 v80, v80, v226
	v_add_f32_e32 v81, v81, v227
	v_add_f32_e32 v82, v82, v228
	v_add_f32_e32 v83, v83, v229
	v_cvt_pk_bf16_f32 v172, v84, v85
	v_cvt_pk_bf16_f32 v173, v86, v87
	v_cvt_pk_bf16_f32 v174, v80, v81
	v_cvt_pk_bf16_f32 v175, v82, v83
	global_store_dwordx4 v206, v[172:175], s[16:17] offset:256
	v_mul_f32_e32 v230, v84, v84
	v_mul_f32_e32 v231, v85, v85
	v_fmac_f32_e32 v230, v86, v86
	v_fmac_f32_e32 v231, v87, v87
	v_fmac_f32_e32 v230, v80, v80
	v_fmac_f32_e32 v231, v81, v81
	v_fmac_f32_e32 v230, v82, v82
	v_fmac_f32_e32 v231, v83, v83
	v_add_f32_e32 v220, v220, v230
	v_add_f32_e32 v221, v221, v231
	v_add_f32_e32 v214, v220, v221
	s_waitcnt vmcnt(14)
	v_lshlrev_b32_e32 v222, 16, v176
	v_and_b32_e32 v223, 0xffff0000, v176
	v_lshlrev_b32_e32 v224, 16, v177
	v_and_b32_e32 v225, 0xffff0000, v177
	v_lshlrev_b32_e32 v226, 16, v178
	v_and_b32_e32 v227, 0xffff0000, v178
	v_lshlrev_b32_e32 v228, 16, v179
	v_and_b32_e32 v229, 0xffff0000, v179
	v_add_f32_e32 v76, v76, v222
	v_add_f32_e32 v77, v77, v223
	v_add_f32_e32 v78, v78, v224
	v_add_f32_e32 v79, v79, v225
	v_add_f32_e32 v72, v72, v226
	v_add_f32_e32 v73, v73, v227
	v_add_f32_e32 v74, v74, v228
	v_add_f32_e32 v75, v75, v229
	v_cvt_pk_bf16_f32 v176, v76, v77
	v_cvt_pk_bf16_f32 v177, v78, v79
	v_cvt_pk_bf16_f32 v178, v72, v73
	v_cvt_pk_bf16_f32 v179, v74, v75
	global_store_dwordx4 v207, v[176:179], s[16:17]
	v_mul_f32_e32 v220, v76, v76
	v_mul_f32_e32 v221, v77, v77
	v_fmac_f32_e32 v220, v78, v78
	v_fmac_f32_e32 v221, v79, v79
	v_fmac_f32_e32 v220, v72, v72
	v_fmac_f32_e32 v221, v73, v73
	v_fmac_f32_e32 v220, v74, v74
	v_fmac_f32_e32 v221, v75, v75
	v_lshlrev_b32_e32 v222, 16, v180
	v_and_b32_e32 v223, 0xffff0000, v180
	v_lshlrev_b32_e32 v224, 16, v181
	v_and_b32_e32 v225, 0xffff0000, v181
	v_lshlrev_b32_e32 v226, 16, v182
	v_and_b32_e32 v227, 0xffff0000, v182
	v_lshlrev_b32_e32 v228, 16, v183
	v_and_b32_e32 v229, 0xffff0000, v183
	v_add_f32_e32 v68, v68, v222
	v_add_f32_e32 v69, v69, v223
	v_add_f32_e32 v70, v70, v224
	v_add_f32_e32 v71, v71, v225
	v_add_f32_e32 v64, v64, v226
	v_add_f32_e32 v65, v65, v227
	v_add_f32_e32 v66, v66, v228
	v_add_f32_e32 v67, v67, v229
	v_cvt_pk_bf16_f32 v180, v68, v69
	v_cvt_pk_bf16_f32 v181, v70, v71
	v_cvt_pk_bf16_f32 v182, v64, v65
	v_cvt_pk_bf16_f32 v183, v66, v67
	global_store_dwordx4 v207, v[180:183], s[16:17] offset:256
	v_mul_f32_e32 v230, v68, v68
	v_mul_f32_e32 v231, v69, v69
	v_fmac_f32_e32 v230, v70, v70
	v_fmac_f32_e32 v231, v71, v71
	v_fmac_f32_e32 v230, v64, v64
	v_fmac_f32_e32 v231, v65, v65
	v_fmac_f32_e32 v230, v66, v66
	v_fmac_f32_e32 v231, v67, v67
	v_add_f32_e32 v220, v220, v230
	v_add_f32_e32 v221, v221, v231
	v_add_f32_e32 v215, v220, v221
	s_waitcnt vmcnt(14)
	v_lshlrev_b32_e32 v222, 16, v184
	v_and_b32_e32 v223, 0xffff0000, v184
	v_lshlrev_b32_e32 v224, 16, v185
	v_and_b32_e32 v225, 0xffff0000, v185
	v_lshlrev_b32_e32 v226, 16, v186
	v_and_b32_e32 v227, 0xffff0000, v186
	v_lshlrev_b32_e32 v228, 16, v187
	v_and_b32_e32 v229, 0xffff0000, v187
	v_add_f32_e32 v60, v60, v222
	v_add_f32_e32 v61, v61, v223
	v_add_f32_e32 v62, v62, v224
	v_add_f32_e32 v63, v63, v225
	v_add_f32_e32 v56, v56, v226
	v_add_f32_e32 v57, v57, v227
	v_add_f32_e32 v58, v58, v228
	v_add_f32_e32 v59, v59, v229
	v_cvt_pk_bf16_f32 v184, v60, v61
	v_cvt_pk_bf16_f32 v185, v62, v63
	v_cvt_pk_bf16_f32 v186, v56, v57
	v_cvt_pk_bf16_f32 v187, v58, v59
	global_store_dwordx4 v208, v[184:187], s[16:17]
	v_mul_f32_e32 v220, v60, v60
	v_mul_f32_e32 v221, v61, v61
	v_fmac_f32_e32 v220, v62, v62
	v_fmac_f32_e32 v221, v63, v63
	v_fmac_f32_e32 v220, v56, v56
	v_fmac_f32_e32 v221, v57, v57
	v_fmac_f32_e32 v220, v58, v58
	v_fmac_f32_e32 v221, v59, v59
	v_lshlrev_b32_e32 v222, 16, v188
	v_and_b32_e32 v223, 0xffff0000, v188
	v_lshlrev_b32_e32 v224, 16, v189
	v_and_b32_e32 v225, 0xffff0000, v189
	v_lshlrev_b32_e32 v226, 16, v190
	v_and_b32_e32 v227, 0xffff0000, v190
	v_lshlrev_b32_e32 v228, 16, v191
	v_and_b32_e32 v229, 0xffff0000, v191
	v_add_f32_e32 v52, v52, v222
	v_add_f32_e32 v53, v53, v223
	v_add_f32_e32 v54, v54, v224
	v_add_f32_e32 v55, v55, v225
	v_add_f32_e32 v48, v48, v226
	v_add_f32_e32 v49, v49, v227
	v_add_f32_e32 v50, v50, v228
	v_add_f32_e32 v51, v51, v229
	v_cvt_pk_bf16_f32 v188, v52, v53
	v_cvt_pk_bf16_f32 v189, v54, v55
	v_cvt_pk_bf16_f32 v190, v48, v49
	v_cvt_pk_bf16_f32 v191, v50, v51
	global_store_dwordx4 v208, v[188:191], s[16:17] offset:256
	v_mul_f32_e32 v230, v52, v52
	v_mul_f32_e32 v231, v53, v53
	v_fmac_f32_e32 v230, v54, v54
	v_fmac_f32_e32 v231, v55, v55
	v_fmac_f32_e32 v230, v48, v48
	v_fmac_f32_e32 v231, v49, v49
	v_fmac_f32_e32 v230, v50, v50
	v_fmac_f32_e32 v231, v51, v51
	v_add_f32_e32 v220, v220, v230
	v_add_f32_e32 v221, v221, v231
	v_add_f32_e32 v216, v220, v221
	s_waitcnt vmcnt(14)
; __device__ __forceinline__ unsigned cvtpk(float lo, float hi) { f32x2_t v = {lo, hi}; bf16x2_t b = __builtin_convertvector(v, bf16x2_t); return __builtin_bit_cast(unsigned, b); }
; __device__ __forceinline__ float bflo(unsigned w) { return __uint_as_float(w << 16); }
; __device__ __forceinline__ float bfhi(unsigned w) { return __uint_as_float(w & 0xffff0000u); }
;     __device__ __forceinline__ void operator()(const f32x4 (&acc)[2][2][4][2], const Unit& u, int wr, int wc, int fr, int fq) const {
;     ...
;         for (int ai = 0; ai < 2; ++ai)
; #pragma unroll
;             for (int m = 0; m < 4; ++m) {
;                 const int row = row0 + ai * HALF + m * 16; float s = 0.f;
; #pragma unroll
;                 for (int bj = 0; bj < 2; ++bj) {
;                     const size_t off = (size_t)row * DM + col0 + bj * HALF;
;                     f32x4 v0, v1;
;                     if (RM == 0) { v0 = *(const f32x4*)(xf + off); v1 = *(const f32x4*)(xf + off + 4); }
;                     else { const u32x4 w = xv[RM == 0 ? 0 : ai][RM == 0 ? 0 : m][RM == 0 ? 0 : bj]; v0 = (f32x4){bflo(w.x), bfhi(w.x), bflo(w.y), bfhi(w.y)}; v1 = (f32x4){bflo(w.z), bfhi(w.z), bflo(w.w), bfhi(w.w)}; }
;                     v0 = v0 + acc[ai][bj][m][0] * alpha; v1 = v1 + acc[ai][bj][m][1] * alpha;
;                     if (RM == 2) { *(f32x4*)(outf + off) = v0; *(f32x4*)(outf + off + 4) = v1; }
;                     else {
;                         u32x4 w; w.x = cvtpk(v0[0], v0[1]); w.y = cvtpk(v0[2], v0[3]); w.z = cvtpk(v1[0], v1[1]); w.w = cvtpk(v1[2], v1[3]);
;                         *(u32x4*)(xb + off) = w;
;                         s += (v0[0] * v0[0] + v0[1] * v0[1]) + (v0[2] * v0[2] + v0[3] * v0[3]) + (v1[0] * v1[0] + v1[1] * v1[1]) + (v1[2] * v1[2] + v1[3] * v1[3]);
;                     }
;                 }
;                 if (RM != 2) { s += __shfl_xor(s, 16); s += __shfl_xor(s, 32); if (fq == 0) ssq_out[(size_t)row * 16 + u.pn * 4 + wc] = s; }
;             }
	v_lshlrev_b32_e32 v222, 16, v120
	v_and_b32_e32 v223, 0xffff0000, v120
	v_lshlrev_b32_e32 v224, 16, v121
	v_and_b32_e32 v225, 0xffff0000, v121
	v_lshlrev_b32_e32 v226, 16, v122
	v_and_b32_e32 v227, 0xffff0000, v122
	v_lshlrev_b32_e32 v228, 16, v123
	v_and_b32_e32 v229, 0xffff0000, v123
	v_add_f32_e32 v44, v44, v222
	v_add_f32_e32 v45, v45, v223
	v_add_f32_e32 v46, v46, v224
	v_add_f32_e32 v47, v47, v225
	v_add_f32_e32 v40, v40, v226
	v_add_f32_e32 v41, v41, v227
	v_add_f32_e32 v42, v42, v228
	v_add_f32_e32 v43, v43, v229
	v_cvt_pk_bf16_f32 v120, v44, v45
	v_cvt_pk_bf16_f32 v121, v46, v47
	v_cvt_pk_bf16_f32 v122, v40, v41
	v_cvt_pk_bf16_f32 v123, v42, v43
	global_store_dwordx4 v209, v[120:123], s[16:17]
	v_mul_f32_e32 v220, v44, v44
	v_mul_f32_e32 v221, v45, v45
	v_fmac_f32_e32 v220, v46, v46
	v_fmac_f32_e32 v221, v47, v47
	v_fmac_f32_e32 v220, v40, v40
	v_fmac_f32_e32 v221, v41, v41
	v_fmac_f32_e32 v220, v42, v42
	v_fmac_f32_e32 v221, v43, v43
	v_lshlrev_b32_e32 v222, 16, v124
	v_and_b32_e32 v223, 0xffff0000, v124
	v_lshlrev_b32_e32 v224, 16, v125
	v_and_b32_e32 v225, 0xffff0000, v125
	v_lshlrev_b32_e32 v226, 16, v126
	v_and_b32_e32 v227, 0xffff0000, v126
	v_lshlrev_b32_e32 v228, 16, v127
	v_and_b32_e32 v229, 0xffff0000, v127
	v_add_f32_e32 v36, v36, v222
	v_add_f32_e32 v37, v37, v223
	v_add_f32_e32 v38, v38, v224
	v_add_f32_e32 v39, v39, v225
	v_add_f32_e32 v32, v32, v226
	v_add_f32_e32 v33, v33, v227
	v_add_f32_e32 v34, v34, v228
	v_add_f32_e32 v35, v35, v229
	v_cvt_pk_bf16_f32 v124, v36, v37
	v_cvt_pk_bf16_f32 v125, v38, v39
	v_cvt_pk_bf16_f32 v126, v32, v33
	v_cvt_pk_bf16_f32 v127, v34, v35
	global_store_dwordx4 v209, v[124:127], s[16:17] offset:256
	v_mul_f32_e32 v230, v36, v36
	v_mul_f32_e32 v231, v37, v37
	v_fmac_f32_e32 v230, v38, v38
	v_fmac_f32_e32 v231, v39, v39
	v_fmac_f32_e32 v230, v32, v32
	v_fmac_f32_e32 v231, v33, v33
	v_fmac_f32_e32 v230, v34, v34
	v_fmac_f32_e32 v231, v35, v35
	v_add_f32_e32 v220, v220, v230
	v_add_f32_e32 v221, v221, v231
	v_add_f32_e32 v217, v220, v221
	s_waitcnt vmcnt(14)
	v_lshlrev_b32_e32 v222, 16, v128
	v_and_b32_e32 v223, 0xffff0000, v128
	v_lshlrev_b32_e32 v224, 16, v129
	v_and_b32_e32 v225, 0xffff0000, v129
	v_lshlrev_b32_e32 v226, 16, v130
	v_and_b32_e32 v227, 0xffff0000, v130
	v_lshlrev_b32_e32 v228, 16, v131
	v_and_b32_e32 v229, 0xffff0000, v131
	v_add_f32_e32 v28, v28, v222
	v_add_f32_e32 v29, v29, v223
	v_add_f32_e32 v30, v30, v224
	v_add_f32_e32 v31, v31, v225
	v_add_f32_e32 v24, v24, v226
	v_add_f32_e32 v25, v25, v227
	v_add_f32_e32 v26, v26, v228
	v_add_f32_e32 v27, v27, v229
	v_cvt_pk_bf16_f32 v128, v28, v29
	v_cvt_pk_bf16_f32 v129, v30, v31
	v_cvt_pk_bf16_f32 v130, v24, v25
	v_cvt_pk_bf16_f32 v131, v26, v27
	global_store_dwordx4 v210, v[128:131], s[16:17]
	v_mul_f32_e32 v220, v28, v28
	v_mul_f32_e32 v221, v29, v29
	v_fmac_f32_e32 v220, v30, v30
	v_fmac_f32_e32 v221, v31, v31
	v_fmac_f32_e32 v220, v24, v24
	v_fmac_f32_e32 v221, v25, v25
	v_fmac_f32_e32 v220, v26, v26
	v_fmac_f32_e32 v221, v27, v27
	v_lshlrev_b32_e32 v222, 16, v132
	v_and_b32_e32 v223, 0xffff0000, v132
	v_lshlrev_b32_e32 v224, 16, v133
	v_and_b32_e32 v225, 0xffff0000, v133
	v_lshlrev_b32_e32 v226, 16, v134
	v_and_b32_e32 v227, 0xffff0000, v134
	v_lshlrev_b32_e32 v228, 16, v135
	v_and_b32_e32 v229, 0xffff0000, v135
	v_add_f32_e32 v20, v20, v222
	v_add_f32_e32 v21, v21, v223
	v_add_f32_e32 v22, v22, v224
	v_add_f32_e32 v23, v23, v225
	v_add_f32_e32 v16, v16, v226
	v_add_f32_e32 v17, v17, v227
	v_add_f32_e32 v18, v18, v228
	v_add_f32_e32 v19, v19, v229
	v_cvt_pk_bf16_f32 v132, v20, v21
	v_cvt_pk_bf16_f32 v133, v22, v23
	v_cvt_pk_bf16_f32 v134, v16, v17
	v_cvt_pk_bf16_f32 v135, v18, v19
	global_store_dwordx4 v210, v[132:135], s[16:17] offset:256
	v_mul_f32_e32 v230, v20, v20
	v_mul_f32_e32 v231, v21, v21
	v_fmac_f32_e32 v230, v22, v22
	v_fmac_f32_e32 v231, v23, v23
	v_fmac_f32_e32 v230, v16, v16
	v_fmac_f32_e32 v231, v17, v17
	v_fmac_f32_e32 v230, v18, v18
	v_fmac_f32_e32 v231, v19, v19
	v_add_f32_e32 v220, v220, v230
	v_add_f32_e32 v221, v221, v231
	v_add_f32_e32 v218, v220, v221
	s_waitcnt vmcnt(14)
	v_lshlrev_b32_e32 v222, 16, v136
	v_and_b32_e32 v223, 0xffff0000, v136
	v_lshlrev_b32_e32 v224, 16, v137
	v_and_b32_e32 v225, 0xffff0000, v137
	v_lshlrev_b32_e32 v226, 16, v138
	v_and_b32_e32 v227, 0xffff0000, v138
	v_lshlrev_b32_e32 v228, 16, v139
	v_and_b32_e32 v229, 0xffff0000, v139
	v_add_f32_e32 v12, v12, v222
	v_add_f32_e32 v13, v13, v223
	v_add_f32_e32 v14, v14, v224
	v_add_f32_e32 v15, v15, v225
	v_add_f32_e32 v8, v8, v226
	v_add_f32_e32 v9, v9, v227
	v_add_f32_e32 v10, v10, v228
	v_add_f32_e32 v11, v11, v229
	v_cvt_pk_bf16_f32 v136, v12, v13
	v_cvt_pk_bf16_f32 v137, v14, v15
	v_cvt_pk_bf16_f32 v138, v8, v9
	v_cvt_pk_bf16_f32 v139, v10, v11
	global_store_dwordx4 v211, v[136:139], s[16:17]
	v_mul_f32_e32 v220, v12, v12
	v_mul_f32_e32 v221, v13, v13
	v_fmac_f32_e32 v220, v14, v14
	v_fmac_f32_e32 v221, v15, v15
	v_fmac_f32_e32 v220, v8, v8
	v_fmac_f32_e32 v221, v9, v9
	v_fmac_f32_e32 v220, v10, v10
	v_fmac_f32_e32 v221, v11, v11
	v_lshlrev_b32_e32 v222, 16, v140
	v_and_b32_e32 v223, 0xffff0000, v140
	v_lshlrev_b32_e32 v224, 16, v141
	v_and_b32_e32 v225, 0xffff0000, v141
	v_lshlrev_b32_e32 v226, 16, v142
	v_and_b32_e32 v227, 0xffff0000, v142
	v_lshlrev_b32_e32 v228, 16, v143
	v_and_b32_e32 v229, 0xffff0000, v143
	v_add_f32_e32 v4, v4, v222
	v_add_f32_e32 v5, v5, v223
	v_add_f32_e32 v6, v6, v224
	v_add_f32_e32 v7, v7, v225
	v_add_f32_e32 v0, v0, v226
	v_add_f32_e32 v1, v1, v227
	v_add_f32_e32 v2, v2, v228
	v_add_f32_e32 v3, v3, v229
	v_cvt_pk_bf16_f32 v140, v4, v5
	v_cvt_pk_bf16_f32 v141, v6, v7
	v_cvt_pk_bf16_f32 v142, v0, v1
	v_cvt_pk_bf16_f32 v143, v2, v3
	global_store_dwordx4 v211, v[140:143], s[16:17] offset:256
	v_mul_f32_e32 v230, v4, v4
	v_mul_f32_e32 v231, v5, v5
	v_fmac_f32_e32 v230, v6, v6
	v_fmac_f32_e32 v231, v7, v7
	v_fmac_f32_e32 v230, v0, v0
	v_fmac_f32_e32 v231, v1, v1
	v_fmac_f32_e32 v230, v2, v2
	v_fmac_f32_e32 v231, v3, v3
	v_add_f32_e32 v220, v220, v230
	v_add_f32_e32 v221, v221, v231
	v_add_f32_e32 v219, v220, v221
	s_nop 1
	v_permlane32_swap_b32_e32 v212, v213
	v_permlane32_swap_b32_e32 v214, v215
	v_permlane32_swap_b32_e32 v216, v217
	v_permlane32_swap_b32_e32 v218, v219
	v_add_f32_e32 v212, v212, v213
	v_add_f32_e32 v214, v214, v215
	v_add_f32_e32 v216, v216, v217
	v_add_f32_e32 v218, v218, v219
	s_nop 1
	v_permlane16_swap_b32_e32 v212, v214
	v_permlane16_swap_b32_e32 v216, v218
	v_add_f32_e32 v212, v212, v214
	v_add_f32_e32 v216, v216, v218
	global_store_dword v236, v212, s[18:19]
	global_store_dword v237, v216, s[18:19]
	s_andn2_b64 vcc, exec, s[8:9]
	s_mov_b64 s[8:9], -1
	s_cbranch_vccnz .LBB0_706
	s_andn2_b64 vcc, exec, s[14:15]
	s_cbranch_vccnz .LBB0_705
	s_barrier
	s_branch .LBB0_705

; __device__ __forceinline__ unsigned cvtpk(float lo, float hi) { f32x2_t v = {lo, hi}; bf16x2_t b = __builtin_convertvector(v, bf16x2_t); return __builtin_bit_cast(unsigned, b); }
;     __device__ __forceinline__ void operator()(const f32x4 (&acc)[2][2][4][2], const Unit& u, int wr, int wc, int fr, int fq) const {
;         const int row0 = u.pm * BM + wr * 64 + fr, col0 = u.pn * BM + wc * 32 + 8 * fq;
;         float* so = (u.pn == 0) ? ssq_o[0] : (u.pn == 1) ? ssq_o[1] : (u.pn == 2) ? ssq_o[2] : (u.pn == 3) ? ssq_o[3] : nullptr;
; #pragma unroll
;         for (int ai = 0; ai < 2; ++ai)
; #pragma unroll
;             for (int m = 0; m < 4; ++m) {
;                 const int row = row0 + ai * HALF + m * 16; float s = 0.f;
;                 const float rs = ssq_in ? 1.0f / sqrtf(ssq_sum(ssq_in + (size_t)row * 16) * inv_dim + EPS) : 1.0f;
; #pragma unroll
;                 for (int bj = 0; bj < 2; ++bj) {
;                     int col = col0 + bj * HALF; if (hd_in) col = (col / hd_in) * hd_out + (col % hd_in);
;                     const f32x4 v0 = acc[ai][bj][m][0] * rs, v1 = acc[ai][bj][m][1] * rs;
;                     u32x4 w; w.x = cvtpk(v0[0], v0[1]); w.y = cvtpk(v0[2], v0[3]); w.z = cvtpk(v1[0], v1[1]); w.w = cvtpk(v1[2], v1[3]);
;                     *(u32x4*)(O + (size_t)row * ldc + col) = w;
;                     s += (v0[0] * v0[0] + v0[1] * v0[1]) + (v0[2] * v0[2] + v0[3] * v0[3]) + (v1[0] * v1[0] + v1[1] * v1[1]) + (v1[2] * v1[2] + v1[3] * v1[3]);
;                 }
.LBB0_814:
	v_readlane_b32 vcc_lo, v254, 7
	v_mbcnt_lo_u32_b32 v156, -1, 0
	v_mbcnt_hi_u32_b32 v156, -1, v156
	v_lshrrev_b32_e32 v157, 1, v156
	v_lshl_add_u32 v157, vcc_lo, 5, v157
	v_and_b32_e32 v158, 1, v156
	v_lshl_add_u32 v159, s8, 8, v157
	v_lshlrev_b32_e32 v159, 6, v159
	v_lshl_add_u32 v159, v158, 5, v159
	global_load_dwordx4 v[160:163], v159, s[16:17]
	global_load_dwordx4 v[164:167], v159, s[16:17] offset:16
	v_lshl_add_u32 v168, s8, 8, v148
	v_mul_u32_u24_e32 v168, 0x400, v168
	v_lshl_or_b32 v169, s9, 8, v150
	v_lshl_add_u32 v168, v169, 1, v168
	v_lshlrev_b32_e32 v157, 2, v157
	v_add_u32_e32 v157, 0x20100, v157
	v_lshlrev_b32_e32 v158, 2, v148
	v_add_u32_e32 v158, 0x20100, v158
	s_waitcnt vmcnt(0)
	v_add_f32_e32 v160, v160, v162
	v_add_f32_e32 v161, v161, v163
	v_add_f32_e32 v164, v164, v166
	v_add_f32_e32 v165, v165, v167
	v_add_f32_e32 v160, v160, v164
	v_add_f32_e32 v161, v161, v165
	v_add_f32_e32 v160, v160, v161
	s_nop 1
	v_add_f32_dpp v160, v160, v160 quad_perm:[1,0,3,2] row_mask:0xf bank_mask:0xf
	v_fmamk_f32 v160, v160, 0x3a800000, v154
	v_rsq_f32_e32 v160, v160
	s_nop 0
	ds_write_b32 v157, v160
	s_waitcnt lgkmcnt(0)
	s_barrier
	ds_read_b32 v160, v158 offset:0
	ds_read_b32 v161, v158 offset:64
	ds_read_b32 v162, v158 offset:128
	ds_read_b32 v163, v158 offset:192
	ds_read_b32 v164, v158 offset:512
	ds_read_b32 v165, v158 offset:576
	ds_read_b32 v166, v158 offset:640
	ds_read_b32 v167, v158 offset:704
	s_waitcnt lgkmcnt(7)
	v_mul_f32_e32 v124, v160, v124
	v_mul_f32_e32 v125, v160, v125
	v_mul_f32_e32 v126, v160, v126
	v_mul_f32_e32 v127, v160, v127
	v_mul_f32_e32 v120, v160, v120
	v_mul_f32_e32 v121, v160, v121
	v_mul_f32_e32 v122, v160, v122
	v_mul_f32_e32 v123, v160, v123
	v_mul_f32_e32 v116, v160, v116
	v_mul_f32_e32 v117, v160, v117
	v_mul_f32_e32 v118, v160, v118
	v_mul_f32_e32 v119, v160, v119
	v_mul_f32_e32 v112, v160, v112
	v_mul_f32_e32 v113, v160, v113
	v_mul_f32_e32 v114, v160, v114
	v_mul_f32_e32 v115, v160, v115
	v_cvt_pk_bf16_f32 v124, v124, v125
	v_cvt_pk_bf16_f32 v125, v126, v127
	v_cvt_pk_bf16_f32 v126, v120, v121
	v_cvt_pk_bf16_f32 v127, v122, v123
	v_cvt_pk_bf16_f32 v116, v116, v117
	v_cvt_pk_bf16_f32 v117, v118, v119
	v_cvt_pk_bf16_f32 v118, v112, v113
	v_cvt_pk_bf16_f32 v119, v114, v115
	global_store_dwordx4 v168, v[124:127], s[14:15]
	global_store_dwordx4 v168, v[116:119], s[14:15] offset:256
	s_waitcnt lgkmcnt(6)
	v_mul_f32_e32 v108, v161, v108
	v_mul_f32_e32 v109, v161, v109
	v_mul_f32_e32 v110, v161, v110
	v_mul_f32_e32 v111, v161, v111
	v_mul_f32_e32 v104, v161, v104
	v_mul_f32_e32 v105, v161, v105
	v_mul_f32_e32 v106, v161, v106
	v_mul_f32_e32 v107, v161, v107
	v_mul_f32_e32 v100, v161, v100
	v_mul_f32_e32 v101, v161, v101
	v_mul_f32_e32 v102, v161, v102
	v_mul_f32_e32 v103, v161, v103
	v_mul_f32_e32 v96, v161, v96
	v_mul_f32_e32 v97, v161, v97
	v_mul_f32_e32 v98, v161, v98
	v_mul_f32_e32 v99, v161, v99
	v_cvt_pk_bf16_f32 v108, v108, v109
	v_cvt_pk_bf16_f32 v109, v110, v111
	v_cvt_pk_bf16_f32 v110, v104, v105
	v_cvt_pk_bf16_f32 v111, v106, v107
	v_cvt_pk_bf16_f32 v100, v100, v101
	v_cvt_pk_bf16_f32 v101, v102, v103
	v_cvt_pk_bf16_f32 v102, v96, v97
	v_cvt_pk_bf16_f32 v103, v98, v99
	v_add_u32_e32 v169, 0x4000, v168
	global_store_dwordx4 v169, v[108:111], s[14:15]
	global_store_dwordx4 v169, v[100:103], s[14:15] offset:256
	s_waitcnt lgkmcnt(5)
	v_mul_f32_e32 v92, v162, v92
	v_mul_f32_e32 v93, v162, v93
	v_mul_f32_e32 v94, v162, v94
	v_mul_f32_e32 v95, v162, v95
	v_mul_f32_e32 v88, v162, v88
	v_mul_f32_e32 v89, v162, v89
	v_mul_f32_e32 v90, v162, v90
	v_mul_f32_e32 v91, v162, v91
	v_mul_f32_e32 v84, v162, v84
	v_mul_f32_e32 v85, v162, v85
	v_mul_f32_e32 v86, v162, v86
	v_mul_f32_e32 v87, v162, v87
	v_mul_f32_e32 v80, v162, v80
	v_mul_f32_e32 v81, v162, v81
	v_mul_f32_e32 v82, v162, v82
	v_mul_f32_e32 v83, v162, v83
	v_cvt_pk_bf16_f32 v92, v92, v93
	v_cvt_pk_bf16_f32 v93, v94, v95
	v_cvt_pk_bf16_f32 v94, v88, v89
	v_cvt_pk_bf16_f32 v95, v90, v91
	v_cvt_pk_bf16_f32 v84, v84, v85
	v_cvt_pk_bf16_f32 v85, v86, v87
	v_cvt_pk_bf16_f32 v86, v80, v81
	v_cvt_pk_bf16_f32 v87, v82, v83
	v_add_u32_e32 v169, 0x8000, v168
	global_store_dwordx4 v169, v[92:95], s[14:15]
	global_store_dwordx4 v169, v[84:87], s[14:15] offset:256
	s_waitcnt lgkmcnt(4)
; __device__ __forceinline__ unsigned cvtpk(float lo, float hi) { f32x2_t v = {lo, hi}; bf16x2_t b = __builtin_convertvector(v, bf16x2_t); return __builtin_bit_cast(unsigned, b); }
;     __device__ __forceinline__ void operator()(const f32x4 (&acc)[2][2][4][2], const Unit& u, int wr, int wc, int fr, int fq) const {
;     ...
; #pragma unroll
;         for (int ai = 0; ai < 2; ++ai)
; #pragma unroll
;             for (int m = 0; m < 4; ++m) {
;                 const int row = row0 + ai * HALF + m * 16; float s = 0.f;
;                 const float rs = ssq_in ? 1.0f / sqrtf(ssq_sum(ssq_in + (size_t)row * 16) * inv_dim + EPS) : 1.0f;
; #pragma unroll
;                 for (int bj = 0; bj < 2; ++bj) {
;                     int col = col0 + bj * HALF; if (hd_in) col = (col / hd_in) * hd_out + (col % hd_in);
;                     const f32x4 v0 = acc[ai][bj][m][0] * rs, v1 = acc[ai][bj][m][1] * rs;
;                     u32x4 w; w.x = cvtpk(v0[0], v0[1]); w.y = cvtpk(v0[2], v0[3]); w.z = cvtpk(v1[0], v1[1]); w.w = cvtpk(v1[2], v1[3]);
;                     *(u32x4*)(O + (size_t)row * ldc + col) = w;
;                     s += (v0[0] * v0[0] + v0[1] * v0[1]) + (v0[2] * v0[2] + v0[3] * v0[3]) + (v1[0] * v1[0] + v1[1] * v1[1]) + (v1[2] * v1[2] + v1[3] * v1[3]);
;                 }
;                 if (so) { s += __shfl_xor(s, 16); s += __shfl_xor(s, 32); if (fq == 0) so[(size_t)row * 16 + (u.pn & 1) * 4 + wc] = s; }
;             }
	v_mul_f32_e32 v76, v163, v76
	v_mul_f32_e32 v77, v163, v77
	v_mul_f32_e32 v78, v163, v78
	v_mul_f32_e32 v79, v163, v79
	v_mul_f32_e32 v72, v163, v72
	v_mul_f32_e32 v73, v163, v73
	v_mul_f32_e32 v74, v163, v74
	v_mul_f32_e32 v75, v163, v75
	v_mul_f32_e32 v68, v163, v68
	v_mul_f32_e32 v69, v163, v69
	v_mul_f32_e32 v70, v163, v70
	v_mul_f32_e32 v71, v163, v71
	v_mul_f32_e32 v64, v163, v64
	v_mul_f32_e32 v65, v163, v65
	v_mul_f32_e32 v66, v163, v66
	v_mul_f32_e32 v67, v163, v67
	v_cvt_pk_bf16_f32 v76, v76, v77
	v_cvt_pk_bf16_f32 v77, v78, v79
	v_cvt_pk_bf16_f32 v78, v72, v73
	v_cvt_pk_bf16_f32 v79, v74, v75
	v_cvt_pk_bf16_f32 v68, v68, v69
	v_cvt_pk_bf16_f32 v69, v70, v71
	v_cvt_pk_bf16_f32 v70, v64, v65
	v_cvt_pk_bf16_f32 v71, v66, v67
	v_add_u32_e32 v169, 0xc000, v168
	global_store_dwordx4 v169, v[76:79], s[14:15]
	global_store_dwordx4 v169, v[68:71], s[14:15] offset:256
	s_waitcnt lgkmcnt(3)
	v_mul_f32_e32 v60, v164, v60
	v_mul_f32_e32 v61, v164, v61
	v_mul_f32_e32 v62, v164, v62
	v_mul_f32_e32 v63, v164, v63
	v_mul_f32_e32 v56, v164, v56
	v_mul_f32_e32 v57, v164, v57
	v_mul_f32_e32 v58, v164, v58
	v_mul_f32_e32 v59, v164, v59
	v_mul_f32_e32 v52, v164, v52
	v_mul_f32_e32 v53, v164, v53
	v_mul_f32_e32 v54, v164, v54
	v_mul_f32_e32 v55, v164, v55
	v_mul_f32_e32 v48, v164, v48
	v_mul_f32_e32 v49, v164, v49
	v_mul_f32_e32 v50, v164, v50
	v_mul_f32_e32 v51, v164, v51
	v_cvt_pk_bf16_f32 v60, v60, v61
	v_cvt_pk_bf16_f32 v61, v62, v63
	v_cvt_pk_bf16_f32 v62, v56, v57
	v_cvt_pk_bf16_f32 v63, v58, v59
	v_cvt_pk_bf16_f32 v52, v52, v53
	v_cvt_pk_bf16_f32 v53, v54, v55
	v_cvt_pk_bf16_f32 v54, v48, v49
	v_cvt_pk_bf16_f32 v55, v50, v51
	v_add_u32_e32 v169, 0x20000, v168
	global_store_dwordx4 v169, v[60:63], s[14:15]
	global_store_dwordx4 v169, v[52:55], s[14:15] offset:256
	s_waitcnt lgkmcnt(2)
	v_mul_f32_e32 v44, v165, v44
	v_mul_f32_e32 v45, v165, v45
	v_mul_f32_e32 v46, v165, v46
	v_mul_f32_e32 v47, v165, v47
	v_mul_f32_e32 v40, v165, v40
	v_mul_f32_e32 v41, v165, v41
	v_mul_f32_e32 v42, v165, v42
	v_mul_f32_e32 v43, v165, v43
	v_mul_f32_e32 v36, v165, v36
	v_mul_f32_e32 v37, v165, v37
	v_mul_f32_e32 v38, v165, v38
	v_mul_f32_e32 v39, v165, v39
	v_mul_f32_e32 v32, v165, v32
	v_mul_f32_e32 v33, v165, v33
	v_mul_f32_e32 v34, v165, v34
	v_mul_f32_e32 v35, v165, v35
	v_cvt_pk_bf16_f32 v44, v44, v45
	v_cvt_pk_bf16_f32 v45, v46, v47
	v_cvt_pk_bf16_f32 v46, v40, v41
	v_cvt_pk_bf16_f32 v47, v42, v43
	v_cvt_pk_bf16_f32 v36, v36, v37
	v_cvt_pk_bf16_f32 v37, v38, v39
	v_cvt_pk_bf16_f32 v38, v32, v33
	v_cvt_pk_bf16_f32 v39, v34, v35
	v_add_u32_e32 v169, 0x24000, v168
	global_store_dwordx4 v169, v[44:47], s[14:15]
	global_store_dwordx4 v169, v[36:39], s[14:15] offset:256
	s_waitcnt lgkmcnt(1)
	v_mul_f32_e32 v28, v166, v28
	v_mul_f32_e32 v29, v166, v29
	v_mul_f32_e32 v30, v166, v30
	v_mul_f32_e32 v31, v166, v31
	v_mul_f32_e32 v24, v166, v24
	v_mul_f32_e32 v25, v166, v25
	v_mul_f32_e32 v26, v166, v26
	v_mul_f32_e32 v27, v166, v27
	v_mul_f32_e32 v20, v166, v20
	v_mul_f32_e32 v21, v166, v21
	v_mul_f32_e32 v22, v166, v22
	v_mul_f32_e32 v23, v166, v23
	v_mul_f32_e32 v16, v166, v16
	v_mul_f32_e32 v17, v166, v17
	v_mul_f32_e32 v18, v166, v18
	v_mul_f32_e32 v19, v166, v19
	v_cvt_pk_bf16_f32 v28, v28, v29
	v_cvt_pk_bf16_f32 v29, v30, v31
	v_cvt_pk_bf16_f32 v30, v24, v25
	v_cvt_pk_bf16_f32 v31, v26, v27
	v_cvt_pk_bf16_f32 v20, v20, v21
	v_cvt_pk_bf16_f32 v21, v22, v23
	v_cvt_pk_bf16_f32 v22, v16, v17
	v_cvt_pk_bf16_f32 v23, v18, v19
	v_add_u32_e32 v169, 0x28000, v168
	global_store_dwordx4 v169, v[28:31], s[14:15]
	global_store_dwordx4 v169, v[20:23], s[14:15] offset:256
	s_waitcnt lgkmcnt(0)
	v_mul_f32_e32 v12, v167, v12
	v_mul_f32_e32 v13, v167, v13
	v_mul_f32_e32 v14, v167, v14
	v_mul_f32_e32 v15, v167, v15
	v_mul_f32_e32 v8, v167, v8
	v_mul_f32_e32 v9, v167, v9
	v_mul_f32_e32 v10, v167, v10
	v_mul_f32_e32 v11, v167, v11
	v_mul_f32_e32 v4, v167, v4
	v_mul_f32_e32 v5, v167, v5
	v_mul_f32_e32 v6, v167, v6
	v_mul_f32_e32 v7, v167, v7
	v_mul_f32_e32 v0, v167, v0
	v_mul_f32_e32 v1, v167, v1
	v_mul_f32_e32 v2, v167, v2
	v_mul_f32_e32 v3, v167, v3
	v_cvt_pk_bf16_f32 v12, v12, v13
	v_cvt_pk_bf16_f32 v13, v14, v15
	v_cvt_pk_bf16_f32 v14, v8, v9
	v_cvt_pk_bf16_f32 v15, v10, v11
	v_cvt_pk_bf16_f32 v4, v4, v5
	v_cvt_pk_bf16_f32 v5, v6, v7
	v_cvt_pk_bf16_f32 v6, v0, v1
	v_cvt_pk_bf16_f32 v7, v2, v3
	v_add_u32_e32 v169, 0x2c000, v168
	global_store_dwordx4 v169, v[12:15], s[14:15]
	global_store_dwordx4 v169, v[4:7], s[14:15] offset:256
	s_andn2_b64 vcc, exec, s[6:7]
	s_mov_b64 s[6:7], -1
	s_cbranch_vccnz .LBB0_803
	s_andn2_b64 vcc, exec, s[12:13]
	s_cbranch_vccnz .LBB0_802
	s_barrier
	s_branch .LBB0_802

; __device__ __forceinline__ unsigned cvtpk(float lo, float hi) { f32x2_t v = {lo, hi}; bf16x2_t b = __builtin_convertvector(v, bf16x2_t); return __builtin_bit_cast(unsigned, b); }
;     __device__ __forceinline__ void operator()(const f32x4 (&acc)[2][2][4][2], const Unit& u, int wr, int wc, int fr, int fq) const {
;         const int row0 = u.pm * BM + wr * 64 + fr, col0 = u.pn * 128 + wc * 32 + 8 * fq;
; #pragma unroll
;         for (int ai = 0; ai < 2; ++ai)
; #pragma unroll
;             for (int m = 0; m < 4; ++m) {
;                 const int row = row0 + ai * HALF + m * 16;
;                 const float rs = 1.0f / sqrtf(ssq_sum(ssq + (size_t)row * 16) * (1.0f / DM) + EPS);
;                 float hv[8];
; #pragma unroll
;                 for (int n = 0; n < 2; ++n)
; #pragma unroll
;                     for (int e = 0; e < 4; ++e) {
;                         const float gg = acc[ai][0][m][n][e] * rs, uu = acc[ai][1][m][n][e] * rs;
;                         const float den = 1.0f + __builtin_amdgcn_exp2f(-gg * LOG2E);
;                         hv[n * 4 + e] = gg * uu * __builtin_amdgcn_rcpf(den);
;                     }
;                 u32x4 w; w.x = cvtpk(hv[0], hv[1]); w.y = cvtpk(hv[2], hv[3]); w.z = cvtpk(hv[4], hv[5]); w.w = cvtpk(hv[6], hv[7]);
;                 *(u32x4*)(H + (size_t)row * DFF + col0) = w;
;             }
.LBB0_1054:
	v_readlane_b32 s9, v254, 7
	v_mbcnt_lo_u32_b32 v144, -1, 0
	v_mbcnt_hi_u32_b32 v144, -1, v144
	v_lshrrev_b32_e32 v145, 1, v144
	v_lshl_add_u32 v145, s9, 5, v145
	v_and_b32_e32 v146, 1, v144
	v_lshl_add_u32 v147, s8, 8, v145
	v_lshlrev_b32_e32 v147, 6, v147
	v_lshl_add_u32 v147, v146, 5, v147
	global_load_dwordx4 v[160:163], v147, s[16:17]
	global_load_dwordx4 v[164:167], v147, s[16:17] offset:16
	v_lshl_add_u32 v148, s8, 8, v152
	v_mov_b64_e32 v[146:147], s[14:15]
	v_mad_i64_i32 v[176:177], s[8:9], v148, s51, v[146:147]
	v_lshl_or_b32 v150, s2, 7, v154
	v_mov_b32_e32 v151, 0
	v_lshlrev_b64 v[150:151], 1, v[150:151]
	v_lshl_add_u64 v[176:177], v[176:177], 0, v[150:151]
	v_lshlrev_b32_e32 v145, 3, v145
	v_add_u32_e32 v145, 0x20100, v145
	v_lshlrev_b32_e32 v146, 3, v152
	v_add_u32_e32 v146, 0x20100, v146
	s_mov_b32 s9, 0
	s_waitcnt vmcnt(0)
	v_add_f32_e32 v160, v160, v162
	v_add_f32_e32 v161, v161, v163
	v_add_f32_e32 v164, v164, v166
	v_add_f32_e32 v165, v165, v167
	v_add_f32_e32 v160, v160, v164
	v_add_f32_e32 v161, v161, v165
	v_add_f32_e32 v160, v160, v161
	s_nop 1
	v_add_f32_dpp v160, v160, v160 quad_perm:[1,0,3,2] row_mask:0xf bank_mask:0xf
	v_fmamk_f32 v160, v160, 0x3a800000, v158
	v_rsq_f32_e32 v161, v160
	s_nop 0
	v_mul_f32_e32 v161, 0xbfb8aa3b, v161
	ds_write_b64 v145, v[160:161]
	s_waitcnt lgkmcnt(0)
	s_barrier
	ds_read_b64 v[160:161], v146 offset:0
	ds_read_b64 v[162:163], v146 offset:128
	ds_read_b64 v[164:165], v146 offset:256
	ds_read_b64 v[166:167], v146 offset:384
	ds_read_b64 v[168:169], v146 offset:1024
	ds_read_b64 v[170:171], v146 offset:1152
	ds_read_b64 v[172:173], v146 offset:1280
	ds_read_b64 v[174:175], v146 offset:1408
	v_mul_f32_e32 v116, v124, v116
	v_mul_f32_e32 v117, v125, v117
	v_mul_f32_e32 v118, v126, v118
	v_mul_f32_e32 v119, v127, v119
	v_mul_f32_e32 v112, v120, v112
	v_mul_f32_e32 v113, v121, v113
	v_mul_f32_e32 v114, v122, v114
	v_mul_f32_e32 v115, v123, v115
	s_waitcnt lgkmcnt(7)
	v_mul_f32_e32 v124, v161, v124
	v_mul_f32_e32 v125, v161, v125
	v_mul_f32_e32 v126, v161, v126
	v_mul_f32_e32 v127, v161, v127
	v_mul_f32_e32 v120, v161, v120
	v_mul_f32_e32 v121, v161, v121
	v_mul_f32_e32 v122, v161, v122
	v_mul_f32_e32 v123, v161, v123
	v_exp_f32_e32 v124, v124
	v_exp_f32_e32 v125, v125
	v_exp_f32_e32 v126, v126
	v_exp_f32_e32 v127, v127
	v_exp_f32_e32 v120, v120
	v_exp_f32_e32 v121, v121
	v_exp_f32_e32 v122, v122
	v_exp_f32_e32 v123, v123
	v_fma_f32 v124, v124, v160, v160
	v_fma_f32 v125, v125, v160, v160
	v_fma_f32 v126, v126, v160, v160
	v_fma_f32 v127, v127, v160, v160
	v_fma_f32 v120, v120, v160, v160
	v_fma_f32 v121, v121, v160, v160
	v_fma_f32 v122, v122, v160, v160
	v_fma_f32 v123, v123, v160, v160
	v_rcp_f32_e32 v124, v124
	v_rcp_f32_e32 v125, v125
	v_rcp_f32_e32 v126, v126
	v_rcp_f32_e32 v127, v127
	v_rcp_f32_e32 v120, v120
	v_rcp_f32_e32 v121, v121
	v_rcp_f32_e32 v122, v122
	v_rcp_f32_e32 v123, v123
	v_mul_f32_e32 v116, v116, v124
	v_mul_f32_e32 v117, v117, v125
	v_mul_f32_e32 v118, v118, v126
	v_mul_f32_e32 v119, v119, v127
	v_mul_f32_e32 v112, v112, v120
	v_mul_f32_e32 v113, v113, v121
	v_mul_f32_e32 v114, v114, v122
	v_mul_f32_e32 v115, v115, v123
	v_cvt_pk_bf16_f32 v124, v116, v117
	v_cvt_pk_bf16_f32 v125, v118, v119
	v_cvt_pk_bf16_f32 v126, v112, v113
	v_cvt_pk_bf16_f32 v127, v114, v115
	global_store_dwordx4 v[176:177], v[124:127], off
	v_mul_f32_e32 v100, v108, v100
	v_mul_f32_e32 v101, v109, v101
	v_mul_f32_e32 v102, v110, v102
	v_mul_f32_e32 v103, v111, v103
	v_mul_f32_e32 v96, v104, v96
	v_mul_f32_e32 v97, v105, v97
	v_mul_f32_e32 v98, v106, v98
	v_mul_f32_e32 v99, v107, v99
	s_waitcnt lgkmcnt(6)
	v_mul_f32_e32 v108, v163, v108
	v_mul_f32_e32 v109, v163, v109
	v_mul_f32_e32 v110, v163, v110
	v_mul_f32_e32 v111, v163, v111
	v_mul_f32_e32 v104, v163, v104
	v_mul_f32_e32 v105, v163, v105
	v_mul_f32_e32 v106, v163, v106
	v_mul_f32_e32 v107, v163, v107
	v_exp_f32_e32 v108, v108
	v_exp_f32_e32 v109, v109
	v_exp_f32_e32 v110, v110
	v_exp_f32_e32 v111, v111
	v_exp_f32_e32 v104, v104
	v_exp_f32_e32 v105, v105
	v_exp_f32_e32 v106, v106
	v_exp_f32_e32 v107, v107
	v_fma_f32 v108, v108, v162, v162
	v_fma_f32 v109, v109, v162, v162
	v_fma_f32 v110, v110, v162, v162
	v_fma_f32 v111, v111, v162, v162
	v_fma_f32 v104, v104, v162, v162
	v_fma_f32 v105, v105, v162, v162
	v_fma_f32 v106, v106, v162, v162
	v_fma_f32 v107, v107, v162, v162
	v_rcp_f32_e32 v108, v108
	v_rcp_f32_e32 v109, v109
	v_rcp_f32_e32 v110, v110
	v_rcp_f32_e32 v111, v111
	v_rcp_f32_e32 v104, v104
	v_rcp_f32_e32 v105, v105
	v_rcp_f32_e32 v106, v106
	v_rcp_f32_e32 v107, v107
	s_mov_b32 s8, 0x16000
	v_mul_f32_e32 v100, v100, v108
	v_mul_f32_e32 v101, v101, v109
	v_mul_f32_e32 v102, v102, v110
	v_mul_f32_e32 v103, v103, v111
	v_mul_f32_e32 v96, v96, v104
	v_mul_f32_e32 v97, v97, v105
	v_mul_f32_e32 v98, v98, v106
	v_mul_f32_e32 v99, v99, v107
	v_cvt_pk_bf16_f32 v108, v100, v101
	v_cvt_pk_bf16_f32 v109, v102, v103
	v_cvt_pk_bf16_f32 v110, v96, v97
	v_cvt_pk_bf16_f32 v111, v98, v99
	v_lshl_add_u64 v[178:179], v[176:177], 0, s[8:9]
	global_store_dwordx4 v[178:179], v[108:111], off
	v_mul_f32_e32 v84, v92, v84
	v_mul_f32_e32 v85, v93, v85
	v_mul_f32_e32 v86, v94, v86
	v_mul_f32_e32 v87, v95, v87
	v_mul_f32_e32 v80, v88, v80
	v_mul_f32_e32 v81, v89, v81
	v_mul_f32_e32 v82, v90, v82
	v_mul_f32_e32 v83, v91, v83
	s_waitcnt lgkmcnt(5)
; __device__ __forceinline__ unsigned cvtpk(float lo, float hi) { f32x2_t v = {lo, hi}; bf16x2_t b = __builtin_convertvector(v, bf16x2_t); return __builtin_bit_cast(unsigned, b); }
;     __device__ __forceinline__ void operator()(const f32x4 (&acc)[2][2][4][2], const Unit& u, int wr, int wc, int fr, int fq) const {
;     ...
;             for (int m = 0; m < 4; ++m) {
;                 const int row = row0 + ai * HALF + m * 16;
;                 const float rs = 1.0f / sqrtf(ssq_sum(ssq + (size_t)row * 16) * (1.0f / DM) + EPS);
;                 float hv[8];
; #pragma unroll
;                 for (int n = 0; n < 2; ++n)
; #pragma unroll
;                     for (int e = 0; e < 4; ++e) {
;                         const float gg = acc[ai][0][m][n][e] * rs, uu = acc[ai][1][m][n][e] * rs;
;                         const float den = 1.0f + __builtin_amdgcn_exp2f(-gg * LOG2E);
;                         hv[n * 4 + e] = gg * uu * __builtin_amdgcn_rcpf(den);
;                     }
;                 u32x4 w; w.x = cvtpk(hv[0], hv[1]); w.y = cvtpk(hv[2], hv[3]); w.z = cvtpk(hv[4], hv[5]); w.w = cvtpk(hv[6], hv[7]);
;                 *(u32x4*)(H + (size_t)row * DFF + col0) = w;
	v_mul_f32_e32 v92, v165, v92
	v_mul_f32_e32 v93, v165, v93
	v_mul_f32_e32 v94, v165, v94
	v_mul_f32_e32 v95, v165, v95
	v_mul_f32_e32 v88, v165, v88
	v_mul_f32_e32 v89, v165, v89
	v_mul_f32_e32 v90, v165, v90
	v_mul_f32_e32 v91, v165, v91
	v_exp_f32_e32 v92, v92
	v_exp_f32_e32 v93, v93
	v_exp_f32_e32 v94, v94
	v_exp_f32_e32 v95, v95
	v_exp_f32_e32 v88, v88
	v_exp_f32_e32 v89, v89
	v_exp_f32_e32 v90, v90
	v_exp_f32_e32 v91, v91
	v_fma_f32 v92, v92, v164, v164
	v_fma_f32 v93, v93, v164, v164
	v_fma_f32 v94, v94, v164, v164
	v_fma_f32 v95, v95, v164, v164
	v_fma_f32 v88, v88, v164, v164
	v_fma_f32 v89, v89, v164, v164
	v_fma_f32 v90, v90, v164, v164
	v_fma_f32 v91, v91, v164, v164
	v_rcp_f32_e32 v92, v92
	v_rcp_f32_e32 v93, v93
	v_rcp_f32_e32 v94, v94
	v_rcp_f32_e32 v95, v95
	v_rcp_f32_e32 v88, v88
	v_rcp_f32_e32 v89, v89
	v_rcp_f32_e32 v90, v90
	v_rcp_f32_e32 v91, v91
	s_mov_b32 s8, 0x2c000
	v_mul_f32_e32 v84, v84, v92
	v_mul_f32_e32 v85, v85, v93
	v_mul_f32_e32 v86, v86, v94
	v_mul_f32_e32 v87, v87, v95
	v_mul_f32_e32 v80, v80, v88
	v_mul_f32_e32 v81, v81, v89
	v_mul_f32_e32 v82, v82, v90
	v_mul_f32_e32 v83, v83, v91
	v_cvt_pk_bf16_f32 v92, v84, v85
	v_cvt_pk_bf16_f32 v93, v86, v87
	v_cvt_pk_bf16_f32 v94, v80, v81
	v_cvt_pk_bf16_f32 v95, v82, v83
	v_lshl_add_u64 v[178:179], v[176:177], 0, s[8:9]
	global_store_dwordx4 v[178:179], v[92:95], off
	v_mul_f32_e32 v68, v76, v68
	v_mul_f32_e32 v69, v77, v69
	v_mul_f32_e32 v70, v78, v70
	v_mul_f32_e32 v71, v79, v71
	v_mul_f32_e32 v64, v72, v64
	v_mul_f32_e32 v65, v73, v65
	v_mul_f32_e32 v66, v74, v66
	v_mul_f32_e32 v67, v75, v67
	s_waitcnt lgkmcnt(4)
	v_mul_f32_e32 v76, v167, v76
	v_mul_f32_e32 v77, v167, v77
	v_mul_f32_e32 v78, v167, v78
	v_mul_f32_e32 v79, v167, v79
	v_mul_f32_e32 v72, v167, v72
	v_mul_f32_e32 v73, v167, v73
	v_mul_f32_e32 v74, v167, v74
	v_mul_f32_e32 v75, v167, v75
	v_exp_f32_e32 v76, v76
	v_exp_f32_e32 v77, v77
	v_exp_f32_e32 v78, v78
	v_exp_f32_e32 v79, v79
	v_exp_f32_e32 v72, v72
	v_exp_f32_e32 v73, v73
	v_exp_f32_e32 v74, v74
	v_exp_f32_e32 v75, v75
	v_fma_f32 v76, v76, v166, v166
	v_fma_f32 v77, v77, v166, v166
	v_fma_f32 v78, v78, v166, v166
	v_fma_f32 v79, v79, v166, v166
	v_fma_f32 v72, v72, v166, v166
	v_fma_f32 v73, v73, v166, v166
	v_fma_f32 v74, v74, v166, v166
	v_fma_f32 v75, v75, v166, v166
	v_rcp_f32_e32 v76, v76
	v_rcp_f32_e32 v77, v77
	v_rcp_f32_e32 v78, v78
	v_rcp_f32_e32 v79, v79
	v_rcp_f32_e32 v72, v72
	v_rcp_f32_e32 v73, v73
	v_rcp_f32_e32 v74, v74
	v_rcp_f32_e32 v75, v75
	s_mov_b32 s8, 0x42000
	v_mul_f32_e32 v68, v68, v76
	v_mul_f32_e32 v69, v69, v77
	v_mul_f32_e32 v70, v70, v78
	v_mul_f32_e32 v71, v71, v79
	v_mul_f32_e32 v64, v64, v72
	v_mul_f32_e32 v65, v65, v73
	v_mul_f32_e32 v66, v66, v74
	v_mul_f32_e32 v67, v67, v75
	v_cvt_pk_bf16_f32 v76, v68, v69
	v_cvt_pk_bf16_f32 v77, v70, v71
	v_cvt_pk_bf16_f32 v78, v64, v65
	v_cvt_pk_bf16_f32 v79, v66, v67
	v_lshl_add_u64 v[178:179], v[176:177], 0, s[8:9]
	global_store_dwordx4 v[178:179], v[76:79], off
	v_mul_f32_e32 v52, v60, v52
	v_mul_f32_e32 v53, v61, v53
	v_mul_f32_e32 v54, v62, v54
	v_mul_f32_e32 v55, v63, v55
	v_mul_f32_e32 v48, v56, v48
	v_mul_f32_e32 v49, v57, v49
	v_mul_f32_e32 v50, v58, v50
	v_mul_f32_e32 v51, v59, v51
	s_waitcnt lgkmcnt(3)
	v_mul_f32_e32 v60, v169, v60
	v_mul_f32_e32 v61, v169, v61
	v_mul_f32_e32 v62, v169, v62
	v_mul_f32_e32 v63, v169, v63
	v_mul_f32_e32 v56, v169, v56
	v_mul_f32_e32 v57, v169, v57
	v_mul_f32_e32 v58, v169, v58
	v_mul_f32_e32 v59, v169, v59
	v_exp_f32_e32 v60, v60
	v_exp_f32_e32 v61, v61
	v_exp_f32_e32 v62, v62
	v_exp_f32_e32 v63, v63
	v_exp_f32_e32 v56, v56
	v_exp_f32_e32 v57, v57
	v_exp_f32_e32 v58, v58
	v_exp_f32_e32 v59, v59
	v_fma_f32 v60, v60, v168, v168
	v_fma_f32 v61, v61, v168, v168
	v_fma_f32 v62, v62, v168, v168
	v_fma_f32 v63, v63, v168, v168
	v_fma_f32 v56, v56, v168, v168
	v_fma_f32 v57, v57, v168, v168
	v_fma_f32 v58, v58, v168, v168
	v_fma_f32 v59, v59, v168, v168
	v_rcp_f32_e32 v60, v60
	v_rcp_f32_e32 v61, v61
	v_rcp_f32_e32 v62, v62
	v_rcp_f32_e32 v63, v63
	v_rcp_f32_e32 v56, v56
	v_rcp_f32_e32 v57, v57
	v_rcp_f32_e32 v58, v58
	v_rcp_f32_e32 v59, v59
	s_mov_b32 s8, 0xb0000
	v_mul_f32_e32 v52, v52, v60
	v_mul_f32_e32 v53, v53, v61
	v_mul_f32_e32 v54, v54, v62
	v_mul_f32_e32 v55, v55, v63
	v_mul_f32_e32 v48, v48, v56
	v_mul_f32_e32 v49, v49, v57
	v_mul_f32_e32 v50, v50, v58
	v_mul_f32_e32 v51, v51, v59
	v_cvt_pk_bf16_f32 v60, v52, v53
	v_cvt_pk_bf16_f32 v61, v54, v55
	v_cvt_pk_bf16_f32 v62, v48, v49
	v_cvt_pk_bf16_f32 v63, v50, v51
	v_lshl_add_u64 v[178:179], v[176:177], 0, s[8:9]
	global_store_dwordx4 v[178:179], v[60:63], off
	v_mul_f32_e32 v36, v44, v36
	v_mul_f32_e32 v37, v45, v37
	v_mul_f32_e32 v38, v46, v38
	v_mul_f32_e32 v39, v47, v39
	v_mul_f32_e32 v32, v40, v32
	v_mul_f32_e32 v33, v41, v33
	v_mul_f32_e32 v34, v42, v34
	v_mul_f32_e32 v35, v43, v35
	s_waitcnt lgkmcnt(2)
; __device__ __forceinline__ unsigned cvtpk(float lo, float hi) { f32x2_t v = {lo, hi}; bf16x2_t b = __builtin_convertvector(v, bf16x2_t); return __builtin_bit_cast(unsigned, b); }
;     __device__ __forceinline__ void operator()(const f32x4 (&acc)[2][2][4][2], const Unit& u, int wr, int wc, int fr, int fq) const {
;     ...
;             for (int m = 0; m < 4; ++m) {
;                 const int row = row0 + ai * HALF + m * 16;
;                 const float rs = 1.0f / sqrtf(ssq_sum(ssq + (size_t)row * 16) * (1.0f / DM) + EPS);
;                 float hv[8];
; #pragma unroll
;                 for (int n = 0; n < 2; ++n)
; #pragma unroll
;                     for (int e = 0; e < 4; ++e) {
;                         const float gg = acc[ai][0][m][n][e] * rs, uu = acc[ai][1][m][n][e] * rs;
;                         const float den = 1.0f + __builtin_amdgcn_exp2f(-gg * LOG2E);
;                         hv[n * 4 + e] = gg * uu * __builtin_amdgcn_rcpf(den);
;                     }
;                 u32x4 w; w.x = cvtpk(hv[0], hv[1]); w.y = cvtpk(hv[2], hv[3]); w.z = cvtpk(hv[4], hv[5]); w.w = cvtpk(hv[6], hv[7]);
;                 *(u32x4*)(H + (size_t)row * DFF + col0) = w;
;             }
	v_mul_f32_e32 v44, v171, v44
	v_mul_f32_e32 v45, v171, v45
	v_mul_f32_e32 v46, v171, v46
	v_mul_f32_e32 v47, v171, v47
	v_mul_f32_e32 v40, v171, v40
	v_mul_f32_e32 v41, v171, v41
	v_mul_f32_e32 v42, v171, v42
	v_mul_f32_e32 v43, v171, v43
	v_exp_f32_e32 v44, v44
	v_exp_f32_e32 v45, v45
	v_exp_f32_e32 v46, v46
	v_exp_f32_e32 v47, v47
	v_exp_f32_e32 v40, v40
	v_exp_f32_e32 v41, v41
	v_exp_f32_e32 v42, v42
	v_exp_f32_e32 v43, v43
	v_fma_f32 v44, v44, v170, v170
	v_fma_f32 v45, v45, v170, v170
	v_fma_f32 v46, v46, v170, v170
	v_fma_f32 v47, v47, v170, v170
	v_fma_f32 v40, v40, v170, v170
	v_fma_f32 v41, v41, v170, v170
	v_fma_f32 v42, v42, v170, v170
	v_fma_f32 v43, v43, v170, v170
	v_rcp_f32_e32 v44, v44
	v_rcp_f32_e32 v45, v45
	v_rcp_f32_e32 v46, v46
	v_rcp_f32_e32 v47, v47
	v_rcp_f32_e32 v40, v40
	v_rcp_f32_e32 v41, v41
	v_rcp_f32_e32 v42, v42
	v_rcp_f32_e32 v43, v43
	s_mov_b32 s8, 0xc6000
	v_mul_f32_e32 v36, v36, v44
	v_mul_f32_e32 v37, v37, v45
	v_mul_f32_e32 v38, v38, v46
	v_mul_f32_e32 v39, v39, v47
	v_mul_f32_e32 v32, v32, v40
	v_mul_f32_e32 v33, v33, v41
	v_mul_f32_e32 v34, v34, v42
	v_mul_f32_e32 v35, v35, v43
	v_cvt_pk_bf16_f32 v44, v36, v37
	v_cvt_pk_bf16_f32 v45, v38, v39
	v_cvt_pk_bf16_f32 v46, v32, v33
	v_cvt_pk_bf16_f32 v47, v34, v35
	v_lshl_add_u64 v[178:179], v[176:177], 0, s[8:9]
	global_store_dwordx4 v[178:179], v[44:47], off
	v_mul_f32_e32 v20, v28, v20
	v_mul_f32_e32 v21, v29, v21
	v_mul_f32_e32 v22, v30, v22
	v_mul_f32_e32 v23, v31, v23
	v_mul_f32_e32 v16, v24, v16
	v_mul_f32_e32 v17, v25, v17
	v_mul_f32_e32 v18, v26, v18
	v_mul_f32_e32 v19, v27, v19
	s_waitcnt lgkmcnt(1)
	v_mul_f32_e32 v28, v173, v28
	v_mul_f32_e32 v29, v173, v29
	v_mul_f32_e32 v30, v173, v30
	v_mul_f32_e32 v31, v173, v31
	v_mul_f32_e32 v24, v173, v24
	v_mul_f32_e32 v25, v173, v25
	v_mul_f32_e32 v26, v173, v26
	v_mul_f32_e32 v27, v173, v27
	v_exp_f32_e32 v28, v28
	v_exp_f32_e32 v29, v29
	v_exp_f32_e32 v30, v30
	v_exp_f32_e32 v31, v31
	v_exp_f32_e32 v24, v24
	v_exp_f32_e32 v25, v25
	v_exp_f32_e32 v26, v26
	v_exp_f32_e32 v27, v27
	v_fma_f32 v28, v28, v172, v172
	v_fma_f32 v29, v29, v172, v172
	v_fma_f32 v30, v30, v172, v172
	v_fma_f32 v31, v31, v172, v172
	v_fma_f32 v24, v24, v172, v172
	v_fma_f32 v25, v25, v172, v172
	v_fma_f32 v26, v26, v172, v172
	v_fma_f32 v27, v27, v172, v172
	v_rcp_f32_e32 v28, v28
	v_rcp_f32_e32 v29, v29
	v_rcp_f32_e32 v30, v30
	v_rcp_f32_e32 v31, v31
	v_rcp_f32_e32 v24, v24
	v_rcp_f32_e32 v25, v25
	v_rcp_f32_e32 v26, v26
	v_rcp_f32_e32 v27, v27
	s_mov_b32 s8, 0xdc000
	v_mul_f32_e32 v20, v20, v28
	v_mul_f32_e32 v21, v21, v29
	v_mul_f32_e32 v22, v22, v30
	v_mul_f32_e32 v23, v23, v31
	v_mul_f32_e32 v16, v16, v24
	v_mul_f32_e32 v17, v17, v25
	v_mul_f32_e32 v18, v18, v26
	v_mul_f32_e32 v19, v19, v27
	v_cvt_pk_bf16_f32 v28, v20, v21
	v_cvt_pk_bf16_f32 v29, v22, v23
	v_cvt_pk_bf16_f32 v30, v16, v17
	v_cvt_pk_bf16_f32 v31, v18, v19
	v_lshl_add_u64 v[178:179], v[176:177], 0, s[8:9]
	global_store_dwordx4 v[178:179], v[28:31], off
	v_mul_f32_e32 v4, v12, v4
	v_mul_f32_e32 v5, v13, v5
	v_mul_f32_e32 v6, v14, v6
	v_mul_f32_e32 v7, v15, v7
	v_mul_f32_e32 v0, v8, v0
	v_mul_f32_e32 v1, v9, v1
	v_mul_f32_e32 v2, v10, v2
	v_mul_f32_e32 v3, v11, v3
	s_waitcnt lgkmcnt(0)
	v_mul_f32_e32 v12, v175, v12
	v_mul_f32_e32 v13, v175, v13
	v_mul_f32_e32 v14, v175, v14
	v_mul_f32_e32 v15, v175, v15
	v_mul_f32_e32 v8, v175, v8
	v_mul_f32_e32 v9, v175, v9
	v_mul_f32_e32 v10, v175, v10
	v_mul_f32_e32 v11, v175, v11
	v_exp_f32_e32 v12, v12
	v_exp_f32_e32 v13, v13
	v_exp_f32_e32 v14, v14
	v_exp_f32_e32 v15, v15
	v_exp_f32_e32 v8, v8
	v_exp_f32_e32 v9, v9
	v_exp_f32_e32 v10, v10
	v_exp_f32_e32 v11, v11
	v_fma_f32 v12, v12, v174, v174
	v_fma_f32 v13, v13, v174, v174
	v_fma_f32 v14, v14, v174, v174
	v_fma_f32 v15, v15, v174, v174
	v_fma_f32 v8, v8, v174, v174
	v_fma_f32 v9, v9, v174, v174
	v_fma_f32 v10, v10, v174, v174
	v_fma_f32 v11, v11, v174, v174
	v_rcp_f32_e32 v12, v12
	v_rcp_f32_e32 v13, v13
	v_rcp_f32_e32 v14, v14
	v_rcp_f32_e32 v15, v15
	v_rcp_f32_e32 v8, v8
	v_rcp_f32_e32 v9, v9
	v_rcp_f32_e32 v10, v10
	v_rcp_f32_e32 v11, v11
	s_mov_b32 s8, 0xf2000
	v_mul_f32_e32 v4, v4, v12
	v_mul_f32_e32 v5, v5, v13
	v_mul_f32_e32 v6, v6, v14
	v_mul_f32_e32 v7, v7, v15
	v_mul_f32_e32 v0, v0, v8
	v_mul_f32_e32 v1, v1, v9
	v_mul_f32_e32 v2, v2, v10
	v_mul_f32_e32 v3, v3, v11
	v_cvt_pk_bf16_f32 v12, v4, v5
	v_cvt_pk_bf16_f32 v13, v6, v7
	v_cvt_pk_bf16_f32 v14, v0, v1
	v_cvt_pk_bf16_f32 v15, v2, v3
	v_lshl_add_u64 v[178:179], v[176:177], 0, s[8:9]
	global_store_dwordx4 v[178:179], v[12:15], off
	s_andn2_b64 vcc, exec, s[6:7]
	s_mov_b64 s[6:7], -1
	s_cbranch_vccnz .LBB0_1047
	s_andn2_b64 vcc, exec, s[12:13]
	s_cbranch_vccnz .LBB0_1046
	s_barrier
	s_branch .LBB0_1046

; __device__ __forceinline__ unsigned cvtpk(float lo, float hi) { f32x2_t v = {lo, hi}; bf16x2_t b = __builtin_convertvector(v, bf16x2_t); return __builtin_bit_cast(unsigned, b); }
; __device__ __forceinline__ float bflo(unsigned w) { return __uint_as_float(w << 16); }
; __device__ __forceinline__ float bfhi(unsigned w) { return __uint_as_float(w & 0xffff0000u); }
;     __device__ __forceinline__ void operator()(const f32x4 (&acc)[2][2][4][2], const Unit& u, int wr, int wc, int fr, int fq) const {
;         const int row0 = u.pm * BM + wr * 64 + fr, col0 = u.pn * BM + wc * 32 + 8 * fq;
;         u32x4 xv[RM == 0 ? 1 : 2][RM == 0 ? 1 : 4][RM == 0 ? 1 : 2];
;         if (RM != 0) {
; #pragma unroll
;             for (int ai = 0; ai < 2; ++ai)
; #pragma unroll
;                 for (int m = 0; m < 4; ++m)
; #pragma unroll
;                     for (int bj = 0; bj < 2; ++bj) xv[RM == 0 ? 0 : ai][RM == 0 ? 0 : m][RM == 0 ? 0 : bj] = *(const u32x4*)(xb + (size_t)(row0 + ai * HALF + m * 16) * DM + col0 + bj * HALF);
;         }
; #pragma unroll
;         for (int ai = 0; ai < 2; ++ai)
; #pragma unroll
;             for (int m = 0; m < 4; ++m) {
;                 const int row = row0 + ai * HALF + m * 16; float s = 0.f;
; #pragma unroll
;                 for (int bj = 0; bj < 2; ++bj) {
;                     const size_t off = (size_t)row * DM + col0 + bj * HALF;
;                     f32x4 v0, v1;
;                     if (RM == 0) { v0 = *(const f32x4*)(xf + off); v1 = *(const f32x4*)(xf + off + 4); }
;                     else { const u32x4 w = xv[RM == 0 ? 0 : ai][RM == 0 ? 0 : m][RM == 0 ? 0 : bj]; v0 = (f32x4){bflo(w.x), bfhi(w.x), bflo(w.y), bfhi(w.y)}; v1 = (f32x4){bflo(w.z), bfhi(w.z), bflo(w.w), bfhi(w.w)}; }
;                     v0 = v0 + acc[ai][bj][m][0] * alpha; v1 = v1 + acc[ai][bj][m][1] * alpha;
;                     if (RM == 2) { *(f32x4*)(outf + off) = v0; *(f32x4*)(outf + off + 4) = v1; }
;                     else {
;                         u32x4 w; w.x = cvtpk(v0[0], v0[1]); w.y = cvtpk(v0[2], v0[3]); w.z = cvtpk(v1[0], v1[1]); w.w = cvtpk(v1[2], v1[3]);
;                         *(u32x4*)(xb + off) = w;
;                         s += (v0[0] * v0[0] + v0[1] * v0[1]) + (v0[2] * v0[2] + v0[3] * v0[3]) + (v1[0] * v1[0] + v1[1] * v1[1]) + (v1[2] * v1[2] + v1[3] * v1[3]);
;                     }
;                 }
.LBB0_1141:
	v_lshl_or_b32 v232, s14, 8, v242
	v_lshl_add_u32 v233, s51, 8, v240
	v_lshlrev_b32_e32 v204, 11, v233
	v_lshl_add_u32 v204, v232, 1, v204
	v_add_u32_e32 v205, 0x8000, v204
	v_add_u32_e32 v206, 0x10000, v204
	v_add_u32_e32 v207, 0x18000, v204
	v_add_u32_e32 v208, 0x40000, v204
	v_add_u32_e32 v209, 0x48000, v204
	v_add_u32_e32 v210, 0x50000, v204
	v_add_u32_e32 v211, 0x58000, v204
	global_load_dwordx4 v[152:155], v204, s[18:19]
	global_load_dwordx4 v[156:159], v204, s[18:19] offset:256
	global_load_dwordx4 v[160:163], v205, s[18:19]
	global_load_dwordx4 v[164:167], v205, s[18:19] offset:256
	global_load_dwordx4 v[168:171], v206, s[18:19]
	global_load_dwordx4 v[172:175], v206, s[18:19] offset:256
	global_load_dwordx4 v[176:179], v207, s[18:19]
	global_load_dwordx4 v[180:183], v207, s[18:19] offset:256
	global_load_dwordx4 v[184:187], v208, s[18:19]
	global_load_dwordx4 v[188:191], v208, s[18:19] offset:256
	global_load_dwordx4 v[120:123], v209, s[18:19]
	global_load_dwordx4 v[124:127], v209, s[18:19] offset:256
	global_load_dwordx4 v[128:131], v210, s[18:19]
	global_load_dwordx4 v[132:135], v210, s[18:19] offset:256
	global_load_dwordx4 v[136:139], v211, s[18:19]
	global_load_dwordx4 v[140:143], v211, s[18:19] offset:256
	v_mbcnt_lo_u32_b32 v234, -1, 0
	v_mbcnt_hi_u32_b32 v234, -1, v234
	v_lshrrev_b32_e32 v235, 4, v234
	v_and_b32_e32 v236, 1, v235
	v_lshlrev_b32_e32 v236, 5, v236
	v_lshrrev_b32_e32 v235, 1, v235
	v_lshl_add_u32 v236, v235, 4, v236
	v_add_u32_e32 v236, v233, v236
	v_lshlrev_b32_e32 v236, 6, v236
	s_lshl_b32 s30, s14, 4
	s_lshl_b32 s31, s40, 2
	s_add_u32 s30, s30, s31
	v_add_u32_e32 v236, s30, v236
	v_add_u32_e32 v237, 0x2000, v236
	s_waitcnt vmcnt(14)
	v_lshlrev_b32_e32 v222, 16, v152
	v_and_b32_e32 v223, 0xffff0000, v152
	v_lshlrev_b32_e32 v224, 16, v153
	v_and_b32_e32 v225, 0xffff0000, v153
	v_lshlrev_b32_e32 v226, 16, v154
	v_and_b32_e32 v227, 0xffff0000, v154
	v_lshlrev_b32_e32 v228, 16, v155
	v_and_b32_e32 v229, 0xffff0000, v155
	v_fma_f32 v148, v148, 0.5, v222
	v_fma_f32 v149, v149, 0.5, v223
	v_fma_f32 v150, v150, 0.5, v224
	v_fma_f32 v151, v151, 0.5, v225
	v_fma_f32 v144, v144, 0.5, v226
	v_fma_f32 v145, v145, 0.5, v227
	v_fma_f32 v146, v146, 0.5, v228
	v_fma_f32 v147, v147, 0.5, v229
	v_cvt_pk_bf16_f32 v152, v148, v149
	v_cvt_pk_bf16_f32 v153, v150, v151
	v_cvt_pk_bf16_f32 v154, v144, v145
	v_cvt_pk_bf16_f32 v155, v146, v147
	global_store_dwordx4 v204, v[152:155], s[18:19]
	v_mul_f32_e32 v220, v148, v148
	v_mul_f32_e32 v221, v149, v149
	v_fmac_f32_e32 v220, v150, v150
	v_fmac_f32_e32 v221, v151, v151
	v_fmac_f32_e32 v220, v144, v144
	v_fmac_f32_e32 v221, v145, v145
	v_fmac_f32_e32 v220, v146, v146
	v_fmac_f32_e32 v221, v147, v147
	v_lshlrev_b32_e32 v222, 16, v156
	v_and_b32_e32 v223, 0xffff0000, v156
	v_lshlrev_b32_e32 v224, 16, v157
	v_and_b32_e32 v225, 0xffff0000, v157
	v_lshlrev_b32_e32 v226, 16, v158
	v_and_b32_e32 v227, 0xffff0000, v158
	v_lshlrev_b32_e32 v228, 16, v159
	v_and_b32_e32 v229, 0xffff0000, v159
	v_fma_f32 v116, v116, 0.5, v222
	v_fma_f32 v117, v117, 0.5, v223
	v_fma_f32 v118, v118, 0.5, v224
	v_fma_f32 v119, v119, 0.5, v225
	v_fma_f32 v112, v112, 0.5, v226
	v_fma_f32 v113, v113, 0.5, v227
	v_fma_f32 v114, v114, 0.5, v228
	v_fma_f32 v115, v115, 0.5, v229
	v_cvt_pk_bf16_f32 v156, v116, v117
	v_cvt_pk_bf16_f32 v157, v118, v119
	v_cvt_pk_bf16_f32 v158, v112, v113
	v_cvt_pk_bf16_f32 v159, v114, v115
	global_store_dwordx4 v204, v[156:159], s[18:19] offset:256
	v_mul_f32_e32 v230, v116, v116
	v_mul_f32_e32 v231, v117, v117
	v_fmac_f32_e32 v230, v118, v118
	v_fmac_f32_e32 v231, v119, v119
	v_fmac_f32_e32 v230, v112, v112
	v_fmac_f32_e32 v231, v113, v113
	v_fmac_f32_e32 v230, v114, v114
	v_fmac_f32_e32 v231, v115, v115
	v_add_f32_e32 v220, v220, v230
	v_add_f32_e32 v221, v221, v231
	v_add_f32_e32 v212, v220, v221
	s_waitcnt vmcnt(14)
	v_lshlrev_b32_e32 v222, 16, v160
	v_and_b32_e32 v223, 0xffff0000, v160
	v_lshlrev_b32_e32 v224, 16, v161
	v_and_b32_e32 v225, 0xffff0000, v161
	v_lshlrev_b32_e32 v226, 16, v162
	v_and_b32_e32 v227, 0xffff0000, v162
	v_lshlrev_b32_e32 v228, 16, v163
	v_and_b32_e32 v229, 0xffff0000, v163
	v_fma_f32 v108, v108, 0.5, v222
	v_fma_f32 v109, v109, 0.5, v223
	v_fma_f32 v110, v110, 0.5, v224
	v_fma_f32 v111, v111, 0.5, v225
	v_fma_f32 v104, v104, 0.5, v226
	v_fma_f32 v105, v105, 0.5, v227
	v_fma_f32 v106, v106, 0.5, v228
	v_fma_f32 v107, v107, 0.5, v229
	v_cvt_pk_bf16_f32 v160, v108, v109
	v_cvt_pk_bf16_f32 v161, v110, v111
	v_cvt_pk_bf16_f32 v162, v104, v105
	v_cvt_pk_bf16_f32 v163, v106, v107
	global_store_dwordx4 v205, v[160:163], s[18:19]
	v_mul_f32_e32 v220, v108, v108
	v_mul_f32_e32 v221, v109, v109
	v_fmac_f32_e32 v220, v110, v110
	v_fmac_f32_e32 v221, v111, v111
	v_fmac_f32_e32 v220, v104, v104
	v_fmac_f32_e32 v221, v105, v105
	v_fmac_f32_e32 v220, v106, v106
	v_fmac_f32_e32 v221, v107, v107
	v_lshlrev_b32_e32 v222, 16, v164
	v_and_b32_e32 v223, 0xffff0000, v164
	v_lshlrev_b32_e32 v224, 16, v165
	v_and_b32_e32 v225, 0xffff0000, v165
	v_lshlrev_b32_e32 v226, 16, v166
	v_and_b32_e32 v227, 0xffff0000, v166
	v_lshlrev_b32_e32 v228, 16, v167
	v_and_b32_e32 v229, 0xffff0000, v167
	v_fma_f32 v100, v100, 0.5, v222
	v_fma_f32 v101, v101, 0.5, v223
	v_fma_f32 v102, v102, 0.5, v224
	v_fma_f32 v103, v103, 0.5, v225
	v_fma_f32 v96, v96, 0.5, v226
	v_fma_f32 v97, v97, 0.5, v227
	v_fma_f32 v98, v98, 0.5, v228
	v_fma_f32 v99, v99, 0.5, v229
	v_cvt_pk_bf16_f32 v164, v100, v101
	v_cvt_pk_bf16_f32 v165, v102, v103
	v_cvt_pk_bf16_f32 v166, v96, v97
	v_cvt_pk_bf16_f32 v167, v98, v99
	global_store_dwordx4 v205, v[164:167], s[18:19] offset:256
	v_mul_f32_e32 v230, v100, v100
	v_mul_f32_e32 v231, v101, v101
	v_fmac_f32_e32 v230, v102, v102
	v_fmac_f32_e32 v231, v103, v103
	v_fmac_f32_e32 v230, v96, v96
	v_fmac_f32_e32 v231, v97, v97
	v_fmac_f32_e32 v230, v98, v98
	v_fmac_f32_e32 v231, v99, v99
	v_add_f32_e32 v220, v220, v230
	v_add_f32_e32 v221, v221, v231
	v_add_f32_e32 v213, v220, v221
	s_waitcnt vmcnt(14)
; __device__ __forceinline__ unsigned cvtpk(float lo, float hi) { f32x2_t v = {lo, hi}; bf16x2_t b = __builtin_convertvector(v, bf16x2_t); return __builtin_bit_cast(unsigned, b); }
; __device__ __forceinline__ float bflo(unsigned w) { return __uint_as_float(w << 16); }
; __device__ __forceinline__ float bfhi(unsigned w) { return __uint_as_float(w & 0xffff0000u); }
;     __device__ __forceinline__ void operator()(const f32x4 (&acc)[2][2][4][2], const Unit& u, int wr, int wc, int fr, int fq) const {
;     ...
;         for (int ai = 0; ai < 2; ++ai)
; #pragma unroll
;             for (int m = 0; m < 4; ++m) {
;                 const int row = row0 + ai * HALF + m * 16; float s = 0.f;
; #pragma unroll
;                 for (int bj = 0; bj < 2; ++bj) {
;                     const size_t off = (size_t)row * DM + col0 + bj * HALF;
;                     f32x4 v0, v1;
;                     if (RM == 0) { v0 = *(const f32x4*)(xf + off); v1 = *(const f32x4*)(xf + off + 4); }
;                     else { const u32x4 w = xv[RM == 0 ? 0 : ai][RM == 0 ? 0 : m][RM == 0 ? 0 : bj]; v0 = (f32x4){bflo(w.x), bfhi(w.x), bflo(w.y), bfhi(w.y)}; v1 = (f32x4){bflo(w.z), bfhi(w.z), bflo(w.w), bfhi(w.w)}; }
;                     v0 = v0 + acc[ai][bj][m][0] * alpha; v1 = v1 + acc[ai][bj][m][1] * alpha;
;                     if (RM == 2) { *(f32x4*)(outf + off) = v0; *(f32x4*)(outf + off + 4) = v1; }
;                     else {
;                         u32x4 w; w.x = cvtpk(v0[0], v0[1]); w.y = cvtpk(v0[2], v0[3]); w.z = cvtpk(v1[0], v1[1]); w.w = cvtpk(v1[2], v1[3]);
;                         *(u32x4*)(xb + off) = w;
;                         s += (v0[0] * v0[0] + v0[1] * v0[1]) + (v0[2] * v0[2] + v0[3] * v0[3]) + (v1[0] * v1[0] + v1[1] * v1[1]) + (v1[2] * v1[2] + v1[3] * v1[3]);
;                     }
;                 }
	v_lshlrev_b32_e32 v222, 16, v168
	v_and_b32_e32 v223, 0xffff0000, v168
	v_lshlrev_b32_e32 v224, 16, v169
	v_and_b32_e32 v225, 0xffff0000, v169
	v_lshlrev_b32_e32 v226, 16, v170
	v_and_b32_e32 v227, 0xffff0000, v170
	v_lshlrev_b32_e32 v228, 16, v171
	v_and_b32_e32 v229, 0xffff0000, v171
	v_fma_f32 v92, v92, 0.5, v222
	v_fma_f32 v93, v93, 0.5, v223
	v_fma_f32 v94, v94, 0.5, v224
	v_fma_f32 v95, v95, 0.5, v225
	v_fma_f32 v88, v88, 0.5, v226
	v_fma_f32 v89, v89, 0.5, v227
	v_fma_f32 v90, v90, 0.5, v228
	v_fma_f32 v91, v91, 0.5, v229
	v_cvt_pk_bf16_f32 v168, v92, v93
	v_cvt_pk_bf16_f32 v169, v94, v95
	v_cvt_pk_bf16_f32 v170, v88, v89
	v_cvt_pk_bf16_f32 v171, v90, v91
	global_store_dwordx4 v206, v[168:171], s[18:19]
	v_mul_f32_e32 v220, v92, v92
	v_mul_f32_e32 v221, v93, v93
	v_fmac_f32_e32 v220, v94, v94
	v_fmac_f32_e32 v221, v95, v95
	v_fmac_f32_e32 v220, v88, v88
	v_fmac_f32_e32 v221, v89, v89
	v_fmac_f32_e32 v220, v90, v90
	v_fmac_f32_e32 v221, v91, v91
	v_lshlrev_b32_e32 v222, 16, v172
	v_and_b32_e32 v223, 0xffff0000, v172
	v_lshlrev_b32_e32 v224, 16, v173
	v_and_b32_e32 v225, 0xffff0000, v173
	v_lshlrev_b32_e32 v226, 16, v174
	v_and_b32_e32 v227, 0xffff0000, v174
	v_lshlrev_b32_e32 v228, 16, v175
	v_and_b32_e32 v229, 0xffff0000, v175
	v_fma_f32 v84, v84, 0.5, v222
	v_fma_f32 v85, v85, 0.5, v223
	v_fma_f32 v86, v86, 0.5, v224
	v_fma_f32 v87, v87, 0.5, v225
	v_fma_f32 v80, v80, 0.5, v226
	v_fma_f32 v81, v81, 0.5, v227
	v_fma_f32 v82, v82, 0.5, v228
	v_fma_f32 v83, v83, 0.5, v229
	v_cvt_pk_bf16_f32 v172, v84, v85
	v_cvt_pk_bf16_f32 v173, v86, v87
	v_cvt_pk_bf16_f32 v174, v80, v81
	v_cvt_pk_bf16_f32 v175, v82, v83
	global_store_dwordx4 v206, v[172:175], s[18:19] offset:256
	v_mul_f32_e32 v230, v84, v84
	v_mul_f32_e32 v231, v85, v85
	v_fmac_f32_e32 v230, v86, v86
	v_fmac_f32_e32 v231, v87, v87
	v_fmac_f32_e32 v230, v80, v80
	v_fmac_f32_e32 v231, v81, v81
	v_fmac_f32_e32 v230, v82, v82
	v_fmac_f32_e32 v231, v83, v83
	v_add_f32_e32 v220, v220, v230
	v_add_f32_e32 v221, v221, v231
	v_add_f32_e32 v214, v220, v221
	s_waitcnt vmcnt(14)
	v_lshlrev_b32_e32 v222, 16, v176
	v_and_b32_e32 v223, 0xffff0000, v176
	v_lshlrev_b32_e32 v224, 16, v177
	v_and_b32_e32 v225, 0xffff0000, v177
	v_lshlrev_b32_e32 v226, 16, v178
	v_and_b32_e32 v227, 0xffff0000, v178
	v_lshlrev_b32_e32 v228, 16, v179
	v_and_b32_e32 v229, 0xffff0000, v179
	v_fma_f32 v76, v76, 0.5, v222
	v_fma_f32 v77, v77, 0.5, v223
	v_fma_f32 v78, v78, 0.5, v224
	v_fma_f32 v79, v79, 0.5, v225
	v_fma_f32 v72, v72, 0.5, v226
	v_fma_f32 v73, v73, 0.5, v227
	v_fma_f32 v74, v74, 0.5, v228
	v_fma_f32 v75, v75, 0.5, v229
	v_cvt_pk_bf16_f32 v176, v76, v77
	v_cvt_pk_bf16_f32 v177, v78, v79
	v_cvt_pk_bf16_f32 v178, v72, v73
	v_cvt_pk_bf16_f32 v179, v74, v75
	global_store_dwordx4 v207, v[176:179], s[18:19]
	v_mul_f32_e32 v220, v76, v76
	v_mul_f32_e32 v221, v77, v77
	v_fmac_f32_e32 v220, v78, v78
	v_fmac_f32_e32 v221, v79, v79
	v_fmac_f32_e32 v220, v72, v72
	v_fmac_f32_e32 v221, v73, v73
	v_fmac_f32_e32 v220, v74, v74
	v_fmac_f32_e32 v221, v75, v75
	v_lshlrev_b32_e32 v222, 16, v180
	v_and_b32_e32 v223, 0xffff0000, v180
	v_lshlrev_b32_e32 v224, 16, v181
	v_and_b32_e32 v225, 0xffff0000, v181
	v_lshlrev_b32_e32 v226, 16, v182
	v_and_b32_e32 v227, 0xffff0000, v182
	v_lshlrev_b32_e32 v228, 16, v183
	v_and_b32_e32 v229, 0xffff0000, v183
	v_fma_f32 v68, v68, 0.5, v222
	v_fma_f32 v69, v69, 0.5, v223
	v_fma_f32 v70, v70, 0.5, v224
	v_fma_f32 v71, v71, 0.5, v225
	v_fma_f32 v64, v64, 0.5, v226
	v_fma_f32 v65, v65, 0.5, v227
	v_fma_f32 v66, v66, 0.5, v228
	v_fma_f32 v67, v67, 0.5, v229
	v_cvt_pk_bf16_f32 v180, v68, v69
	v_cvt_pk_bf16_f32 v181, v70, v71
	v_cvt_pk_bf16_f32 v182, v64, v65
	v_cvt_pk_bf16_f32 v183, v66, v67
	global_store_dwordx4 v207, v[180:183], s[18:19] offset:256
	v_mul_f32_e32 v230, v68, v68
	v_mul_f32_e32 v231, v69, v69
	v_fmac_f32_e32 v230, v70, v70
	v_fmac_f32_e32 v231, v71, v71
	v_fmac_f32_e32 v230, v64, v64
	v_fmac_f32_e32 v231, v65, v65
	v_fmac_f32_e32 v230, v66, v66
	v_fmac_f32_e32 v231, v67, v67
	v_add_f32_e32 v220, v220, v230
	v_add_f32_e32 v221, v221, v231
	v_add_f32_e32 v215, v220, v221
	s_waitcnt vmcnt(14)
	v_lshlrev_b32_e32 v222, 16, v184
	v_and_b32_e32 v223, 0xffff0000, v184
	v_lshlrev_b32_e32 v224, 16, v185
	v_and_b32_e32 v225, 0xffff0000, v185
	v_lshlrev_b32_e32 v226, 16, v186
	v_and_b32_e32 v227, 0xffff0000, v186
	v_lshlrev_b32_e32 v228, 16, v187
	v_and_b32_e32 v229, 0xffff0000, v187
	v_fma_f32 v60, v60, 0.5, v222
	v_fma_f32 v61, v61, 0.5, v223
	v_fma_f32 v62, v62, 0.5, v224
	v_fma_f32 v63, v63, 0.5, v225
	v_fma_f32 v56, v56, 0.5, v226
	v_fma_f32 v57, v57, 0.5, v227
	v_fma_f32 v58, v58, 0.5, v228
	v_fma_f32 v59, v59, 0.5, v229
	v_cvt_pk_bf16_f32 v184, v60, v61
	v_cvt_pk_bf16_f32 v185, v62, v63
	v_cvt_pk_bf16_f32 v186, v56, v57
	v_cvt_pk_bf16_f32 v187, v58, v59
	global_store_dwordx4 v208, v[184:187], s[18:19]
	v_mul_f32_e32 v220, v60, v60
	v_mul_f32_e32 v221, v61, v61
	v_fmac_f32_e32 v220, v62, v62
	v_fmac_f32_e32 v221, v63, v63
	v_fmac_f32_e32 v220, v56, v56
	v_fmac_f32_e32 v221, v57, v57
	v_fmac_f32_e32 v220, v58, v58
	v_fmac_f32_e32 v221, v59, v59
	v_lshlrev_b32_e32 v222, 16, v188
	v_and_b32_e32 v223, 0xffff0000, v188
	v_lshlrev_b32_e32 v224, 16, v189
	v_and_b32_e32 v225, 0xffff0000, v189
	v_lshlrev_b32_e32 v226, 16, v190
	v_and_b32_e32 v227, 0xffff0000, v190
	v_lshlrev_b32_e32 v228, 16, v191
	v_and_b32_e32 v229, 0xffff0000, v191
	v_fma_f32 v52, v52, 0.5, v222
	v_fma_f32 v53, v53, 0.5, v223
	v_fma_f32 v54, v54, 0.5, v224
	v_fma_f32 v55, v55, 0.5, v225
	v_fma_f32 v48, v48, 0.5, v226
	v_fma_f32 v49, v49, 0.5, v227
	v_fma_f32 v50, v50, 0.5, v228
	v_fma_f32 v51, v51, 0.5, v229
	v_cvt_pk_bf16_f32 v188, v52, v53
	v_cvt_pk_bf16_f32 v189, v54, v55
	v_cvt_pk_bf16_f32 v190, v48, v49
	v_cvt_pk_bf16_f32 v191, v50, v51
	global_store_dwordx4 v208, v[188:191], s[18:19] offset:256
	v_mul_f32_e32 v230, v52, v52
	v_mul_f32_e32 v231, v53, v53
	v_fmac_f32_e32 v230, v54, v54
	v_fmac_f32_e32 v231, v55, v55
	v_fmac_f32_e32 v230, v48, v48
	v_fmac_f32_e32 v231, v49, v49
	v_fmac_f32_e32 v230, v50, v50
	v_fmac_f32_e32 v231, v51, v51
	v_add_f32_e32 v220, v220, v230
	v_add_f32_e32 v221, v221, v231
	v_add_f32_e32 v216, v220, v221
	s_waitcnt vmcnt(14)
; __device__ __forceinline__ unsigned cvtpk(float lo, float hi) { f32x2_t v = {lo, hi}; bf16x2_t b = __builtin_convertvector(v, bf16x2_t); return __builtin_bit_cast(unsigned, b); }
; __device__ __forceinline__ float bflo(unsigned w) { return __uint_as_float(w << 16); }
; __device__ __forceinline__ float bfhi(unsigned w) { return __uint_as_float(w & 0xffff0000u); }
;     __device__ __forceinline__ void operator()(const f32x4 (&acc)[2][2][4][2], const Unit& u, int wr, int wc, int fr, int fq) const {
;     ...
;                 for (int bj = 0; bj < 2; ++bj) {
;                     const size_t off = (size_t)row * DM + col0 + bj * HALF;
;                     f32x4 v0, v1;
;                     if (RM == 0) { v0 = *(const f32x4*)(xf + off); v1 = *(const f32x4*)(xf + off + 4); }
;                     else { const u32x4 w = xv[RM == 0 ? 0 : ai][RM == 0 ? 0 : m][RM == 0 ? 0 : bj]; v0 = (f32x4){bflo(w.x), bfhi(w.x), bflo(w.y), bfhi(w.y)}; v1 = (f32x4){bflo(w.z), bfhi(w.z), bflo(w.w), bfhi(w.w)}; }
;                     v0 = v0 + acc[ai][bj][m][0] * alpha; v1 = v1 + acc[ai][bj][m][1] * alpha;
;                     if (RM == 2) { *(f32x4*)(outf + off) = v0; *(f32x4*)(outf + off + 4) = v1; }
;                     else {
;                         u32x4 w; w.x = cvtpk(v0[0], v0[1]); w.y = cvtpk(v0[2], v0[3]); w.z = cvtpk(v1[0], v1[1]); w.w = cvtpk(v1[2], v1[3]);
;                         *(u32x4*)(xb + off) = w;
;                         s += (v0[0] * v0[0] + v0[1] * v0[1]) + (v0[2] * v0[2] + v0[3] * v0[3]) + (v1[0] * v1[0] + v1[1] * v1[1]) + (v1[2] * v1[2] + v1[3] * v1[3]);
;                     }
;                 }
;                 if (RM != 2) { s += __shfl_xor(s, 16); s += __shfl_xor(s, 32); if (fq == 0) ssq_out[(size_t)row * 16 + u.pn * 4 + wc] = s; }
	v_lshlrev_b32_e32 v222, 16, v120
	v_and_b32_e32 v223, 0xffff0000, v120
	v_lshlrev_b32_e32 v224, 16, v121
	v_and_b32_e32 v225, 0xffff0000, v121
	v_lshlrev_b32_e32 v226, 16, v122
	v_and_b32_e32 v227, 0xffff0000, v122
	v_lshlrev_b32_e32 v228, 16, v123
	v_and_b32_e32 v229, 0xffff0000, v123
	v_fma_f32 v44, v44, 0.5, v222
	v_fma_f32 v45, v45, 0.5, v223
	v_fma_f32 v46, v46, 0.5, v224
	v_fma_f32 v47, v47, 0.5, v225
	v_fma_f32 v40, v40, 0.5, v226
	v_fma_f32 v41, v41, 0.5, v227
	v_fma_f32 v42, v42, 0.5, v228
	v_fma_f32 v43, v43, 0.5, v229
	v_cvt_pk_bf16_f32 v120, v44, v45
	v_cvt_pk_bf16_f32 v121, v46, v47
	v_cvt_pk_bf16_f32 v122, v40, v41
	v_cvt_pk_bf16_f32 v123, v42, v43
	global_store_dwordx4 v209, v[120:123], s[18:19]
	v_mul_f32_e32 v220, v44, v44
	v_mul_f32_e32 v221, v45, v45
	v_fmac_f32_e32 v220, v46, v46
	v_fmac_f32_e32 v221, v47, v47
	v_fmac_f32_e32 v220, v40, v40
	v_fmac_f32_e32 v221, v41, v41
	v_fmac_f32_e32 v220, v42, v42
	v_fmac_f32_e32 v221, v43, v43
	v_lshlrev_b32_e32 v222, 16, v124
	v_and_b32_e32 v223, 0xffff0000, v124
	v_lshlrev_b32_e32 v224, 16, v125
	v_and_b32_e32 v225, 0xffff0000, v125
	v_lshlrev_b32_e32 v226, 16, v126
	v_and_b32_e32 v227, 0xffff0000, v126
	v_lshlrev_b32_e32 v228, 16, v127
	v_and_b32_e32 v229, 0xffff0000, v127
	v_fma_f32 v36, v36, 0.5, v222
	v_fma_f32 v37, v37, 0.5, v223
	v_fma_f32 v38, v38, 0.5, v224
	v_fma_f32 v39, v39, 0.5, v225
	v_fma_f32 v32, v32, 0.5, v226
	v_fma_f32 v33, v33, 0.5, v227
	v_fma_f32 v34, v34, 0.5, v228
	v_fma_f32 v35, v35, 0.5, v229
	v_cvt_pk_bf16_f32 v124, v36, v37
	v_cvt_pk_bf16_f32 v125, v38, v39
	v_cvt_pk_bf16_f32 v126, v32, v33
	v_cvt_pk_bf16_f32 v127, v34, v35
	global_store_dwordx4 v209, v[124:127], s[18:19] offset:256
	v_mul_f32_e32 v230, v36, v36
	v_mul_f32_e32 v231, v37, v37
	v_fmac_f32_e32 v230, v38, v38
	v_fmac_f32_e32 v231, v39, v39
	v_fmac_f32_e32 v230, v32, v32
	v_fmac_f32_e32 v231, v33, v33
	v_fmac_f32_e32 v230, v34, v34
	v_fmac_f32_e32 v231, v35, v35
	v_add_f32_e32 v220, v220, v230
	v_add_f32_e32 v221, v221, v231
	v_add_f32_e32 v217, v220, v221
	s_waitcnt vmcnt(14)
	v_lshlrev_b32_e32 v222, 16, v128
	v_and_b32_e32 v223, 0xffff0000, v128
	v_lshlrev_b32_e32 v224, 16, v129
	v_and_b32_e32 v225, 0xffff0000, v129
	v_lshlrev_b32_e32 v226, 16, v130
	v_and_b32_e32 v227, 0xffff0000, v130
	v_lshlrev_b32_e32 v228, 16, v131
	v_and_b32_e32 v229, 0xffff0000, v131
	v_fma_f32 v28, v28, 0.5, v222
	v_fma_f32 v29, v29, 0.5, v223
	v_fma_f32 v30, v30, 0.5, v224
	v_fma_f32 v31, v31, 0.5, v225
	v_fma_f32 v24, v24, 0.5, v226
	v_fma_f32 v25, v25, 0.5, v227
	v_fma_f32 v26, v26, 0.5, v228
	v_fma_f32 v27, v27, 0.5, v229
	v_cvt_pk_bf16_f32 v128, v28, v29
	v_cvt_pk_bf16_f32 v129, v30, v31
	v_cvt_pk_bf16_f32 v130, v24, v25
	v_cvt_pk_bf16_f32 v131, v26, v27
	global_store_dwordx4 v210, v[128:131], s[18:19]
	v_mul_f32_e32 v220, v28, v28
	v_mul_f32_e32 v221, v29, v29
	v_fmac_f32_e32 v220, v30, v30
	v_fmac_f32_e32 v221, v31, v31
	v_fmac_f32_e32 v220, v24, v24
	v_fmac_f32_e32 v221, v25, v25
	v_fmac_f32_e32 v220, v26, v26
	v_fmac_f32_e32 v221, v27, v27
	v_lshlrev_b32_e32 v222, 16, v132
	v_and_b32_e32 v223, 0xffff0000, v132
	v_lshlrev_b32_e32 v224, 16, v133
	v_and_b32_e32 v225, 0xffff0000, v133
	v_lshlrev_b32_e32 v226, 16, v134
	v_and_b32_e32 v227, 0xffff0000, v134
	v_lshlrev_b32_e32 v228, 16, v135
	v_and_b32_e32 v229, 0xffff0000, v135
	v_fma_f32 v20, v20, 0.5, v222
	v_fma_f32 v21, v21, 0.5, v223
	v_fma_f32 v22, v22, 0.5, v224
	v_fma_f32 v23, v23, 0.5, v225
	v_fma_f32 v16, v16, 0.5, v226
	v_fma_f32 v17, v17, 0.5, v227
	v_fma_f32 v18, v18, 0.5, v228
	v_fma_f32 v19, v19, 0.5, v229
	v_cvt_pk_bf16_f32 v132, v20, v21
	v_cvt_pk_bf16_f32 v133, v22, v23
	v_cvt_pk_bf16_f32 v134, v16, v17
	v_cvt_pk_bf16_f32 v135, v18, v19
	global_store_dwordx4 v210, v[132:135], s[18:19] offset:256
	v_mul_f32_e32 v230, v20, v20
	v_mul_f32_e32 v231, v21, v21
	v_fmac_f32_e32 v230, v22, v22
	v_fmac_f32_e32 v231, v23, v23
	v_fmac_f32_e32 v230, v16, v16
	v_fmac_f32_e32 v231, v17, v17
	v_fmac_f32_e32 v230, v18, v18
	v_fmac_f32_e32 v231, v19, v19
	v_add_f32_e32 v220, v220, v230
	v_add_f32_e32 v221, v221, v231
	v_add_f32_e32 v218, v220, v221
	s_waitcnt vmcnt(14)
	v_lshlrev_b32_e32 v222, 16, v136
	v_and_b32_e32 v223, 0xffff0000, v136
	v_lshlrev_b32_e32 v224, 16, v137
	v_and_b32_e32 v225, 0xffff0000, v137
	v_lshlrev_b32_e32 v226, 16, v138
	v_and_b32_e32 v227, 0xffff0000, v138
	v_lshlrev_b32_e32 v228, 16, v139
	v_and_b32_e32 v229, 0xffff0000, v139
	v_fma_f32 v12, v12, 0.5, v222
	v_fma_f32 v13, v13, 0.5, v223
	v_fma_f32 v14, v14, 0.5, v224
	v_fma_f32 v15, v15, 0.5, v225
	v_fma_f32 v8, v8, 0.5, v226
	v_fma_f32 v9, v9, 0.5, v227
	v_fma_f32 v10, v10, 0.5, v228
	v_fma_f32 v11, v11, 0.5, v229
	v_cvt_pk_bf16_f32 v136, v12, v13
	v_cvt_pk_bf16_f32 v137, v14, v15
	v_cvt_pk_bf16_f32 v138, v8, v9
	v_cvt_pk_bf16_f32 v139, v10, v11
	global_store_dwordx4 v211, v[136:139], s[18:19]
	v_mul_f32_e32 v220, v12, v12
	v_mul_f32_e32 v221, v13, v13
	v_fmac_f32_e32 v220, v14, v14
	v_fmac_f32_e32 v221, v15, v15
	v_fmac_f32_e32 v220, v8, v8
	v_fmac_f32_e32 v221, v9, v9
	v_fmac_f32_e32 v220, v10, v10
	v_fmac_f32_e32 v221, v11, v11
	v_lshlrev_b32_e32 v222, 16, v140
	v_and_b32_e32 v223, 0xffff0000, v140
	v_lshlrev_b32_e32 v224, 16, v141
	v_and_b32_e32 v225, 0xffff0000, v141
	v_lshlrev_b32_e32 v226, 16, v142
	v_and_b32_e32 v227, 0xffff0000, v142
	v_lshlrev_b32_e32 v228, 16, v143
	v_and_b32_e32 v229, 0xffff0000, v143
	v_fma_f32 v4, v4, 0.5, v222
	v_fma_f32 v5, v5, 0.5, v223
	v_fma_f32 v6, v6, 0.5, v224
	v_fma_f32 v7, v7, 0.5, v225
	v_fma_f32 v0, v0, 0.5, v226
	v_fma_f32 v1, v1, 0.5, v227
	v_fma_f32 v2, v2, 0.5, v228
	v_fma_f32 v3, v3, 0.5, v229
	v_cvt_pk_bf16_f32 v140, v4, v5
	v_cvt_pk_bf16_f32 v141, v6, v7
	v_cvt_pk_bf16_f32 v142, v0, v1
	v_cvt_pk_bf16_f32 v143, v2, v3
	global_store_dwordx4 v211, v[140:143], s[18:19] offset:256
	v_mul_f32_e32 v230, v4, v4
	v_mul_f32_e32 v231, v5, v5
	v_fmac_f32_e32 v230, v6, v6
	v_fmac_f32_e32 v231, v7, v7
	v_fmac_f32_e32 v230, v0, v0
	v_fmac_f32_e32 v231, v1, v1
	v_fmac_f32_e32 v230, v2, v2
	v_fmac_f32_e32 v231, v3, v3
	v_add_f32_e32 v220, v220, v230
	v_add_f32_e32 v221, v221, v231
	v_add_f32_e32 v219, v220, v221
	s_nop 1
	v_permlane32_swap_b32_e32 v212, v213
	v_permlane32_swap_b32_e32 v214, v215
	v_permlane32_swap_b32_e32 v216, v217
	v_permlane32_swap_b32_e32 v218, v219
	v_add_f32_e32 v212, v212, v213
	v_add_f32_e32 v214, v214, v215
	v_add_f32_e32 v216, v216, v217
	v_add_f32_e32 v218, v218, v219
	s_nop 1
	v_permlane16_swap_b32_e32 v212, v214
	v_permlane16_swap_b32_e32 v216, v218
	v_add_f32_e32 v212, v212, v214
	v_add_f32_e32 v216, v216, v218
	global_store_dword v236, v212, s[20:21]
	global_store_dword v237, v216, s[20:21]
	s_and_b64 vcc, exec, s[8:9]
	s_mov_b64 s[8:9], -1
	s_cbranch_vccnz .LBB0_1126
	s_andn2_b64 vcc, exec, s[16:17]
	s_cbranch_vccnz .LBB0_1125
	s_barrier
	s_branch .LBB0_1125

; __device__ __forceinline__ unsigned cvtpk(float lo, float hi) { f32x2_t v = {lo, hi}; bf16x2_t b = __builtin_convertvector(v, bf16x2_t); return __builtin_bit_cast(unsigned, b); }
;     __device__ __forceinline__ void operator()(const f32x4 (&acc)[2][2][4][2], const Unit& u, int wr, int wc, int fr, int fq) const {
;         const int row0 = u.pm * BM + wr * 64 + fr, col0 = u.pn * BM + wc * 32 + 8 * fq;
;         float* so = (u.pn == 0) ? ssq_o[0] : (u.pn == 1) ? ssq_o[1] : (u.pn == 2) ? ssq_o[2] : (u.pn == 3) ? ssq_o[3] : nullptr;
; #pragma unroll
;         for (int ai = 0; ai < 2; ++ai)
; #pragma unroll
;             for (int m = 0; m < 4; ++m) {
;                 const int row = row0 + ai * HALF + m * 16; float s = 0.f;
;                 const float rs = ssq_in ? 1.0f / sqrtf(ssq_sum(ssq_in + (size_t)row * 16) * inv_dim + EPS) : 1.0f;
; #pragma unroll
;                 for (int bj = 0; bj < 2; ++bj) {
;                     int col = col0 + bj * HALF; if (hd_in) col = (col / hd_in) * hd_out + (col % hd_in);
;                     const f32x4 v0 = acc[ai][bj][m][0] * rs, v1 = acc[ai][bj][m][1] * rs;
;                     u32x4 w; w.x = cvtpk(v0[0], v0[1]); w.y = cvtpk(v0[2], v0[3]); w.z = cvtpk(v1[0], v1[1]); w.w = cvtpk(v1[2], v1[3]);
;                     *(u32x4*)(O + (size_t)row * ldc + col) = w;
.LBB0_1527:
	v_readlane_b32 vcc_lo, v254, 7
	v_mbcnt_lo_u32_b32 v158, -1, 0
	v_mbcnt_hi_u32_b32 v158, -1, v158
	v_lshrrev_b32_e32 v159, 1, v158
	v_lshl_add_u32 v159, vcc_lo, 5, v159
	v_and_b32_e32 v160, 1, v158
	v_lshl_add_u32 v161, s8, 8, v159
	v_lshlrev_b32_e32 v161, 6, v161
	v_lshl_add_u32 v161, v160, 5, v161
	global_load_dwordx4 v[162:165], v161, s[20:21]
	global_load_dwordx4 v[166:169], v161, s[20:21] offset:16
	v_lshl_add_u32 v170, s8, 8, v150
	v_mul_u32_u24_e32 v170, 0xc00, v170
	v_lshl_or_b32 v171, s9, 8, v152
	v_lshl_add_u32 v170, v171, 1, v170
	v_lshlrev_b32_e32 v159, 2, v159
	v_add_u32_e32 v159, 0x20100, v159
	v_lshlrev_b32_e32 v160, 2, v150
	v_add_u32_e32 v160, 0x20100, v160
	s_waitcnt vmcnt(0)
	v_add_f32_e32 v162, v162, v164
	v_add_f32_e32 v163, v163, v165
	v_add_f32_e32 v166, v166, v168
	v_add_f32_e32 v167, v167, v169
	v_add_f32_e32 v162, v162, v166
	v_add_f32_e32 v163, v163, v167
	v_add_f32_e32 v162, v162, v163
	s_nop 1
	v_add_f32_dpp v162, v162, v162 quad_perm:[1,0,3,2] row_mask:0xf bank_mask:0xf
	v_fmamk_f32 v162, v162, 0x3b000000, v156
	v_rsq_f32_e32 v162, v162
	s_nop 0
	ds_write_b32 v159, v162
	s_waitcnt lgkmcnt(0)
	s_barrier
	ds_read_b32 v162, v160 offset:0
	ds_read_b32 v163, v160 offset:64
	ds_read_b32 v164, v160 offset:128
	ds_read_b32 v165, v160 offset:192
	ds_read_b32 v166, v160 offset:512
	ds_read_b32 v167, v160 offset:576
	ds_read_b32 v168, v160 offset:640
	ds_read_b32 v169, v160 offset:704
	s_waitcnt lgkmcnt(7)
	v_mul_f32_e32 v124, v162, v124
	v_mul_f32_e32 v125, v162, v125
	v_mul_f32_e32 v126, v162, v126
	v_mul_f32_e32 v127, v162, v127
	v_mul_f32_e32 v120, v162, v120
	v_mul_f32_e32 v121, v162, v121
	v_mul_f32_e32 v122, v162, v122
	v_mul_f32_e32 v123, v162, v123
	v_mul_f32_e32 v116, v162, v116
	v_mul_f32_e32 v117, v162, v117
	v_mul_f32_e32 v118, v162, v118
	v_mul_f32_e32 v119, v162, v119
	v_mul_f32_e32 v112, v162, v112
	v_mul_f32_e32 v113, v162, v113
	v_mul_f32_e32 v114, v162, v114
	v_mul_f32_e32 v115, v162, v115
	v_cvt_pk_bf16_f32 v124, v124, v125
	v_cvt_pk_bf16_f32 v125, v126, v127
	v_cvt_pk_bf16_f32 v126, v120, v121
	v_cvt_pk_bf16_f32 v127, v122, v123
	v_cvt_pk_bf16_f32 v116, v116, v117
	v_cvt_pk_bf16_f32 v117, v118, v119
	v_cvt_pk_bf16_f32 v118, v112, v113
	v_cvt_pk_bf16_f32 v119, v114, v115
	global_store_dwordx4 v170, v[124:127], s[16:17]
	global_store_dwordx4 v170, v[116:119], s[16:17] offset:256
	s_waitcnt lgkmcnt(6)
	v_mul_f32_e32 v108, v163, v108
	v_mul_f32_e32 v109, v163, v109
	v_mul_f32_e32 v110, v163, v110
	v_mul_f32_e32 v111, v163, v111
	v_mul_f32_e32 v104, v163, v104
	v_mul_f32_e32 v105, v163, v105
	v_mul_f32_e32 v106, v163, v106
	v_mul_f32_e32 v107, v163, v107
	v_mul_f32_e32 v100, v163, v100
	v_mul_f32_e32 v101, v163, v101
	v_mul_f32_e32 v102, v163, v102
	v_mul_f32_e32 v103, v163, v103
	v_mul_f32_e32 v96, v163, v96
	v_mul_f32_e32 v97, v163, v97
	v_mul_f32_e32 v98, v163, v98
	v_mul_f32_e32 v99, v163, v99
	v_cvt_pk_bf16_f32 v108, v108, v109
	v_cvt_pk_bf16_f32 v109, v110, v111
	v_cvt_pk_bf16_f32 v110, v104, v105
	v_cvt_pk_bf16_f32 v111, v106, v107
	v_cvt_pk_bf16_f32 v100, v100, v101
	v_cvt_pk_bf16_f32 v101, v102, v103
	v_cvt_pk_bf16_f32 v102, v96, v97
	v_cvt_pk_bf16_f32 v103, v98, v99
	v_add_u32_e32 v171, 0xc000, v170
	global_store_dwordx4 v171, v[108:111], s[16:17]
	global_store_dwordx4 v171, v[100:103], s[16:17] offset:256
	s_waitcnt lgkmcnt(5)
	v_mul_f32_e32 v92, v164, v92
	v_mul_f32_e32 v93, v164, v93
	v_mul_f32_e32 v94, v164, v94
	v_mul_f32_e32 v95, v164, v95
	v_mul_f32_e32 v88, v164, v88
	v_mul_f32_e32 v89, v164, v89
	v_mul_f32_e32 v90, v164, v90
	v_mul_f32_e32 v91, v164, v91
	v_mul_f32_e32 v84, v164, v84
	v_mul_f32_e32 v85, v164, v85
	v_mul_f32_e32 v86, v164, v86
	v_mul_f32_e32 v87, v164, v87
	v_mul_f32_e32 v80, v164, v80
	v_mul_f32_e32 v81, v164, v81
	v_mul_f32_e32 v82, v164, v82
	v_mul_f32_e32 v83, v164, v83
	v_cvt_pk_bf16_f32 v92, v92, v93
	v_cvt_pk_bf16_f32 v93, v94, v95
	v_cvt_pk_bf16_f32 v94, v88, v89
	v_cvt_pk_bf16_f32 v95, v90, v91
	v_cvt_pk_bf16_f32 v84, v84, v85
	v_cvt_pk_bf16_f32 v85, v86, v87
	v_cvt_pk_bf16_f32 v86, v80, v81
	v_cvt_pk_bf16_f32 v87, v82, v83
	v_add_u32_e32 v171, 0x18000, v170
	global_store_dwordx4 v171, v[92:95], s[16:17]
	global_store_dwordx4 v171, v[84:87], s[16:17] offset:256
	s_waitcnt lgkmcnt(4)
; __device__ __forceinline__ unsigned cvtpk(float lo, float hi) { f32x2_t v = {lo, hi}; bf16x2_t b = __builtin_convertvector(v, bf16x2_t); return __builtin_bit_cast(unsigned, b); }
;     __device__ __forceinline__ void operator()(const f32x4 (&acc)[2][2][4][2], const Unit& u, int wr, int wc, int fr, int fq) const {
;     ...
;                 for (int bj = 0; bj < 2; ++bj) {
;                     int col = col0 + bj * HALF; if (hd_in) col = (col / hd_in) * hd_out + (col % hd_in);
;                     const f32x4 v0 = acc[ai][bj][m][0] * rs, v1 = acc[ai][bj][m][1] * rs;
;                     u32x4 w; w.x = cvtpk(v0[0], v0[1]); w.y = cvtpk(v0[2], v0[3]); w.z = cvtpk(v1[0], v1[1]); w.w = cvtpk(v1[2], v1[3]);
;                     *(u32x4*)(O + (size_t)row * ldc + col) = w;
	v_mul_f32_e32 v76, v165, v76
	v_mul_f32_e32 v77, v165, v77
	v_mul_f32_e32 v78, v165, v78
	v_mul_f32_e32 v79, v165, v79
	v_mul_f32_e32 v72, v165, v72
	v_mul_f32_e32 v73, v165, v73
	v_mul_f32_e32 v74, v165, v74
	v_mul_f32_e32 v75, v165, v75
	v_mul_f32_e32 v68, v165, v68
	v_mul_f32_e32 v69, v165, v69
	v_mul_f32_e32 v70, v165, v70
	v_mul_f32_e32 v71, v165, v71
	v_mul_f32_e32 v64, v165, v64
	v_mul_f32_e32 v65, v165, v65
	v_mul_f32_e32 v66, v165, v66
	v_mul_f32_e32 v67, v165, v67
	v_cvt_pk_bf16_f32 v76, v76, v77
	v_cvt_pk_bf16_f32 v77, v78, v79
	v_cvt_pk_bf16_f32 v78, v72, v73
	v_cvt_pk_bf16_f32 v79, v74, v75
	v_cvt_pk_bf16_f32 v68, v68, v69
	v_cvt_pk_bf16_f32 v69, v70, v71
	v_cvt_pk_bf16_f32 v70, v64, v65
	v_cvt_pk_bf16_f32 v71, v66, v67
	v_add_u32_e32 v171, 0x24000, v170
	global_store_dwordx4 v171, v[76:79], s[16:17]
	global_store_dwordx4 v171, v[68:71], s[16:17] offset:256
	s_waitcnt lgkmcnt(3)
	v_mul_f32_e32 v60, v166, v60
	v_mul_f32_e32 v61, v166, v61
	v_mul_f32_e32 v62, v166, v62
	v_mul_f32_e32 v63, v166, v63
	v_mul_f32_e32 v56, v166, v56
	v_mul_f32_e32 v57, v166, v57
	v_mul_f32_e32 v58, v166, v58
	v_mul_f32_e32 v59, v166, v59
	v_mul_f32_e32 v52, v166, v52
	v_mul_f32_e32 v53, v166, v53
	v_mul_f32_e32 v54, v166, v54
	v_mul_f32_e32 v55, v166, v55
	v_mul_f32_e32 v48, v166, v48
	v_mul_f32_e32 v49, v166, v49
	v_mul_f32_e32 v50, v166, v50
	v_mul_f32_e32 v51, v166, v51
	v_cvt_pk_bf16_f32 v60, v60, v61
	v_cvt_pk_bf16_f32 v61, v62, v63
	v_cvt_pk_bf16_f32 v62, v56, v57
	v_cvt_pk_bf16_f32 v63, v58, v59
	v_cvt_pk_bf16_f32 v52, v52, v53
	v_cvt_pk_bf16_f32 v53, v54, v55
	v_cvt_pk_bf16_f32 v54, v48, v49
	v_cvt_pk_bf16_f32 v55, v50, v51
	v_add_u32_e32 v171, 0x60000, v170
	global_store_dwordx4 v171, v[60:63], s[16:17]
	global_store_dwordx4 v171, v[52:55], s[16:17] offset:256
	s_waitcnt lgkmcnt(2)
	v_mul_f32_e32 v44, v167, v44
	v_mul_f32_e32 v45, v167, v45
	v_mul_f32_e32 v46, v167, v46
	v_mul_f32_e32 v47, v167, v47
	v_mul_f32_e32 v40, v167, v40
	v_mul_f32_e32 v41, v167, v41
	v_mul_f32_e32 v42, v167, v42
	v_mul_f32_e32 v43, v167, v43
	v_mul_f32_e32 v36, v167, v36
	v_mul_f32_e32 v37, v167, v37
	v_mul_f32_e32 v38, v167, v38
	v_mul_f32_e32 v39, v167, v39
	v_mul_f32_e32 v32, v167, v32
	v_mul_f32_e32 v33, v167, v33
	v_mul_f32_e32 v34, v167, v34
	v_mul_f32_e32 v35, v167, v35
	v_cvt_pk_bf16_f32 v44, v44, v45
	v_cvt_pk_bf16_f32 v45, v46, v47
	v_cvt_pk_bf16_f32 v46, v40, v41
	v_cvt_pk_bf16_f32 v47, v42, v43
	v_cvt_pk_bf16_f32 v36, v36, v37
	v_cvt_pk_bf16_f32 v37, v38, v39
	v_cvt_pk_bf16_f32 v38, v32, v33
	v_cvt_pk_bf16_f32 v39, v34, v35
	v_add_u32_e32 v171, 0x6c000, v170
	global_store_dwordx4 v171, v[44:47], s[16:17]
	global_store_dwordx4 v171, v[36:39], s[16:17] offset:256
	s_waitcnt lgkmcnt(1)
	v_mul_f32_e32 v28, v168, v28
	v_mul_f32_e32 v29, v168, v29
	v_mul_f32_e32 v30, v168, v30
	v_mul_f32_e32 v31, v168, v31
	v_mul_f32_e32 v24, v168, v24
	v_mul_f32_e32 v25, v168, v25
	v_mul_f32_e32 v26, v168, v26
	v_mul_f32_e32 v27, v168, v27
	v_mul_f32_e32 v20, v168, v20
	v_mul_f32_e32 v21, v168, v21
	v_mul_f32_e32 v22, v168, v22
	v_mul_f32_e32 v23, v168, v23
	v_mul_f32_e32 v16, v168, v16
	v_mul_f32_e32 v17, v168, v17
	v_mul_f32_e32 v18, v168, v18
	v_mul_f32_e32 v19, v168, v19
	v_cvt_pk_bf16_f32 v28, v28, v29
	v_cvt_pk_bf16_f32 v29, v30, v31
	v_cvt_pk_bf16_f32 v30, v24, v25
	v_cvt_pk_bf16_f32 v31, v26, v27
	v_cvt_pk_bf16_f32 v20, v20, v21
	v_cvt_pk_bf16_f32 v21, v22, v23
	v_cvt_pk_bf16_f32 v22, v16, v17
	v_cvt_pk_bf16_f32 v23, v18, v19
	v_add_u32_e32 v171, 0x78000, v170
	global_store_dwordx4 v171, v[28:31], s[16:17]
	global_store_dwordx4 v171, v[20:23], s[16:17] offset:256
	s_waitcnt lgkmcnt(0)
	v_mul_f32_e32 v12, v169, v12
	v_mul_f32_e32 v13, v169, v13
	v_mul_f32_e32 v14, v169, v14
	v_mul_f32_e32 v15, v169, v15
	v_mul_f32_e32 v8, v169, v8
	v_mul_f32_e32 v9, v169, v9
	v_mul_f32_e32 v10, v169, v10
	v_mul_f32_e32 v11, v169, v11
	v_mul_f32_e32 v4, v169, v4
	v_mul_f32_e32 v5, v169, v5
	v_mul_f32_e32 v6, v169, v6
	v_mul_f32_e32 v7, v169, v7
	v_mul_f32_e32 v0, v169, v0
	v_mul_f32_e32 v1, v169, v1
	v_mul_f32_e32 v2, v169, v2
	v_mul_f32_e32 v3, v169, v3
	v_cvt_pk_bf16_f32 v12, v12, v13
	v_cvt_pk_bf16_f32 v13, v14, v15
	v_cvt_pk_bf16_f32 v14, v8, v9
	v_cvt_pk_bf16_f32 v15, v10, v11
	v_cvt_pk_bf16_f32 v4, v4, v5
	v_cvt_pk_bf16_f32 v5, v6, v7
	v_cvt_pk_bf16_f32 v6, v0, v1
	v_cvt_pk_bf16_f32 v7, v2, v3
	v_add_u32_e32 v171, 0x84000, v170
	global_store_dwordx4 v171, v[12:15], s[16:17]
	global_store_dwordx4 v171, v[4:7], s[16:17] offset:256
	s_andn2_b64 vcc, exec, s[6:7]
	s_mov_b64 s[6:7], -1
	s_cbranch_vccnz .LBB0_1520
	s_andn2_b64 vcc, exec, s[14:15]
	s_cbranch_vccnz .LBB0_1519
	s_barrier
	s_branch .LBB0_1519

; __device__ __forceinline__ unsigned cvtpk(float lo, float hi) { f32x2_t v = {lo, hi}; bf16x2_t b = __builtin_convertvector(v, bf16x2_t); return __builtin_bit_cast(unsigned, b); }
;     __device__ __forceinline__ void operator()(const f32x4 (&acc)[2][2][4][2], const Unit& u, int wr, int wc, int fr, int fq) const {
;         const int row0 = u.pm * BM + wr * 64 + fr, col0 = u.pn * BM + wc * 32 + 8 * fq;
;         f32x4 cs[2][2];
; #pragma unroll
;         for (int bj = 0; bj < 2; ++bj)
; #pragma unroll
;             for (int n = 0; n < 2; ++n) {
; #pragma unroll
;                 for (int e = 0; e < 4; ++e) cs[bj][n][e] = 1.0f / sqrtf(ssq_sum(ssq_in + (size_t)(col0 + bj * HALF + 4 * n + e) * 16) * inv_dim + EPS); }
; #pragma unroll
;         for (int ai = 0; ai < 2; ++ai)
; #pragma unroll
;             for (int m = 0; m < 4; ++m) {
;                 const int row = row0 + ai * HALF + m * 16;
; #pragma unroll
;                 for (int bj = 0; bj < 2; ++bj) {
;                     const f32x4 v0 = acc[ai][bj][m][0] * cs[bj][0], v1 = acc[ai][bj][m][1] * cs[bj][1];
;                     u32x4 w; w.x = cvtpk(v0[0], v0[1]); w.y = cvtpk(v0[2], v0[3]); w.z = cvtpk(v1[0], v1[1]); w.w = cvtpk(v1[2], v1[3]);
;                     *(u32x4*)(O + (size_t)row * ldc + col0 + bj * HALF) = w;
;                 }
.LBB0_1573:
	v_readlane_b32 vcc_lo, v254, 7
	v_mbcnt_lo_u32_b32 v166, -1, 0
	v_mbcnt_hi_u32_b32 v166, -1, v166
	v_lshrrev_b32_e32 v167, 1, v166
	v_lshl_add_u32 v167, vcc_lo, 5, v167
	v_and_b32_e32 v168, 1, v166
	v_lshl_add_u32 v169, s2, 8, v167
	v_lshlrev_b32_e32 v169, 6, v169
	v_lshl_add_u32 v169, v168, 5, v169
	global_load_dwordx4 v[170:173], v169, s[14:15]
	global_load_dwordx4 v[174:177], v169, s[14:15] offset:16
	v_lshl_or_b32 v178, s2, 8, v160
	v_lshl_add_u32 v179, s42, 8, v158
	v_lshlrev_b32_e32 v179, 16, v179
	v_lshl_add_u32 v179, v178, 1, v179
	v_lshlrev_b32_e32 v167, 2, v167
	v_add_u32_e32 v167, 0x20100, v167
	v_lshlrev_b32_e32 v168, 2, v160
	v_add_u32_e32 v168, 0x20100, v168
	s_waitcnt vmcnt(0)
	v_add_f32_e32 v170, v170, v172
	v_add_f32_e32 v171, v171, v173
	v_add_f32_e32 v174, v174, v176
	v_add_f32_e32 v175, v175, v177
	v_add_f32_e32 v170, v170, v174
	v_add_f32_e32 v171, v171, v175
	v_add_f32_e32 v170, v170, v171
	s_nop 1
	v_add_f32_dpp v170, v170, v170 quad_perm:[1,0,3,2] row_mask:0xf bank_mask:0xf
	v_fmamk_f32 v170, v170, 0x3b800000, v164
	v_rsq_f32_e32 v170, v170
	s_nop 0
	ds_write_b32 v167, v170
	s_waitcnt lgkmcnt(0)
	s_barrier
	ds_read_b128 v[142:145], v168
	ds_read_b128 v[146:149], v168 offset:16
	ds_read_b128 v[150:153], v168 offset:512
	ds_read_b128 v[154:157], v168 offset:528
	s_waitcnt lgkmcnt(0)
	v_mul_f32_e32 v124, v124, v142
	v_mul_f32_e32 v125, v125, v143
	v_mul_f32_e32 v126, v126, v144
	v_mul_f32_e32 v127, v127, v145
	v_mul_f32_e32 v120, v120, v146
	v_mul_f32_e32 v121, v121, v147
	v_mul_f32_e32 v122, v122, v148
	v_mul_f32_e32 v123, v123, v149
	v_mul_f32_e32 v116, v116, v150
	v_mul_f32_e32 v117, v117, v151
	v_mul_f32_e32 v118, v118, v152
	v_mul_f32_e32 v119, v119, v153
	v_mul_f32_e32 v104, v104, v154
	v_mul_f32_e32 v105, v105, v155
	v_mul_f32_e32 v106, v106, v156
	v_mul_f32_e32 v107, v107, v157
	v_cvt_pk_bf16_f32 v124, v124, v125
	v_cvt_pk_bf16_f32 v125, v126, v127
	v_cvt_pk_bf16_f32 v126, v120, v121
	v_cvt_pk_bf16_f32 v127, v122, v123
	v_cvt_pk_bf16_f32 v116, v116, v117
	v_cvt_pk_bf16_f32 v117, v118, v119
	v_cvt_pk_bf16_f32 v118, v104, v105
	v_cvt_pk_bf16_f32 v119, v106, v107
	global_store_dwordx4 v179, v[124:127], s[18:19]
	global_store_dwordx4 v179, v[116:119], s[18:19] offset:256
	v_mul_f32_e32 v112, v112, v142
	v_mul_f32_e32 v113, v113, v143
	v_mul_f32_e32 v114, v114, v144
	v_mul_f32_e32 v115, v115, v145
	v_mul_f32_e32 v108, v108, v146
	v_mul_f32_e32 v109, v109, v147
	v_mul_f32_e32 v110, v110, v148
	v_mul_f32_e32 v111, v111, v149
	v_mul_f32_e32 v96, v96, v150
	v_mul_f32_e32 v97, v97, v151
	v_mul_f32_e32 v98, v98, v152
	v_mul_f32_e32 v99, v99, v153
	v_mul_f32_e32 v88, v88, v154
	v_mul_f32_e32 v89, v89, v155
	v_mul_f32_e32 v90, v90, v156
	v_mul_f32_e32 v91, v91, v157
	v_cvt_pk_bf16_f32 v112, v112, v113
	v_cvt_pk_bf16_f32 v113, v114, v115
	v_cvt_pk_bf16_f32 v114, v108, v109
	v_cvt_pk_bf16_f32 v115, v110, v111
	v_cvt_pk_bf16_f32 v96, v96, v97
	v_cvt_pk_bf16_f32 v97, v98, v99
	v_cvt_pk_bf16_f32 v98, v88, v89
	v_cvt_pk_bf16_f32 v99, v90, v91
	v_add_u32_e32 v180, 0x100000, v179
	global_store_dwordx4 v180, v[112:115], s[18:19]
	global_store_dwordx4 v180, v[96:99], s[18:19] offset:256
	v_mul_f32_e32 v100, v100, v142
	v_mul_f32_e32 v101, v101, v143
	v_mul_f32_e32 v102, v102, v144
	v_mul_f32_e32 v103, v103, v145
	v_mul_f32_e32 v92, v92, v146
	v_mul_f32_e32 v93, v93, v147
	v_mul_f32_e32 v94, v94, v148
	v_mul_f32_e32 v95, v95, v149
	v_mul_f32_e32 v80, v80, v150
	v_mul_f32_e32 v81, v81, v151
	v_mul_f32_e32 v82, v82, v152
	v_mul_f32_e32 v83, v83, v153
	v_mul_f32_e32 v72, v72, v154
	v_mul_f32_e32 v73, v73, v155
	v_mul_f32_e32 v74, v74, v156
	v_mul_f32_e32 v75, v75, v157
	v_cvt_pk_bf16_f32 v100, v100, v101
	v_cvt_pk_bf16_f32 v101, v102, v103
	v_cvt_pk_bf16_f32 v102, v92, v93
	v_cvt_pk_bf16_f32 v103, v94, v95
	v_cvt_pk_bf16_f32 v80, v80, v81
	v_cvt_pk_bf16_f32 v81, v82, v83
	v_cvt_pk_bf16_f32 v82, v72, v73
	v_cvt_pk_bf16_f32 v83, v74, v75
	v_add_u32_e32 v180, 0x200000, v179
	global_store_dwordx4 v180, v[100:103], s[18:19]
	global_store_dwordx4 v180, v[80:83], s[18:19] offset:256
	v_mul_f32_e32 v84, v84, v142
	v_mul_f32_e32 v85, v85, v143
	v_mul_f32_e32 v86, v86, v144
	v_mul_f32_e32 v87, v87, v145
	v_mul_f32_e32 v76, v76, v146
	v_mul_f32_e32 v77, v77, v147
	v_mul_f32_e32 v78, v78, v148
	v_mul_f32_e32 v79, v79, v149
; __device__ __forceinline__ unsigned cvtpk(float lo, float hi) { f32x2_t v = {lo, hi}; bf16x2_t b = __builtin_convertvector(v, bf16x2_t); return __builtin_bit_cast(unsigned, b); }
;     __device__ __forceinline__ void operator()(const f32x4 (&acc)[2][2][4][2], const Unit& u, int wr, int wc, int fr, int fq) const {
;     ...
;         for (int ai = 0; ai < 2; ++ai)
; #pragma unroll
;             for (int m = 0; m < 4; ++m) {
;                 const int row = row0 + ai * HALF + m * 16;
; #pragma unroll
;                 for (int bj = 0; bj < 2; ++bj) {
;                     const f32x4 v0 = acc[ai][bj][m][0] * cs[bj][0], v1 = acc[ai][bj][m][1] * cs[bj][1];
;                     u32x4 w; w.x = cvtpk(v0[0], v0[1]); w.y = cvtpk(v0[2], v0[3]); w.z = cvtpk(v1[0], v1[1]); w.w = cvtpk(v1[2], v1[3]);
;                     *(u32x4*)(O + (size_t)row * ldc + col0 + bj * HALF) = w;
;                 }
	v_mul_f32_e32 v68, v68, v150
	v_mul_f32_e32 v69, v69, v151
	v_mul_f32_e32 v70, v70, v152
	v_mul_f32_e32 v71, v71, v153
	v_mul_f32_e32 v64, v64, v154
	v_mul_f32_e32 v65, v65, v155
	v_mul_f32_e32 v66, v66, v156
	v_mul_f32_e32 v67, v67, v157
	v_cvt_pk_bf16_f32 v84, v84, v85
	v_cvt_pk_bf16_f32 v85, v86, v87
	v_cvt_pk_bf16_f32 v86, v76, v77
	v_cvt_pk_bf16_f32 v87, v78, v79
	v_cvt_pk_bf16_f32 v68, v68, v69
	v_cvt_pk_bf16_f32 v69, v70, v71
	v_cvt_pk_bf16_f32 v70, v64, v65
	v_cvt_pk_bf16_f32 v71, v66, v67
	v_add_u32_e32 v180, 0x300000, v179
	global_store_dwordx4 v180, v[84:87], s[18:19]
	global_store_dwordx4 v180, v[68:71], s[18:19] offset:256
	v_mul_f32_e32 v60, v60, v142
	v_mul_f32_e32 v61, v61, v143
	v_mul_f32_e32 v62, v62, v144
	v_mul_f32_e32 v63, v63, v145
	v_mul_f32_e32 v56, v56, v146
	v_mul_f32_e32 v57, v57, v147
	v_mul_f32_e32 v58, v58, v148
	v_mul_f32_e32 v59, v59, v149
	v_mul_f32_e32 v48, v48, v150
	v_mul_f32_e32 v49, v49, v151
	v_mul_f32_e32 v50, v50, v152
	v_mul_f32_e32 v51, v51, v153
	v_mul_f32_e32 v40, v40, v154
	v_mul_f32_e32 v41, v41, v155
	v_mul_f32_e32 v42, v42, v156
	v_mul_f32_e32 v43, v43, v157
	v_cvt_pk_bf16_f32 v60, v60, v61
	v_cvt_pk_bf16_f32 v61, v62, v63
	v_cvt_pk_bf16_f32 v62, v56, v57
	v_cvt_pk_bf16_f32 v63, v58, v59
	v_cvt_pk_bf16_f32 v48, v48, v49
	v_cvt_pk_bf16_f32 v49, v50, v51
	v_cvt_pk_bf16_f32 v50, v40, v41
	v_cvt_pk_bf16_f32 v51, v42, v43
	v_add_u32_e32 v180, 0x800000, v179
	global_store_dwordx4 v180, v[60:63], s[18:19]
	global_store_dwordx4 v180, v[48:51], s[18:19] offset:256
	v_mul_f32_e32 v52, v52, v142
	v_mul_f32_e32 v53, v53, v143
	v_mul_f32_e32 v54, v54, v144
	v_mul_f32_e32 v55, v55, v145
	v_mul_f32_e32 v44, v44, v146
	v_mul_f32_e32 v45, v45, v147
	v_mul_f32_e32 v46, v46, v148
	v_mul_f32_e32 v47, v47, v149
	v_mul_f32_e32 v32, v32, v150
	v_mul_f32_e32 v33, v33, v151
	v_mul_f32_e32 v34, v34, v152
	v_mul_f32_e32 v35, v35, v153
	v_mul_f32_e32 v24, v24, v154
	v_mul_f32_e32 v25, v25, v155
	v_mul_f32_e32 v26, v26, v156
	v_mul_f32_e32 v27, v27, v157
	v_cvt_pk_bf16_f32 v52, v52, v53
	v_cvt_pk_bf16_f32 v53, v54, v55
	v_cvt_pk_bf16_f32 v54, v44, v45
	v_cvt_pk_bf16_f32 v55, v46, v47
	v_cvt_pk_bf16_f32 v32, v32, v33
	v_cvt_pk_bf16_f32 v33, v34, v35
	v_cvt_pk_bf16_f32 v34, v24, v25
	v_cvt_pk_bf16_f32 v35, v26, v27
	v_add_u32_e32 v180, 0x900000, v179
	global_store_dwordx4 v180, v[52:55], s[18:19]
	global_store_dwordx4 v180, v[32:35], s[18:19] offset:256
	v_mul_f32_e32 v36, v36, v142
	v_mul_f32_e32 v37, v37, v143
	v_mul_f32_e32 v38, v38, v144
	v_mul_f32_e32 v39, v39, v145
	v_mul_f32_e32 v28, v28, v146
	v_mul_f32_e32 v29, v29, v147
	v_mul_f32_e32 v30, v30, v148
	v_mul_f32_e32 v31, v31, v149
	v_mul_f32_e32 v16, v16, v150
	v_mul_f32_e32 v17, v17, v151
	v_mul_f32_e32 v18, v18, v152
	v_mul_f32_e32 v19, v19, v153
	v_mul_f32_e32 v8, v8, v154
	v_mul_f32_e32 v9, v9, v155
	v_mul_f32_e32 v10, v10, v156
	v_mul_f32_e32 v11, v11, v157
	v_cvt_pk_bf16_f32 v36, v36, v37
	v_cvt_pk_bf16_f32 v37, v38, v39
	v_cvt_pk_bf16_f32 v38, v28, v29
	v_cvt_pk_bf16_f32 v39, v30, v31
	v_cvt_pk_bf16_f32 v16, v16, v17
	v_cvt_pk_bf16_f32 v17, v18, v19
	v_cvt_pk_bf16_f32 v18, v8, v9
	v_cvt_pk_bf16_f32 v19, v10, v11
	v_add_u32_e32 v180, 0xa00000, v179
	global_store_dwordx4 v180, v[36:39], s[18:19]
	global_store_dwordx4 v180, v[16:19], s[18:19] offset:256
	v_mul_f32_e32 v20, v20, v142
	v_mul_f32_e32 v21, v21, v143
	v_mul_f32_e32 v22, v22, v144
	v_mul_f32_e32 v23, v23, v145
	v_mul_f32_e32 v12, v12, v146
	v_mul_f32_e32 v13, v13, v147
	v_mul_f32_e32 v14, v14, v148
	v_mul_f32_e32 v15, v15, v149
	v_mul_f32_e32 v4, v4, v150
	v_mul_f32_e32 v5, v5, v151
	v_mul_f32_e32 v6, v6, v152
	v_mul_f32_e32 v7, v7, v153
	v_mul_f32_e32 v0, v0, v154
	v_mul_f32_e32 v1, v1, v155
	v_mul_f32_e32 v2, v2, v156
	v_mul_f32_e32 v3, v3, v157
	v_cvt_pk_bf16_f32 v20, v20, v21
	v_cvt_pk_bf16_f32 v21, v22, v23
	v_cvt_pk_bf16_f32 v22, v12, v13
	v_cvt_pk_bf16_f32 v23, v14, v15
	v_cvt_pk_bf16_f32 v4, v4, v5
	v_cvt_pk_bf16_f32 v5, v6, v7
	v_cvt_pk_bf16_f32 v6, v0, v1
	v_cvt_pk_bf16_f32 v7, v2, v3
	v_add_u32_e32 v180, 0xb00000, v179
	global_store_dwordx4 v180, v[20:23], s[18:19]
	global_store_dwordx4 v180, v[4:7], s[18:19] offset:256
	s_andn2_b64 vcc, exec, s[6:7]
	s_mov_b64 s[6:7], -1
	s_cbranch_vccnz .LBB0_1562
	s_andn2_b64 vcc, exec, s[16:17]
	s_cbranch_vccnz .LBB0_1561
	s_barrier
	s_branch .LBB0_1561
